# main loops: ALU instructions between a cluster's last MFMA and the rendezvous barrier moved behind the barrier
# speedup vs baseline: 1.0112x; 1.0112x over previous
.LBB0_403:
	s_add_u32 s14, s4, 0x100
	s_addc_u32 s15, s5, 0
	s_add_i32 s38, 0, 0x10000
	v_add_u32_e32 v12, s38, v193
	ds_read_b128 v[0:3], v12
	ds_read_b128 v[8:11], v12 offset:2048
	ds_read_b128 v[4:7], v12 offset:1024
	ds_read_b128 v[12:15], v12 offset:3072
	s_cmp_eq_u32 s37, 12
	s_cselect_b32 s19, s9, s15
	s_cselect_b32 s18, s8, s14
	s_cselect_b32 s17, s11, s36
	s_cselect_b32 s16, s10, s7
	v_lshl_add_u64 v[190:191], s[4:5], 0, v[186:187]
	s_add_i32 m0, s23, 0xc000
	ds_read_b128 v[16:19], v206
	ds_read_b128 v[24:27], v206 offset:2048
	ds_read_b128 v[162:165], v206 offset:4096
	ds_read_b128 v[170:173], v206 offset:6144
	ds_read_b128 v[20:23], v206 offset:1024
	ds_read_b128 v[28:31], v206 offset:3072
	ds_read_b128 v[166:169], v206 offset:5120
	ds_read_b128 v[174:177], v206 offset:7168
	global_load_lds_dwordx4 v[190:191], off
	v_lshl_add_u64 v[190:191], s[4:5], 0, v[188:189]
	s_add_i32 m0, s23, 0xe000
	s_nop 0
	global_load_lds_dwordx4 v[190:191], off
	s_waitcnt lgkmcnt(8)
	s_barrier
	s_waitcnt lgkmcnt(7)
	s_setprio 1
	v_mfma_f32_16x16x32_f16 v[158:161], v[0:3], v[16:19], v[158:161]
	v_mfma_f32_16x16x32_f16 v[142:145], v[8:11], v[16:19], v[142:145]
	s_waitcnt lgkmcnt(6)
	v_mfma_f32_16x16x32_f16 v[150:153], v[0:3], v[24:27], v[150:153]
	v_mfma_f32_16x16x32_f16 v[134:137], v[8:11], v[24:27], v[134:137]
	s_waitcnt lgkmcnt(5)
	v_mfma_f32_16x16x32_f16 v[154:157], v[0:3], v[162:165], v[154:157]
	v_mfma_f32_16x16x32_f16 v[138:141], v[8:11], v[162:165], v[138:141]
	s_waitcnt lgkmcnt(4)
	v_mfma_f32_16x16x32_f16 v[146:149], v[0:3], v[170:173], v[146:149]
	v_mfma_f32_16x16x32_f16 v[130:133], v[8:11], v[170:173], v[130:133]
	s_waitcnt lgkmcnt(3)
	v_mfma_f32_16x16x32_f16 v[158:161], v[4:7], v[20:23], v[158:161]
	v_mfma_f32_16x16x32_f16 v[142:145], v[12:15], v[20:23], v[142:145]
	s_waitcnt lgkmcnt(2)
	v_mfma_f32_16x16x32_f16 v[150:153], v[4:7], v[28:31], v[150:153]
	v_mfma_f32_16x16x32_f16 v[134:137], v[12:15], v[28:31], v[134:137]
	s_waitcnt lgkmcnt(1)
	v_mfma_f32_16x16x32_f16 v[154:157], v[4:7], v[166:169], v[154:157]
	v_mfma_f32_16x16x32_f16 v[138:141], v[12:15], v[166:169], v[138:141]
	s_waitcnt lgkmcnt(0)
	v_mfma_f32_16x16x32_f16 v[146:149], v[4:7], v[174:177], v[146:149]
	v_mfma_f32_16x16x32_f16 v[130:133], v[12:15], v[174:177], v[130:133]
	s_setprio 0
	s_barrier
	s_add_i32 s39, 0, 0x14000
	s_add_i32 s4, s38, s22
	v_add_u32_e32 v32, s39, v193
	v_lshl_add_u64 v[190:191], s[16:17], 0, v[178:179]
	s_mov_b32 m0, s4
	ds_read_b128 v[208:211], v32
	ds_read_b128 v[216:219], v32 offset:2048
	ds_read_b128 v[212:215], v32 offset:1024
	ds_read_b128 v[230:233], v32 offset:3072
	global_load_lds_dwordx4 v[190:191], off
	v_lshl_add_u64 v[238:239], s[16:17], 0, v[180:181]
	s_add_i32 m0, s4, 0x2000
	s_nop 0
	global_load_lds_dwordx4 v[238:239], off
	s_barrier
	s_waitcnt lgkmcnt(2)
	s_setprio 1
	v_mfma_f32_16x16x32_f16 v[94:97], v[208:211], v[16:19], v[94:97]
	v_mfma_f32_16x16x32_f16 v[16:19], v[216:219], v[16:19], v[78:81]
	s_waitcnt lgkmcnt(0)
	v_mfma_f32_16x16x32_f16 v[94:97], v[212:215], v[20:23], v[94:97]
	v_mfma_f32_16x16x32_f16 v[16:19], v[230:233], v[20:23], v[16:19]
	v_mfma_f32_16x16x32_f16 v[20:23], v[208:211], v[24:27], v[86:89]
	v_mfma_f32_16x16x32_f16 v[24:27], v[216:219], v[24:27], v[70:73]
	v_mfma_f32_16x16x32_f16 v[70:73], v[216:219], v[162:165], v[74:77]
	v_mfma_f32_16x16x32_f16 v[74:77], v[230:233], v[166:169], v[70:73]
	v_mfma_f32_16x16x32_f16 v[70:73], v[208:211], v[170:173], v[82:85]
	v_mfma_f32_16x16x32_f16 v[66:69], v[216:219], v[170:173], v[66:69]
	v_mfma_f32_16x16x32_f16 v[20:23], v[212:215], v[28:31], v[20:23]
	v_mfma_f32_16x16x32_f16 v[24:27], v[230:233], v[28:31], v[24:27]
	v_mfma_f32_16x16x32_f16 v[28:31], v[208:211], v[162:165], v[90:93]
	v_mfma_f32_16x16x32_f16 v[82:85], v[212:215], v[174:177], v[70:73]
	v_mfma_f32_16x16x32_f16 v[66:69], v[230:233], v[174:177], v[66:69]
	v_mfma_f32_16x16x32_f16 v[28:31], v[212:215], v[166:169], v[28:31]
	s_setprio 0
	s_barrier
	s_mov_b32 m0, s23
	v_lshl_add_u64 v[240:241], s[18:19], 0, v[178:179]
	ds_read_b128 v[70:73], v206 offset:16384
	ds_read_b128 v[86:89], v206 offset:18432
	ds_read_b128 v[162:165], v206 offset:20480
	ds_read_b128 v[170:173], v206 offset:22528
	ds_read_b128 v[78:81], v206 offset:17408
	ds_read_b128 v[90:93], v206 offset:19456
	ds_read_b128 v[166:169], v206 offset:21504
	ds_read_b128 v[174:177], v206 offset:23552
	global_load_lds_dwordx4 v[240:241], off
	v_lshl_add_u64 v[242:243], s[18:19], 0, v[180:181]
	s_mov_b32 m0, s24
	s_nop 0
	global_load_lds_dwordx4 v[242:243], off
	s_barrier
	s_waitcnt lgkmcnt(7)
	s_setprio 1
	v_mfma_f32_16x16x32_f16 v[126:129], v[0:3], v[70:73], v[126:129]
	v_mfma_f32_16x16x32_f16 v[110:113], v[8:11], v[70:73], v[110:113]
	s_waitcnt lgkmcnt(6)
	v_mfma_f32_16x16x32_f16 v[118:121], v[0:3], v[86:89], v[118:121]
	v_mfma_f32_16x16x32_f16 v[102:105], v[8:11], v[86:89], v[102:105]
	s_waitcnt lgkmcnt(5)
	v_mfma_f32_16x16x32_f16 v[122:125], v[0:3], v[162:165], v[122:125]
	v_mfma_f32_16x16x32_f16 v[106:109], v[8:11], v[162:165], v[106:109]
	s_waitcnt lgkmcnt(3)
	v_mfma_f32_16x16x32_f16 v[0:3], v[0:3], v[170:173], v[114:117]
	v_mfma_f32_16x16x32_f16 v[126:129], v[4:7], v[78:81], v[126:129]
	s_waitcnt lgkmcnt(2)
	v_mfma_f32_16x16x32_f16 v[110:113], v[12:15], v[78:81], v[110:113]
	v_mfma_f32_16x16x32_f16 v[118:121], v[4:7], v[90:93], v[118:121]
	s_waitcnt lgkmcnt(1)
	v_mfma_f32_16x16x32_f16 v[102:105], v[12:15], v[90:93], v[102:105]
	v_mfma_f32_16x16x32_f16 v[122:125], v[4:7], v[166:169], v[122:125]
	s_waitcnt lgkmcnt(0)
	v_mfma_f32_16x16x32_f16 v[106:109], v[12:15], v[166:169], v[106:109]
	v_mfma_f32_16x16x32_f16 v[0:3], v[4:7], v[174:177], v[0:3]
	v_mfma_f32_16x16x32_f16 v[4:7], v[8:11], v[170:173], v[98:101]
	v_mfma_f32_16x16x32_f16 v[4:7], v[12:15], v[174:177], v[4:7]
	s_setprio 0
	s_barrier
	s_add_u32 s4, s16, 0x40000
	s_addc_u32 s5, s17, 0
	s_add_i32 s38, s39, s22
	v_lshl_add_u64 v[8:9], s[4:5], 0, v[178:179]
	s_mov_b32 m0, s38
	s_nop 0
	global_load_lds_dwordx4 v[8:9], off
	v_lshl_add_u64 v[8:9], s[4:5], 0, v[180:181]
	s_add_i32 m0, s38, 0x2000
	s_nop 0
	global_load_lds_dwordx4 v[8:9], off
	s_waitcnt vmcnt(6)
	s_barrier
	s_setprio 1
	v_mfma_f32_16x16x32_f16 v[12:15], v[216:219], v[70:73], v[46:49]
	v_mfma_f32_16x16x32_f16 v[46:49], v[208:211], v[86:89], v[54:57]
	v_mfma_f32_16x16x32_f16 v[54:57], v[212:215], v[90:93], v[46:49]
	v_mfma_f32_16x16x32_f16 v[46:49], v[208:211], v[162:165], v[58:61]
	v_mfma_f32_16x16x32_f16 v[38:41], v[216:219], v[86:89], v[38:41]
	v_mfma_f32_16x16x32_f16 v[58:61], v[212:215], v[166:169], v[46:49]
	v_mfma_f32_16x16x32_f16 v[42:45], v[216:219], v[162:165], v[42:45]
	v_mfma_f32_16x16x32_f16 v[46:49], v[208:211], v[170:173], v[50:53]
	v_mfma_f32_16x16x32_f16 v[34:37], v[216:219], v[170:173], v[34:37]
	v_mfma_f32_16x16x32_f16 v[8:11], v[208:211], v[70:73], v[62:65]
	v_mfma_f32_16x16x32_f16 v[38:41], v[230:233], v[90:93], v[38:41]
	v_mfma_f32_16x16x32_f16 v[42:45], v[230:233], v[166:169], v[42:45]
	v_mfma_f32_16x16x32_f16 v[50:53], v[212:215], v[174:177], v[46:49]
	v_mfma_f32_16x16x32_f16 v[34:37], v[230:233], v[174:177], v[34:37]
	v_mfma_f32_16x16x32_f16 v[8:11], v[212:215], v[78:81], v[8:11]
	v_mfma_f32_16x16x32_f16 v[12:15], v[230:233], v[78:81], v[12:15]
	s_setprio 0
	s_barrier
	s_add_i32 s38, 0, 0x18000
	v_add_u32_e32 v32, s38, v193
	ds_read_b128 v[46:49], v32
	ds_read_b128 v[62:65], v32 offset:1024
	ds_read_b128 v[98:101], v32 offset:2048
	ds_read_b128 v[162:165], v32 offset:3072
	s_add_u32 s4, s18, 0x40000
	s_addc_u32 s5, s19, 0
	s_mov_b32 m0, s25
	v_lshl_add_u64 v[86:87], s[4:5], 0, v[178:179]
	ds_read_b128 v[70:73], v206 offset:32768
	ds_read_b128 v[78:81], v206 offset:33792
	ds_read_b128 v[90:93], v206 offset:34816
	ds_read_b128 v[114:117], v206 offset:35840
	ds_read_b128 v[166:169], v206 offset:36864
	ds_read_b128 v[170:173], v206 offset:37888
	ds_read_b128 v[174:177], v206 offset:38912
	ds_read_b128 v[208:211], v206 offset:39936
	global_load_lds_dwordx4 v[86:87], off
	v_lshl_add_u64 v[86:87], s[4:5], 0, v[180:181]
	s_mov_b32 m0, s26
	s_nop 0
	global_load_lds_dwordx4 v[86:87], off
	s_waitcnt lgkmcnt(8)
	s_barrier
	s_waitcnt lgkmcnt(6)
	s_setprio 1
	v_mfma_f32_16x16x32_f16 v[86:89], v[46:49], v[70:73], v[158:161]
	v_mfma_f32_16x16x32_f16 v[158:161], v[62:65], v[78:81], v[86:89]
	v_mfma_f32_16x16x32_f16 v[86:89], v[98:101], v[70:73], v[142:145]
	v_mfma_f32_16x16x32_f16 v[142:145], v[162:165], v[78:81], v[86:89]
	s_waitcnt lgkmcnt(4)
	v_mfma_f32_16x16x32_f16 v[86:89], v[46:49], v[90:93], v[150:153]
	v_mfma_f32_16x16x32_f16 v[150:153], v[62:65], v[114:117], v[86:89]
	v_mfma_f32_16x16x32_f16 v[86:89], v[98:101], v[90:93], v[134:137]
	v_mfma_f32_16x16x32_f16 v[134:137], v[162:165], v[114:117], v[86:89]
	s_waitcnt lgkmcnt(2)
	v_mfma_f32_16x16x32_f16 v[86:89], v[46:49], v[166:169], v[154:157]
	v_mfma_f32_16x16x32_f16 v[154:157], v[62:65], v[170:173], v[86:89]
	v_mfma_f32_16x16x32_f16 v[86:89], v[98:101], v[166:169], v[138:141]
	v_mfma_f32_16x16x32_f16 v[138:141], v[162:165], v[170:173], v[86:89]
	s_waitcnt lgkmcnt(0)
	v_mfma_f32_16x16x32_f16 v[86:89], v[46:49], v[174:177], v[146:149]
	v_mfma_f32_16x16x32_f16 v[146:149], v[62:65], v[208:211], v[86:89]
	v_mfma_f32_16x16x32_f16 v[86:89], v[98:101], v[174:177], v[130:133]
	v_mfma_f32_16x16x32_f16 v[130:133], v[162:165], v[208:211], v[86:89]
	s_setprio 0
	s_barrier
	s_add_i32 s18, 0, 0x1c000
	s_add_i32 s4, s38, s22
	v_add_u32_e32 v32, s18, v193
	s_nop 1
	v_lshl_add_u64 v[86:87], v[190:191], 0, s[84:85]
	s_mov_b32 m0, s4
	ds_read_b128 v[212:215], v32
	ds_read_b128 v[230:233], v32 offset:2048
	ds_read_b128 v[216:219], v32 offset:1024
	ds_read_b128 v[234:237], v32 offset:3072
	global_load_lds_dwordx4 v[86:87], off
	v_lshl_add_u64 v[86:87], v[238:239], 0, s[84:85]
	s_add_i32 m0, s4, 0x2000
	s_nop 0
	global_load_lds_dwordx4 v[86:87], off
	s_barrier
	s_waitcnt lgkmcnt(2)
	s_setprio 1
	v_mfma_f32_16x16x32_f16 v[86:89], v[212:215], v[70:73], v[94:97]
	v_mfma_f32_16x16x32_f16 v[16:19], v[230:233], v[70:73], v[16:19]
	s_waitcnt lgkmcnt(0)
	v_mfma_f32_16x16x32_f16 v[94:97], v[216:219], v[78:81], v[86:89]
	v_mfma_f32_16x16x32_f16 v[78:81], v[234:237], v[78:81], v[16:19]
	v_mfma_f32_16x16x32_f16 v[16:19], v[212:215], v[90:93], v[20:23]
	v_mfma_f32_16x16x32_f16 v[86:89], v[216:219], v[114:117], v[16:19]
	v_mfma_f32_16x16x32_f16 v[16:19], v[230:233], v[90:93], v[24:27]
	v_mfma_f32_16x16x32_f16 v[70:73], v[234:237], v[114:117], v[16:19]
	v_mfma_f32_16x16x32_f16 v[16:19], v[212:215], v[166:169], v[28:31]
	v_mfma_f32_16x16x32_f16 v[90:93], v[216:219], v[170:173], v[16:19]
	v_mfma_f32_16x16x32_f16 v[16:19], v[230:233], v[166:169], v[74:77]
	v_mfma_f32_16x16x32_f16 v[74:77], v[234:237], v[170:173], v[16:19]
	v_mfma_f32_16x16x32_f16 v[16:19], v[212:215], v[174:177], v[82:85]
	v_mfma_f32_16x16x32_f16 v[82:85], v[216:219], v[208:211], v[16:19]
	v_mfma_f32_16x16x32_f16 v[16:19], v[230:233], v[174:177], v[66:69]
	v_mfma_f32_16x16x32_f16 v[66:69], v[234:237], v[208:211], v[16:19]
	s_setprio 0
	s_barrier
	s_mov_b32 m0, s28
	v_lshl_add_u64 v[114:115], v[240:241], 0, s[84:85]
	s_nop 2
	ds_read_b128 v[16:19], v206 offset:49152
	ds_read_b128 v[20:23], v206 offset:50176
	ds_read_b128 v[24:27], v206 offset:51200
	ds_read_b128 v[28:31], v206 offset:52224
	ds_read_b128 v[166:169], v206 offset:53248
	ds_read_b128 v[174:177], v206 offset:55296
	ds_read_b128 v[170:173], v206 offset:54272
	ds_read_b128 v[208:211], v206 offset:56320
	global_load_lds_dwordx4 v[114:115], off
	v_lshl_add_u64 v[114:115], v[242:243], 0, s[84:85]
	s_mov_b32 m0, s29
	s_nop 0
	global_load_lds_dwordx4 v[114:115], off
	s_barrier
	s_waitcnt lgkmcnt(6)
	s_setprio 1
	v_mfma_f32_16x16x32_f16 v[114:117], v[46:49], v[16:19], v[126:129]
	v_mfma_f32_16x16x32_f16 v[126:129], v[62:65], v[20:23], v[114:117]
	s_waitcnt lgkmcnt(4)
	v_mfma_f32_16x16x32_f16 v[114:117], v[46:49], v[24:27], v[118:121]
	v_mfma_f32_16x16x32_f16 v[118:121], v[62:65], v[28:31], v[114:117]
	s_waitcnt lgkmcnt(2)
	v_mfma_f32_16x16x32_f16 v[114:117], v[46:49], v[166:169], v[122:125]
	v_mfma_f32_16x16x32_f16 v[0:3], v[46:49], v[174:177], v[0:3]
	v_mfma_f32_16x16x32_f16 v[110:113], v[98:101], v[16:19], v[110:113]
	v_mfma_f32_16x16x32_f16 v[102:105], v[98:101], v[24:27], v[102:105]
	s_waitcnt lgkmcnt(1)
	v_mfma_f32_16x16x32_f16 v[122:125], v[62:65], v[170:173], v[114:117]
	v_mfma_f32_16x16x32_f16 v[106:109], v[98:101], v[166:169], v[106:109]
	s_waitcnt lgkmcnt(0)
	v_mfma_f32_16x16x32_f16 v[114:117], v[62:65], v[208:211], v[0:3]
	v_mfma_f32_16x16x32_f16 v[0:3], v[98:101], v[174:177], v[4:7]
	v_mfma_f32_16x16x32_f16 v[110:113], v[162:165], v[20:23], v[110:113]
	v_mfma_f32_16x16x32_f16 v[102:105], v[162:165], v[28:31], v[102:105]
	v_mfma_f32_16x16x32_f16 v[106:109], v[162:165], v[170:173], v[106:109]
	v_mfma_f32_16x16x32_f16 v[98:101], v[162:165], v[208:211], v[0:3]
	s_setprio 0
	s_barrier
	s_add_u32 s4, s16, 0x40080
	s_addc_u32 s5, s17, 0
	s_add_i32 s16, s18, s22
	v_lshl_add_u64 v[0:1], s[4:5], 0, v[178:179]
	s_mov_b32 m0, s16
	s_nop 0
	global_load_lds_dwordx4 v[0:1], off
	v_lshl_add_u64 v[0:1], s[4:5], 0, v[180:181]
	s_add_i32 m0, s16, 0x2000
	s_nop 0
	global_load_lds_dwordx4 v[0:1], off
	s_waitcnt vmcnt(6)
	s_barrier
	s_setprio 1
	v_mfma_f32_16x16x32_f16 v[0:3], v[212:215], v[16:19], v[8:11]
	v_mfma_f32_16x16x32_f16 v[62:65], v[216:219], v[20:23], v[0:3]
	v_mfma_f32_16x16x32_f16 v[0:3], v[230:233], v[16:19], v[12:15]
	v_mfma_f32_16x16x32_f16 v[46:49], v[234:237], v[20:23], v[0:3]
	v_mfma_f32_16x16x32_f16 v[0:3], v[212:215], v[24:27], v[54:57]
	v_mfma_f32_16x16x32_f16 v[54:57], v[216:219], v[28:31], v[0:3]
	v_mfma_f32_16x16x32_f16 v[0:3], v[230:233], v[24:27], v[38:41]
	v_mfma_f32_16x16x32_f16 v[38:41], v[234:237], v[28:31], v[0:3]
	v_mfma_f32_16x16x32_f16 v[0:3], v[212:215], v[166:169], v[58:61]
	v_mfma_f32_16x16x32_f16 v[58:61], v[216:219], v[170:173], v[0:3]
	v_mfma_f32_16x16x32_f16 v[0:3], v[230:233], v[166:169], v[42:45]
	v_mfma_f32_16x16x32_f16 v[42:45], v[234:237], v[170:173], v[0:3]
	v_mfma_f32_16x16x32_f16 v[0:3], v[212:215], v[174:177], v[50:53]
	v_mfma_f32_16x16x32_f16 v[50:53], v[216:219], v[208:211], v[0:3]
	v_mfma_f32_16x16x32_f16 v[0:3], v[230:233], v[174:177], v[34:37]
	v_mfma_f32_16x16x32_f16 v[34:37], v[234:237], v[208:211], v[0:3]
	s_setprio 0
	s_barrier
	s_add_i32 s37, s37, 2
	s_add_u32 s7, s7, 0x100
	s_addc_u32 s36, s36, 0
	s_cmp_gt_u32 s37, 13
	s_mov_b64 s[4:5], s[14:15]
	s_cbranch_scc0 .LBB0_403
	s_lshl_b32 s7, s34, 8
	s_cmp_lt_i32 s35, 28
	s_mov_b64 s[4:5], -1
	s_cbranch_scc0 .LBB0_431
	s_add_i32 s16, s7, s27
	v_or_b32_e32 v207, s16, v192
	s_cmp_gt_i32 s35, 3
	s_cbranch_scc0 .LBB0_411
	s_add_i32 s4, s35, -12
	s_cmp_gt_u32 s4, 7
	s_mov_b64 s[4:5], -1
	s_cbranch_scc0 .LBB0_408
	s_lshl_b32 s4, s35, 8
	s_add_i32 s5, s4, 0xfffffc00
	s_cmp_lt_u32 s35, 12
	s_cselect_b32 s4, s4, s5
	v_and_b32_e32 v10, 7, v220
	v_and_b32_e32 v11, 8, v220
	v_cmp_ne_u32_e32 vcc, 0, v11
	v_and_b32_e32 v12, 0x60, v194
	v_lshlrev_b32_e32 v12, 1, v12
	v_lshl_or_b32 v12, v11, 2, v12
	v_and_b32_e32 v13, 0x18, v194
	v_or_b32_e32 v12, v12, v13
	v_or_b32_e32 v32, s4, v12
	v_or_b32_e32 v14, s16, v10
	v_mov_b64_e32 v[4:5], s[70:71]
	v_mad_i64_i32 v[0:1], s[4:5], v14, s33, v[4:5]
	v_lshlrev_b64 v[6:7], 1, v[32:33]
	v_lshl_add_u64 v[16:17], v[0:1], 0, v[6:7]
	v_mov_b32_e32 v32, 0x30000
	v_lshl_add_u64 v[18:19], v[16:17], 0, v[32:33]
	v_lshl_add_u64 v[20:21], v[18:19], 0, v[32:33]
	v_lshl_add_u64 v[22:23], v[20:21], 0, v[32:33]
	v_mov_b32_e32 v8, 0x180000
	v_mov_b32_e32 v9, 0
	v_lshl_add_u64 v[24:25], v[16:17], 0, v[8:9]
	v_lshl_add_u64 v[26:27], v[24:25], 0, v[32:33]
	v_lshl_add_u64 v[28:29], v[26:27], 0, v[32:33]
	v_lshl_add_u64 v[30:31], v[28:29], 0, v[32:33]
	v_mov_b32_e32 v8, 0x18000
	v_cvt_pk_f16_f32 v158, v158, v159
	v_cvt_pk_f16_f32 v159, v160, v161
	v_cvt_pk_f16_f32 v160, v142, v143
	v_cvt_pk_f16_f32 v161, v144, v145
	v_cvt_pk_f16_f32 v94, v94, v95
	v_cvt_pk_f16_f32 v95, v96, v97
	v_cvt_pk_f16_f32 v96, v78, v79
	v_cvt_pk_f16_f32 v97, v80, v81
	v_mov_b32_dpp v0, v158 row_ror:8 row_mask:0xf bank_mask:0xf
	v_mov_b32_dpp v1, v159 row_ror:8 row_mask:0xf bank_mask:0xf
	v_mov_b32_dpp v2, v160 row_ror:8 row_mask:0xf bank_mask:0xf
	v_mov_b32_dpp v3, v161 row_ror:8 row_mask:0xf bank_mask:0xf
	v_mov_b32_dpp v4, v94 row_ror:8 row_mask:0xf bank_mask:0xf
	v_mov_b32_dpp v5, v95 row_ror:8 row_mask:0xf bank_mask:0xf
	v_mov_b32_dpp v6, v96 row_ror:8 row_mask:0xf bank_mask:0xf
	v_mov_b32_dpp v7, v97 row_ror:8 row_mask:0xf bank_mask:0xf
	v_cndmask_b32_e32 v158, v158, v4, vcc
	v_cndmask_b32_e32 v159, v159, v5, vcc
	v_cndmask_b32_e32 v160, v160, v6, vcc
	v_cndmask_b32_e32 v161, v161, v7, vcc
	v_cndmask_b32_e32 v94, v0, v94, vcc
	v_cndmask_b32_e32 v95, v1, v95, vcc
	v_cndmask_b32_e32 v96, v2, v96, vcc
	v_cndmask_b32_e32 v97, v3, v97, vcc
	v_lshl_add_u64 v[10:11], v[16:17], 0, v[8:9]
	global_store_dwordx4 v[16:17], v[158:161], off
	global_store_dwordx4 v[10:11], v[94:97], off
	v_cvt_pk_f16_f32 v150, v150, v151
	v_cvt_pk_f16_f32 v151, v152, v153
	v_cvt_pk_f16_f32 v152, v134, v135
	v_cvt_pk_f16_f32 v153, v136, v137
	v_cvt_pk_f16_f32 v86, v86, v87
	v_cvt_pk_f16_f32 v87, v88, v89
	v_cvt_pk_f16_f32 v88, v70, v71
	v_cvt_pk_f16_f32 v89, v72, v73
	v_mov_b32_dpp v0, v150 row_ror:8 row_mask:0xf bank_mask:0xf
	v_mov_b32_dpp v1, v151 row_ror:8 row_mask:0xf bank_mask:0xf
	v_mov_b32_dpp v2, v152 row_ror:8 row_mask:0xf bank_mask:0xf
	v_mov_b32_dpp v3, v153 row_ror:8 row_mask:0xf bank_mask:0xf
	v_mov_b32_dpp v4, v86 row_ror:8 row_mask:0xf bank_mask:0xf
	v_mov_b32_dpp v5, v87 row_ror:8 row_mask:0xf bank_mask:0xf
	v_mov_b32_dpp v6, v88 row_ror:8 row_mask:0xf bank_mask:0xf
	v_mov_b32_dpp v7, v89 row_ror:8 row_mask:0xf bank_mask:0xf
	v_cndmask_b32_e32 v150, v150, v4, vcc
	v_cndmask_b32_e32 v151, v151, v5, vcc
	v_cndmask_b32_e32 v152, v152, v6, vcc
	v_cndmask_b32_e32 v153, v153, v7, vcc
	v_cndmask_b32_e32 v86, v0, v86, vcc
	v_cndmask_b32_e32 v87, v1, v87, vcc
	v_cndmask_b32_e32 v88, v2, v88, vcc
	v_cndmask_b32_e32 v89, v3, v89, vcc
	v_lshl_add_u64 v[10:11], v[18:19], 0, v[8:9]
	global_store_dwordx4 v[18:19], v[150:153], off
	global_store_dwordx4 v[10:11], v[86:89], off
	v_cvt_pk_f16_f32 v154, v154, v155
	v_cvt_pk_f16_f32 v155, v156, v157
	v_cvt_pk_f16_f32 v156, v138, v139
	v_cvt_pk_f16_f32 v157, v140, v141
	v_cvt_pk_f16_f32 v90, v90, v91
	v_cvt_pk_f16_f32 v91, v92, v93
	v_cvt_pk_f16_f32 v92, v74, v75
	v_cvt_pk_f16_f32 v93, v76, v77
	v_mov_b32_dpp v0, v154 row_ror:8 row_mask:0xf bank_mask:0xf
	v_mov_b32_dpp v1, v155 row_ror:8 row_mask:0xf bank_mask:0xf
	v_mov_b32_dpp v2, v156 row_ror:8 row_mask:0xf bank_mask:0xf
	v_mov_b32_dpp v3, v157 row_ror:8 row_mask:0xf bank_mask:0xf
	v_mov_b32_dpp v4, v90 row_ror:8 row_mask:0xf bank_mask:0xf
	v_mov_b32_dpp v5, v91 row_ror:8 row_mask:0xf bank_mask:0xf
	v_mov_b32_dpp v6, v92 row_ror:8 row_mask:0xf bank_mask:0xf
	v_mov_b32_dpp v7, v93 row_ror:8 row_mask:0xf bank_mask:0xf
	v_cndmask_b32_e32 v154, v154, v4, vcc
	v_cndmask_b32_e32 v155, v155, v5, vcc
	v_cndmask_b32_e32 v156, v156, v6, vcc
	v_cndmask_b32_e32 v157, v157, v7, vcc
	v_cndmask_b32_e32 v90, v0, v90, vcc
	v_cndmask_b32_e32 v91, v1, v91, vcc
	v_cndmask_b32_e32 v92, v2, v92, vcc
	v_cndmask_b32_e32 v93, v3, v93, vcc
	v_lshl_add_u64 v[10:11], v[20:21], 0, v[8:9]
	global_store_dwordx4 v[20:21], v[154:157], off
	global_store_dwordx4 v[10:11], v[90:93], off
	v_cvt_pk_f16_f32 v146, v146, v147
	v_cvt_pk_f16_f32 v147, v148, v149
	v_cvt_pk_f16_f32 v148, v130, v131
	v_cvt_pk_f16_f32 v149, v132, v133
	v_cvt_pk_f16_f32 v82, v82, v83
	v_cvt_pk_f16_f32 v83, v84, v85
	v_cvt_pk_f16_f32 v84, v66, v67
	v_cvt_pk_f16_f32 v85, v68, v69
	v_mov_b32_dpp v0, v146 row_ror:8 row_mask:0xf bank_mask:0xf
	v_mov_b32_dpp v1, v147 row_ror:8 row_mask:0xf bank_mask:0xf
	v_mov_b32_dpp v2, v148 row_ror:8 row_mask:0xf bank_mask:0xf
	v_mov_b32_dpp v3, v149 row_ror:8 row_mask:0xf bank_mask:0xf
	v_mov_b32_dpp v4, v82 row_ror:8 row_mask:0xf bank_mask:0xf
	v_mov_b32_dpp v5, v83 row_ror:8 row_mask:0xf bank_mask:0xf
	v_mov_b32_dpp v6, v84 row_ror:8 row_mask:0xf bank_mask:0xf
	v_mov_b32_dpp v7, v85 row_ror:8 row_mask:0xf bank_mask:0xf
	v_cndmask_b32_e32 v146, v146, v4, vcc
	v_cndmask_b32_e32 v147, v147, v5, vcc
	v_cndmask_b32_e32 v148, v148, v6, vcc
	v_cndmask_b32_e32 v149, v149, v7, vcc
	v_cndmask_b32_e32 v82, v0, v82, vcc
	v_cndmask_b32_e32 v83, v1, v83, vcc
	v_cndmask_b32_e32 v84, v2, v84, vcc
	v_cndmask_b32_e32 v85, v3, v85, vcc
	v_lshl_add_u64 v[10:11], v[22:23], 0, v[8:9]
	global_store_dwordx4 v[22:23], v[146:149], off
	global_store_dwordx4 v[10:11], v[82:85], off
	v_cvt_pk_f16_f32 v126, v126, v127
	v_cvt_pk_f16_f32 v127, v128, v129
	v_cvt_pk_f16_f32 v128, v110, v111
	v_cvt_pk_f16_f32 v129, v112, v113
	v_cvt_pk_f16_f32 v62, v62, v63
	v_cvt_pk_f16_f32 v63, v64, v65
	v_cvt_pk_f16_f32 v64, v46, v47
	v_cvt_pk_f16_f32 v65, v48, v49
	v_mov_b32_dpp v0, v126 row_ror:8 row_mask:0xf bank_mask:0xf
	v_mov_b32_dpp v1, v127 row_ror:8 row_mask:0xf bank_mask:0xf
	v_mov_b32_dpp v2, v128 row_ror:8 row_mask:0xf bank_mask:0xf
	v_mov_b32_dpp v3, v129 row_ror:8 row_mask:0xf bank_mask:0xf
	v_mov_b32_dpp v4, v62 row_ror:8 row_mask:0xf bank_mask:0xf
	v_mov_b32_dpp v5, v63 row_ror:8 row_mask:0xf bank_mask:0xf
	v_mov_b32_dpp v6, v64 row_ror:8 row_mask:0xf bank_mask:0xf
	v_mov_b32_dpp v7, v65 row_ror:8 row_mask:0xf bank_mask:0xf
	v_cndmask_b32_e32 v126, v126, v4, vcc
	v_cndmask_b32_e32 v127, v127, v5, vcc
	v_cndmask_b32_e32 v128, v128, v6, vcc
	v_cndmask_b32_e32 v129, v129, v7, vcc
	v_cndmask_b32_e32 v62, v0, v62, vcc
	v_cndmask_b32_e32 v63, v1, v63, vcc
	v_cndmask_b32_e32 v64, v2, v64, vcc
	v_cndmask_b32_e32 v65, v3, v65, vcc
	v_lshl_add_u64 v[10:11], v[24:25], 0, v[8:9]
	global_store_dwordx4 v[24:25], v[126:129], off
	global_store_dwordx4 v[10:11], v[62:65], off
	v_cvt_pk_f16_f32 v118, v118, v119
	v_cvt_pk_f16_f32 v119, v120, v121
	v_cvt_pk_f16_f32 v120, v102, v103
	v_cvt_pk_f16_f32 v121, v104, v105
	v_cvt_pk_f16_f32 v54, v54, v55
	v_cvt_pk_f16_f32 v55, v56, v57
	v_cvt_pk_f16_f32 v56, v38, v39
	v_cvt_pk_f16_f32 v57, v40, v41
	v_mov_b32_dpp v0, v118 row_ror:8 row_mask:0xf bank_mask:0xf
	v_mov_b32_dpp v1, v119 row_ror:8 row_mask:0xf bank_mask:0xf
	v_mov_b32_dpp v2, v120 row_ror:8 row_mask:0xf bank_mask:0xf
	v_mov_b32_dpp v3, v121 row_ror:8 row_mask:0xf bank_mask:0xf
	v_mov_b32_dpp v4, v54 row_ror:8 row_mask:0xf bank_mask:0xf
	v_mov_b32_dpp v5, v55 row_ror:8 row_mask:0xf bank_mask:0xf
	v_mov_b32_dpp v6, v56 row_ror:8 row_mask:0xf bank_mask:0xf
	v_mov_b32_dpp v7, v57 row_ror:8 row_mask:0xf bank_mask:0xf
	v_cndmask_b32_e32 v118, v118, v4, vcc
	v_cndmask_b32_e32 v119, v119, v5, vcc
	v_cndmask_b32_e32 v120, v120, v6, vcc
	v_cndmask_b32_e32 v121, v121, v7, vcc
	v_cndmask_b32_e32 v54, v0, v54, vcc
	v_cndmask_b32_e32 v55, v1, v55, vcc
	v_cndmask_b32_e32 v56, v2, v56, vcc
	v_cndmask_b32_e32 v57, v3, v57, vcc
	v_lshl_add_u64 v[10:11], v[26:27], 0, v[8:9]
	global_store_dwordx4 v[26:27], v[118:121], off
	global_store_dwordx4 v[10:11], v[54:57], off
	v_cvt_pk_f16_f32 v122, v122, v123
	v_cvt_pk_f16_f32 v123, v124, v125
	v_cvt_pk_f16_f32 v124, v106, v107
	v_cvt_pk_f16_f32 v125, v108, v109
	v_cvt_pk_f16_f32 v58, v58, v59
	v_cvt_pk_f16_f32 v59, v60, v61
	v_cvt_pk_f16_f32 v60, v42, v43
	v_cvt_pk_f16_f32 v61, v44, v45
	v_mov_b32_dpp v0, v122 row_ror:8 row_mask:0xf bank_mask:0xf
	v_mov_b32_dpp v1, v123 row_ror:8 row_mask:0xf bank_mask:0xf
	v_mov_b32_dpp v2, v124 row_ror:8 row_mask:0xf bank_mask:0xf
	v_mov_b32_dpp v3, v125 row_ror:8 row_mask:0xf bank_mask:0xf
	v_mov_b32_dpp v4, v58 row_ror:8 row_mask:0xf bank_mask:0xf
	v_mov_b32_dpp v5, v59 row_ror:8 row_mask:0xf bank_mask:0xf
	v_mov_b32_dpp v6, v60 row_ror:8 row_mask:0xf bank_mask:0xf
	v_mov_b32_dpp v7, v61 row_ror:8 row_mask:0xf bank_mask:0xf
	v_cndmask_b32_e32 v122, v122, v4, vcc
	v_cndmask_b32_e32 v123, v123, v5, vcc
	v_cndmask_b32_e32 v124, v124, v6, vcc
	v_cndmask_b32_e32 v125, v125, v7, vcc
	v_cndmask_b32_e32 v58, v0, v58, vcc
	v_cndmask_b32_e32 v59, v1, v59, vcc
	v_cndmask_b32_e32 v60, v2, v60, vcc
	v_cndmask_b32_e32 v61, v3, v61, vcc
	v_lshl_add_u64 v[10:11], v[28:29], 0, v[8:9]
	global_store_dwordx4 v[28:29], v[122:125], off
	global_store_dwordx4 v[10:11], v[58:61], off
	v_cvt_pk_f16_f32 v114, v114, v115
	v_cvt_pk_f16_f32 v115, v116, v117
	v_cvt_pk_f16_f32 v116, v98, v99
	v_cvt_pk_f16_f32 v117, v100, v101
	v_cvt_pk_f16_f32 v50, v50, v51
	v_cvt_pk_f16_f32 v51, v52, v53
	v_cvt_pk_f16_f32 v52, v34, v35
	v_cvt_pk_f16_f32 v53, v36, v37
	v_mov_b32_dpp v0, v114 row_ror:8 row_mask:0xf bank_mask:0xf
	v_mov_b32_dpp v1, v115 row_ror:8 row_mask:0xf bank_mask:0xf
	v_mov_b32_dpp v2, v116 row_ror:8 row_mask:0xf bank_mask:0xf
	v_mov_b32_dpp v3, v117 row_ror:8 row_mask:0xf bank_mask:0xf
	v_mov_b32_dpp v4, v50 row_ror:8 row_mask:0xf bank_mask:0xf
	v_mov_b32_dpp v5, v51 row_ror:8 row_mask:0xf bank_mask:0xf
	v_mov_b32_dpp v6, v52 row_ror:8 row_mask:0xf bank_mask:0xf
	v_mov_b32_dpp v7, v53 row_ror:8 row_mask:0xf bank_mask:0xf
	v_cndmask_b32_e32 v114, v114, v4, vcc
	v_cndmask_b32_e32 v115, v115, v5, vcc
	v_cndmask_b32_e32 v116, v116, v6, vcc
	v_cndmask_b32_e32 v117, v117, v7, vcc
	v_cndmask_b32_e32 v50, v0, v50, vcc
	v_cndmask_b32_e32 v51, v1, v51, vcc
	v_cndmask_b32_e32 v52, v2, v52, vcc
	v_cndmask_b32_e32 v53, v3, v53, vcc
	v_lshl_add_u64 v[10:11], v[30:31], 0, v[8:9]
	global_store_dwordx4 v[30:31], v[114:117], off
	global_store_dwordx4 v[10:11], v[50:53], off
	s_mov_b64 s[4:5], 0

.LBB0_940:
	s_add_u32 s20, s14, 0x100
	s_addc_u32 s21, s15, 0
	s_add_i32 s40, 0, 0x10000
	v_add_u32_e32 v32, s40, v209
	ds_read_b128 v[132:135], v32
	ds_read_b128 v[140:143], v32 offset:2048
	ds_read_b128 v[136:139], v32 offset:1024
	ds_read_b128 v[144:147], v32 offset:3072
	s_cmp_eq_u32 s11, 12
	s_cselect_b32 s25, s17, s21
	s_cselect_b32 s24, s16, s20
	s_cselect_b32 s23, s19, s3
	s_cselect_b32 s22, s18, s1
	v_lshl_add_u64 v[34:35], s[14:15], 0, v[200:201]
	s_add_i32 m0, s30, 0xc000
	ds_read_b128 v[148:151], v211
	ds_read_b128 v[156:159], v211 offset:2048
	ds_read_b128 v[164:167], v211 offset:4096
	ds_read_b128 v[172:175], v211 offset:6144
	ds_read_b128 v[152:155], v211 offset:1024
	ds_read_b128 v[160:163], v211 offset:3072
	ds_read_b128 v[168:171], v211 offset:5120
	ds_read_b128 v[176:179], v211 offset:7168
	global_load_lds_dwordx4 v[34:35], off
	v_lshl_add_u64 v[34:35], s[14:15], 0, v[202:203]
	s_add_i32 m0, s30, 0xe000
	s_nop 0
	global_load_lds_dwordx4 v[34:35], off
	s_waitcnt lgkmcnt(8)
	s_barrier
	s_waitcnt lgkmcnt(7)
	s_setprio 1
	v_mfma_f32_16x16x32_f16 v[128:131], v[132:135], v[148:151], v[128:131]
	v_mfma_f32_16x16x32_f16 v[124:127], v[140:143], v[148:151], v[124:127]
	s_waitcnt lgkmcnt(6)
	v_mfma_f32_16x16x32_f16 v[120:123], v[132:135], v[156:159], v[120:123]
	v_mfma_f32_16x16x32_f16 v[116:119], v[140:143], v[156:159], v[116:119]
	s_waitcnt lgkmcnt(5)
	v_mfma_f32_16x16x32_f16 v[112:115], v[132:135], v[164:167], v[112:115]
	v_mfma_f32_16x16x32_f16 v[108:111], v[140:143], v[164:167], v[108:111]
	s_waitcnt lgkmcnt(4)
	v_mfma_f32_16x16x32_f16 v[104:107], v[132:135], v[172:175], v[104:107]
	v_mfma_f32_16x16x32_f16 v[100:103], v[140:143], v[172:175], v[100:103]
	s_waitcnt lgkmcnt(3)
	v_mfma_f32_16x16x32_f16 v[128:131], v[136:139], v[152:155], v[128:131]
	v_mfma_f32_16x16x32_f16 v[124:127], v[144:147], v[152:155], v[124:127]
	s_waitcnt lgkmcnt(2)
	v_mfma_f32_16x16x32_f16 v[120:123], v[136:139], v[160:163], v[120:123]
	v_mfma_f32_16x16x32_f16 v[116:119], v[144:147], v[160:163], v[116:119]
	s_waitcnt lgkmcnt(1)
	v_mfma_f32_16x16x32_f16 v[112:115], v[136:139], v[168:171], v[112:115]
	v_mfma_f32_16x16x32_f16 v[108:111], v[144:147], v[168:171], v[108:111]
	s_waitcnt lgkmcnt(0)
	v_mfma_f32_16x16x32_f16 v[104:107], v[136:139], v[176:179], v[104:107]
	v_mfma_f32_16x16x32_f16 v[100:103], v[144:147], v[176:179], v[100:103]
	s_setprio 0
	s_barrier
	s_add_i32 s41, 0, 0x14000
	s_add_i32 s14, s40, s29
	v_add_u32_e32 v32, s41, v209
	v_lshl_add_u64 v[204:205], s[22:23], 0, v[196:197]
	s_mov_b32 m0, s14
	ds_read_b128 v[180:183], v32
	ds_read_b128 v[188:191], v32 offset:2048
	ds_read_b128 v[184:187], v32 offset:1024
	ds_read_b128 v[192:195], v32 offset:3072
	global_load_lds_dwordx4 v[204:205], off
	v_lshl_add_u64 v[206:207], s[22:23], 0, v[198:199]
	s_add_i32 m0, s14, 0x2000
	s_nop 0
	global_load_lds_dwordx4 v[206:207], off
	s_barrier
	s_waitcnt lgkmcnt(2)
	s_setprio 1
	v_mfma_f32_16x16x32_f16 v[96:99], v[180:183], v[148:151], v[96:99]
	v_mfma_f32_16x16x32_f16 v[92:95], v[188:191], v[148:151], v[92:95]
	v_mfma_f32_16x16x32_f16 v[88:91], v[180:183], v[156:159], v[88:91]
	v_mfma_f32_16x16x32_f16 v[84:87], v[188:191], v[156:159], v[84:87]
	v_mfma_f32_16x16x32_f16 v[80:83], v[180:183], v[164:167], v[80:83]
	v_mfma_f32_16x16x32_f16 v[76:79], v[188:191], v[164:167], v[76:79]
	v_mfma_f32_16x16x32_f16 v[72:75], v[180:183], v[172:175], v[72:75]
	v_mfma_f32_16x16x32_f16 v[68:71], v[188:191], v[172:175], v[68:71]
	s_waitcnt lgkmcnt(0)
	v_mfma_f32_16x16x32_f16 v[96:99], v[184:187], v[152:155], v[96:99]
	v_mfma_f32_16x16x32_f16 v[92:95], v[192:195], v[152:155], v[92:95]
	v_mfma_f32_16x16x32_f16 v[88:91], v[184:187], v[160:163], v[88:91]
	v_mfma_f32_16x16x32_f16 v[84:87], v[192:195], v[160:163], v[84:87]
	v_mfma_f32_16x16x32_f16 v[80:83], v[184:187], v[168:171], v[80:83]
	v_mfma_f32_16x16x32_f16 v[76:79], v[192:195], v[168:171], v[76:79]
	v_mfma_f32_16x16x32_f16 v[72:75], v[184:187], v[176:179], v[72:75]
	v_mfma_f32_16x16x32_f16 v[68:71], v[192:195], v[176:179], v[68:71]
	s_setprio 0
	s_barrier
	s_mov_b32 m0, s30
	v_lshl_add_u64 v[212:213], s[24:25], 0, v[196:197]
	ds_read_b128 v[148:151], v211 offset:16384
	ds_read_b128 v[156:159], v211 offset:18432
	ds_read_b128 v[164:167], v211 offset:20480
	ds_read_b128 v[172:175], v211 offset:22528
	ds_read_b128 v[152:155], v211 offset:17408
	ds_read_b128 v[160:163], v211 offset:19456
	ds_read_b128 v[168:171], v211 offset:21504
	ds_read_b128 v[176:179], v211 offset:23552
	global_load_lds_dwordx4 v[212:213], off
	v_lshl_add_u64 v[214:215], s[24:25], 0, v[198:199]
	s_mov_b32 m0, s31
	s_nop 0
	global_load_lds_dwordx4 v[214:215], off
	s_barrier
	s_waitcnt lgkmcnt(7)
	s_setprio 1
	v_mfma_f32_16x16x32_f16 v[64:67], v[132:135], v[148:151], v[64:67]
	v_mfma_f32_16x16x32_f16 v[60:63], v[140:143], v[148:151], v[60:63]
	s_waitcnt lgkmcnt(6)
	v_mfma_f32_16x16x32_f16 v[56:59], v[132:135], v[156:159], v[56:59]
	v_mfma_f32_16x16x32_f16 v[52:55], v[140:143], v[156:159], v[52:55]
	s_waitcnt lgkmcnt(5)
	v_mfma_f32_16x16x32_f16 v[48:51], v[132:135], v[164:167], v[48:51]
	v_mfma_f32_16x16x32_f16 v[44:47], v[140:143], v[164:167], v[44:47]
	s_waitcnt lgkmcnt(4)
	v_mfma_f32_16x16x32_f16 v[40:43], v[132:135], v[172:175], v[40:43]
	v_mfma_f32_16x16x32_f16 v[34:37], v[140:143], v[172:175], v[36:39]
	s_waitcnt lgkmcnt(3)
	v_mfma_f32_16x16x32_f16 v[64:67], v[136:139], v[152:155], v[64:67]
	v_mfma_f32_16x16x32_f16 v[60:63], v[144:147], v[152:155], v[60:63]
	s_waitcnt lgkmcnt(2)
	v_mfma_f32_16x16x32_f16 v[56:59], v[136:139], v[160:163], v[56:59]
	v_mfma_f32_16x16x32_f16 v[52:55], v[144:147], v[160:163], v[52:55]
	s_waitcnt lgkmcnt(1)
	v_mfma_f32_16x16x32_f16 v[48:51], v[136:139], v[168:171], v[48:51]
	v_mfma_f32_16x16x32_f16 v[44:47], v[144:147], v[168:171], v[44:47]
	s_waitcnt lgkmcnt(0)
	v_mfma_f32_16x16x32_f16 v[40:43], v[136:139], v[176:179], v[40:43]
	v_mfma_f32_16x16x32_f16 v[34:37], v[144:147], v[176:179], v[34:37]
	s_setprio 0
	s_barrier
	s_add_u32 s14, s22, 0x40000
	s_addc_u32 s15, s23, 0
	s_add_i32 s40, s41, s29
	v_lshl_add_u64 v[38:39], s[14:15], 0, v[196:197]
	s_mov_b32 m0, s40
	s_nop 0
	global_load_lds_dwordx4 v[38:39], off
	v_lshl_add_u64 v[38:39], s[14:15], 0, v[198:199]
	s_add_i32 m0, s40, 0x2000
	s_nop 0
	global_load_lds_dwordx4 v[38:39], off
	s_waitcnt vmcnt(6)
	s_barrier
	s_setprio 1
	v_mfma_f32_16x16x32_f16 v[28:31], v[180:183], v[148:151], v[28:31]
	v_mfma_f32_16x16x32_f16 v[24:27], v[188:191], v[148:151], v[24:27]
	v_mfma_f32_16x16x32_f16 v[20:23], v[180:183], v[156:159], v[20:23]
	v_mfma_f32_16x16x32_f16 v[16:19], v[188:191], v[156:159], v[16:19]
	v_mfma_f32_16x16x32_f16 v[12:15], v[180:183], v[164:167], v[12:15]
	v_mfma_f32_16x16x32_f16 v[8:11], v[188:191], v[164:167], v[8:11]
	v_mfma_f32_16x16x32_f16 v[4:7], v[180:183], v[172:175], v[4:7]
	v_mfma_f32_16x16x32_f16 v[0:3], v[188:191], v[172:175], v[0:3]
	v_mfma_f32_16x16x32_f16 v[28:31], v[184:187], v[152:155], v[28:31]
	v_mfma_f32_16x16x32_f16 v[24:27], v[192:195], v[152:155], v[24:27]
	v_mfma_f32_16x16x32_f16 v[20:23], v[184:187], v[160:163], v[20:23]
	v_mfma_f32_16x16x32_f16 v[16:19], v[192:195], v[160:163], v[16:19]
	v_mfma_f32_16x16x32_f16 v[12:15], v[184:187], v[168:171], v[12:15]
	v_mfma_f32_16x16x32_f16 v[8:11], v[192:195], v[168:171], v[8:11]
	v_mfma_f32_16x16x32_f16 v[4:7], v[184:187], v[176:179], v[4:7]
	v_mfma_f32_16x16x32_f16 v[0:3], v[192:195], v[176:179], v[0:3]
	s_setprio 0
	s_barrier
	s_add_i32 s40, 0, 0x18000
	v_add_u32_e32 v32, s40, v209
	ds_read_b128 v[132:135], v32
	ds_read_b128 v[140:143], v32 offset:2048
	ds_read_b128 v[136:139], v32 offset:1024
	ds_read_b128 v[144:147], v32 offset:3072
	s_add_u32 s14, s24, 0x40000
	s_addc_u32 s15, s25, 0
	s_mov_b32 m0, s34
	v_lshl_add_u64 v[38:39], s[14:15], 0, v[196:197]
	ds_read_b128 v[148:151], v211 offset:32768
	ds_read_b128 v[156:159], v211 offset:34816
	ds_read_b128 v[164:167], v211 offset:36864
	ds_read_b128 v[172:175], v211 offset:38912
	ds_read_b128 v[152:155], v211 offset:33792
	ds_read_b128 v[160:163], v211 offset:35840
	ds_read_b128 v[168:171], v211 offset:37888
	ds_read_b128 v[176:179], v211 offset:39936
	global_load_lds_dwordx4 v[38:39], off
	v_lshl_add_u64 v[38:39], s[14:15], 0, v[198:199]
	s_mov_b32 m0, s35
	s_nop 0
	global_load_lds_dwordx4 v[38:39], off
	s_waitcnt lgkmcnt(8)
	s_barrier
	s_waitcnt lgkmcnt(7)
	s_setprio 1
	v_mfma_f32_16x16x32_f16 v[128:131], v[132:135], v[148:151], v[128:131]
	v_mfma_f32_16x16x32_f16 v[124:127], v[140:143], v[148:151], v[124:127]
	s_waitcnt lgkmcnt(6)
	v_mfma_f32_16x16x32_f16 v[120:123], v[132:135], v[156:159], v[120:123]
	v_mfma_f32_16x16x32_f16 v[116:119], v[140:143], v[156:159], v[116:119]
	s_waitcnt lgkmcnt(5)
	v_mfma_f32_16x16x32_f16 v[112:115], v[132:135], v[164:167], v[112:115]
	v_mfma_f32_16x16x32_f16 v[108:111], v[140:143], v[164:167], v[108:111]
	s_waitcnt lgkmcnt(4)
	v_mfma_f32_16x16x32_f16 v[104:107], v[132:135], v[172:175], v[104:107]
	v_mfma_f32_16x16x32_f16 v[100:103], v[140:143], v[172:175], v[100:103]
	s_waitcnt lgkmcnt(3)
	v_mfma_f32_16x16x32_f16 v[128:131], v[136:139], v[152:155], v[128:131]
	v_mfma_f32_16x16x32_f16 v[124:127], v[144:147], v[152:155], v[124:127]
	s_waitcnt lgkmcnt(2)
	v_mfma_f32_16x16x32_f16 v[120:123], v[136:139], v[160:163], v[120:123]
	v_mfma_f32_16x16x32_f16 v[116:119], v[144:147], v[160:163], v[116:119]
	s_waitcnt lgkmcnt(1)
	v_mfma_f32_16x16x32_f16 v[112:115], v[136:139], v[168:171], v[112:115]
	v_mfma_f32_16x16x32_f16 v[108:111], v[144:147], v[168:171], v[108:111]
	s_waitcnt lgkmcnt(0)
	v_mfma_f32_16x16x32_f16 v[104:107], v[136:139], v[176:179], v[104:107]
	v_mfma_f32_16x16x32_f16 v[100:103], v[144:147], v[176:179], v[100:103]
	s_setprio 0
	s_barrier
	s_add_i32 s24, 0, 0x1c000
	s_add_i32 s14, s40, s29
	v_add_u32_e32 v32, s24, v209
	v_lshl_add_u64 v[38:39], v[204:205], 0, s[84:85]
	s_mov_b32 m0, s14
	ds_read_b128 v[180:183], v32
	ds_read_b128 v[188:191], v32 offset:2048
	ds_read_b128 v[184:187], v32 offset:1024
	ds_read_b128 v[192:195], v32 offset:3072
	global_load_lds_dwordx4 v[38:39], off
	v_lshl_add_u64 v[38:39], v[206:207], 0, s[84:85]
	s_add_i32 m0, s14, 0x2000
	s_nop 0
	global_load_lds_dwordx4 v[38:39], off
	s_barrier
	s_waitcnt lgkmcnt(2)
	s_setprio 1
	v_mfma_f32_16x16x32_f16 v[96:99], v[180:183], v[148:151], v[96:99]
	v_mfma_f32_16x16x32_f16 v[92:95], v[188:191], v[148:151], v[92:95]
	v_mfma_f32_16x16x32_f16 v[88:91], v[180:183], v[156:159], v[88:91]
	v_mfma_f32_16x16x32_f16 v[84:87], v[188:191], v[156:159], v[84:87]
	v_mfma_f32_16x16x32_f16 v[80:83], v[180:183], v[164:167], v[80:83]
	v_mfma_f32_16x16x32_f16 v[76:79], v[188:191], v[164:167], v[76:79]
	v_mfma_f32_16x16x32_f16 v[72:75], v[180:183], v[172:175], v[72:75]
	v_mfma_f32_16x16x32_f16 v[68:71], v[188:191], v[172:175], v[68:71]
	s_waitcnt lgkmcnt(0)
	v_mfma_f32_16x16x32_f16 v[96:99], v[184:187], v[152:155], v[96:99]
	v_mfma_f32_16x16x32_f16 v[92:95], v[192:195], v[152:155], v[92:95]
	v_mfma_f32_16x16x32_f16 v[88:91], v[184:187], v[160:163], v[88:91]
	v_mfma_f32_16x16x32_f16 v[84:87], v[192:195], v[160:163], v[84:87]
	v_mfma_f32_16x16x32_f16 v[80:83], v[184:187], v[168:171], v[80:83]
	v_mfma_f32_16x16x32_f16 v[76:79], v[192:195], v[168:171], v[76:79]
	v_mfma_f32_16x16x32_f16 v[72:75], v[184:187], v[176:179], v[72:75]
	v_mfma_f32_16x16x32_f16 v[68:71], v[192:195], v[176:179], v[68:71]
	s_setprio 0
	s_barrier
	s_mov_b32 m0, s36
	v_lshl_add_u64 v[38:39], v[212:213], 0, s[84:85]
	ds_read_b128 v[148:151], v211 offset:49152
	ds_read_b128 v[156:159], v211 offset:51200
	ds_read_b128 v[164:167], v211 offset:53248
	ds_read_b128 v[172:175], v211 offset:55296
	ds_read_b128 v[152:155], v211 offset:50176
	ds_read_b128 v[160:163], v211 offset:52224
	ds_read_b128 v[168:171], v211 offset:54272
	ds_read_b128 v[176:179], v211 offset:56320
	global_load_lds_dwordx4 v[38:39], off
	v_lshl_add_u64 v[38:39], v[214:215], 0, s[84:85]
	s_mov_b32 m0, s37
	s_nop 0
	global_load_lds_dwordx4 v[38:39], off
	s_barrier
	s_waitcnt lgkmcnt(7)
	s_setprio 1
	v_mfma_f32_16x16x32_f16 v[64:67], v[132:135], v[148:151], v[64:67]
	v_mfma_f32_16x16x32_f16 v[60:63], v[140:143], v[148:151], v[60:63]
	s_waitcnt lgkmcnt(6)
	v_mfma_f32_16x16x32_f16 v[56:59], v[132:135], v[156:159], v[56:59]
	v_mfma_f32_16x16x32_f16 v[52:55], v[140:143], v[156:159], v[52:55]
	s_waitcnt lgkmcnt(5)
	v_mfma_f32_16x16x32_f16 v[48:51], v[132:135], v[164:167], v[48:51]
	v_mfma_f32_16x16x32_f16 v[44:47], v[140:143], v[164:167], v[44:47]
	s_waitcnt lgkmcnt(4)
	v_mfma_f32_16x16x32_f16 v[38:41], v[132:135], v[172:175], v[40:43]
	v_mfma_f32_16x16x32_f16 v[34:37], v[140:143], v[172:175], v[34:37]
	s_waitcnt lgkmcnt(3)
	v_mfma_f32_16x16x32_f16 v[64:67], v[136:139], v[152:155], v[64:67]
	v_mfma_f32_16x16x32_f16 v[60:63], v[144:147], v[152:155], v[60:63]
	s_waitcnt lgkmcnt(2)
	v_mfma_f32_16x16x32_f16 v[56:59], v[136:139], v[160:163], v[56:59]
	v_mfma_f32_16x16x32_f16 v[52:55], v[144:147], v[160:163], v[52:55]
	s_waitcnt lgkmcnt(1)
	v_mfma_f32_16x16x32_f16 v[48:51], v[136:139], v[168:171], v[48:51]
	v_mfma_f32_16x16x32_f16 v[44:47], v[144:147], v[168:171], v[44:47]
	s_waitcnt lgkmcnt(0)
	v_mfma_f32_16x16x32_f16 v[40:43], v[136:139], v[176:179], v[38:41]
	v_mfma_f32_16x16x32_f16 v[36:39], v[144:147], v[176:179], v[34:37]
	s_setprio 0
	s_barrier
	s_add_u32 s14, s22, 0x40080
	s_addc_u32 s15, s23, 0
	s_add_i32 s22, s24, s29
	v_lshl_add_u64 v[34:35], s[14:15], 0, v[196:197]
	s_mov_b32 m0, s22
	s_nop 0
	global_load_lds_dwordx4 v[34:35], off
	v_lshl_add_u64 v[34:35], s[14:15], 0, v[198:199]
	s_add_i32 m0, s22, 0x2000
	s_nop 0
	global_load_lds_dwordx4 v[34:35], off
	s_waitcnt vmcnt(6)
	s_barrier
	s_setprio 1
	v_mfma_f32_16x16x32_f16 v[28:31], v[180:183], v[148:151], v[28:31]
	v_mfma_f32_16x16x32_f16 v[24:27], v[188:191], v[148:151], v[24:27]
	v_mfma_f32_16x16x32_f16 v[20:23], v[180:183], v[156:159], v[20:23]
	v_mfma_f32_16x16x32_f16 v[16:19], v[188:191], v[156:159], v[16:19]
	v_mfma_f32_16x16x32_f16 v[12:15], v[180:183], v[164:167], v[12:15]
	v_mfma_f32_16x16x32_f16 v[8:11], v[188:191], v[164:167], v[8:11]
	v_mfma_f32_16x16x32_f16 v[4:7], v[180:183], v[172:175], v[4:7]
	v_mfma_f32_16x16x32_f16 v[0:3], v[188:191], v[172:175], v[0:3]
	v_mfma_f32_16x16x32_f16 v[28:31], v[184:187], v[152:155], v[28:31]
	v_mfma_f32_16x16x32_f16 v[24:27], v[192:195], v[152:155], v[24:27]
	v_mfma_f32_16x16x32_f16 v[20:23], v[184:187], v[160:163], v[20:23]
	v_mfma_f32_16x16x32_f16 v[16:19], v[192:195], v[160:163], v[16:19]
	v_mfma_f32_16x16x32_f16 v[12:15], v[184:187], v[168:171], v[12:15]
	v_mfma_f32_16x16x32_f16 v[8:11], v[192:195], v[168:171], v[8:11]
	v_mfma_f32_16x16x32_f16 v[4:7], v[184:187], v[176:179], v[4:7]
	v_mfma_f32_16x16x32_f16 v[0:3], v[192:195], v[176:179], v[0:3]
	s_setprio 0
	s_barrier
	s_add_i32 s11, s11, 2
	s_add_u32 s1, s1, 0x100
	s_addc_u32 s3, s3, 0
	s_cmp_gt_u32 s11, 13
	s_mov_b64 s[14:15], s[20:21]
	s_cbranch_scc0 .LBB0_940
	v_lshl_add_u32 v34, s12, 8, v208
	v_lshl_or_b32 v156, s10, 8, v210
	s_cmp_lg_u32 s13, 0
	s_cselect_b64 s[10:11], -1, 0
	s_cmp_eq_u32 s13, 0
	v_ashrrev_i32_e32 v157, 31, v156
	v_ashrrev_i32_e32 v35, 31, v34
	v_mad_i64_i32 v[158:159], s[12:13], v34, s33, 0
	v_or_b32_e32 v160, 16, v34
	v_or_b32_e32 v162, 32, v34
	v_or_b32_e32 v164, 48, v34
	s_cbranch_scc1 .LBB0_946
	v_lshl_add_u64 v[132:133], s[70:71], 0, v[158:159]
	v_lshlrev_b64 v[166:167], 1, v[156:157]
	v_lshl_add_u64 v[132:133], v[132:133], 0, v[166:167]
	s_mov_b64 s[16:17], 0x2800
	v_mov_b64_e32 v[168:169], s[70:71]
	s_movk_i32 s1, 0x2000
	v_lshl_add_u64 v[134:135], v[132:133], 0, s[16:17]
	v_mad_i64_i32 v[136:137], s[12:13], v160, s33, v[168:169]
	v_add_co_u32_e32 v132, vcc, s1, v132
	v_lshl_add_u64 v[136:137], v[136:137], 0, v[166:167]
	s_nop 0
	v_addc_co_u32_e32 v133, vcc, 0, v133, vcc
	v_lshl_add_u64 v[138:139], v[136:137], 0, s[16:17]
	v_mad_i64_i32 v[140:141], s[12:13], v162, s33, v[168:169]
	v_add_co_u32_e32 v136, vcc, s1, v136
	v_lshl_add_u64 v[140:141], v[140:141], 0, v[166:167]
	s_nop 0
	v_addc_co_u32_e32 v137, vcc, 0, v137, vcc
	v_mad_i64_i32 v[144:145], s[12:13], v164, s33, v[168:169]
	global_load_dwordx4 v[170:173], v[132:133], off offset:2048
	global_load_dwordx4 v[152:155], v[136:137], off offset:2048
	global_load_dwordx4 v[174:177], v[134:135], off offset:256
	global_load_dwordx4 v[148:151], v[138:139], off offset:256
	v_add_co_u32_e32 v132, vcc, s1, v140
	v_lshl_add_u64 v[144:145], v[144:145], 0, v[166:167]
	s_nop 0
	v_addc_co_u32_e32 v133, vcc, 0, v141, vcc
	v_add_co_u32_e32 v134, vcc, s1, v144
	v_lshl_add_u64 v[142:143], v[140:141], 0, s[16:17]
	s_nop 0
	v_addc_co_u32_e32 v135, vcc, 0, v145, vcc
	v_lshl_add_u64 v[178:179], v[144:145], 0, s[16:17]
	global_load_dwordx4 v[144:147], v[132:133], off offset:2048
	global_load_dwordx4 v[136:139], v[134:135], off offset:2048
	s_nop 0
	global_load_dwordx4 v[140:143], v[142:143], off offset:256
	s_nop 0
	global_load_dwordx4 v[132:135], v[178:179], off offset:256
	v_ashrrev_i32_e32 v161, 31, v160
	v_ashrrev_i32_e32 v163, 31, v162
	v_ashrrev_i32_e32 v165, 31, v164
	s_waitcnt vmcnt(0)
	v_cvt_f32_f16_e32 v32, v170
	v_cvt_f32_f16_sdwa v170, v170 dst_sel:DWORD dst_unused:UNUSED_PAD src0_sel:WORD_1
	v_lshlrev_b64 v[178:179], 11, v[34:35]
	v_readlane_b32 s14, v252, 9
	v_max_f32_e32 v32, 0xc1f00000, v32
	v_max_f32_e32 v35, 0xc1f00000, v170
	v_cvt_f32_f16_e32 v170, v171
	v_cvt_f32_f16_sdwa v171, v171 dst_sel:DWORD dst_unused:UNUSED_PAD src0_sel:WORD_1
	v_mul_f32_e32 v35, 0xbfb8aa3b, v35
	v_exp_f32_e32 v35, v35
	v_max_f32_e32 v170, 0xc1f00000, v170
	v_mul_f32_e32 v170, 0xbfb8aa3b, v170
	v_exp_f32_e32 v180, v170
	v_max_f32_e32 v170, 0xc1f00000, v171
	v_mul_f32_e32 v170, 0xbfb8aa3b, v170
	v_cvt_f32_f16_e32 v171, v172
	v_exp_f32_e32 v181, v170
	v_cvt_f32_f16_sdwa v170, v172 dst_sel:DWORD dst_unused:UNUSED_PAD src0_sel:WORD_1
	v_mul_f32_e32 v32, 0xbfb8aa3b, v32
	v_max_f32_e32 v171, 0xc1f00000, v171
	v_mul_f32_e32 v171, 0xbfb8aa3b, v171
	v_max_f32_e32 v170, 0xc1f00000, v170
	v_mul_f32_e32 v170, 0xbfb8aa3b, v170
	v_exp_f32_e32 v182, v171
	v_cvt_f32_f16_e32 v171, v173
	v_exp_f32_e32 v183, v170
	v_cvt_f32_f16_sdwa v170, v173 dst_sel:DWORD dst_unused:UNUSED_PAD src0_sel:WORD_1
	v_exp_f32_e32 v32, v32
	v_max_f32_e32 v171, 0xc1f00000, v171
	v_mul_f32_e32 v171, 0xbfb8aa3b, v171
	v_max_f32_e32 v170, 0xc1f00000, v170
	v_mul_f32_e32 v170, 0xbfb8aa3b, v170
	v_add_f32_e32 v35, 1.0, v35
	v_exp_f32_e32 v184, v171
	v_exp_f32_e32 v185, v170
	v_rcp_f32_e32 v170, v35
	v_add_f32_e32 v35, 1.0, v180
	v_rcp_f32_e32 v171, v35
	v_add_f32_e32 v35, 1.0, v181
	v_add_f32_e32 v32, 1.0, v32
	v_rcp_f32_e32 v172, v35
	v_add_f32_e32 v35, 1.0, v182
	v_rcp_f32_e32 v32, v32
	v_rcp_f32_e32 v173, v35
	v_add_f32_e32 v35, 1.0, v183
	v_rcp_f32_e32 v180, v35
	v_add_f32_e32 v35, 1.0, v184
	v_rcp_f32_e32 v181, v35
	v_mov_b32_e32 v182, v129
	v_mov_b32_e32 v183, v130
	v_pk_mul_f32 v[170:171], v[182:183], v[170:171]
	v_pk_mov_b32 v[182:183], v[130:131], v[124:125] op_sel:[1,0]
	v_add_f32_e32 v35, 1.0, v185
	v_fma_mixlo_f16 v32, v128, v32, 0
	v_cvt_pk_f16_f32 v171, v170, v171
	v_pk_mul_f32 v[172:173], v[182:183], v[172:173]
	v_rcp_f32_e32 v35, v35
	v_pack_b32_f16 v170, v32, v171
	v_cvt_pk_f16_f32 v32, v172, v173
	v_mov_b32_e32 v172, v125
	v_mov_b32_e32 v173, v126
	v_pk_mul_f32 v[172:173], v[172:173], v[180:181]
	v_readlane_b32 s15, v252, 10
	v_cvt_pk_f16_f32 v173, v172, v173
	v_alignbit_b32 v172, v173, v32, 16
	v_lshrrev_b32_e32 v173, 16, v173
	v_lshl_add_u64 v[178:179], s[14:15], 0, v[178:179]
	v_alignbit_b32 v171, v32, v171, 16
	v_fma_mixhi_f16 v173, v127, v35, 0
	v_lshl_add_u64 v[178:179], v[178:179], 0, v[166:167]
	global_store_dwordx4 v[178:179], v[170:173], off
	v_cvt_f32_f16_sdwa v35, v174 dst_sel:DWORD dst_unused:UNUSED_PAD src0_sel:WORD_1
	v_cvt_f32_f16_e32 v32, v174
	v_cvt_f32_f16_e32 v170, v175
	v_cvt_f32_f16_sdwa v171, v175 dst_sel:DWORD dst_unused:UNUSED_PAD src0_sel:WORD_1
	v_max_f32_e32 v35, 0xc1f00000, v35
	v_mul_f32_e32 v35, 0xbfb8aa3b, v35
	v_max_f32_e32 v170, 0xc1f00000, v170
	v_mul_f32_e32 v170, 0xbfb8aa3b, v170
	v_exp_f32_e32 v172, v170
	v_max_f32_e32 v170, 0xc1f00000, v171
	v_mul_f32_e32 v170, 0xbfb8aa3b, v170
	v_cvt_f32_f16_e32 v171, v176
	v_exp_f32_e32 v173, v170
	v_cvt_f32_f16_sdwa v170, v176 dst_sel:DWORD dst_unused:UNUSED_PAD src0_sel:WORD_1
	v_exp_f32_e32 v35, v35
	v_max_f32_e32 v171, 0xc1f00000, v171
	v_mul_f32_e32 v171, 0xbfb8aa3b, v171
	v_max_f32_e32 v170, 0xc1f00000, v170
	v_mul_f32_e32 v170, 0xbfb8aa3b, v170
	v_exp_f32_e32 v174, v171
	v_cvt_f32_f16_e32 v171, v177
	v_exp_f32_e32 v175, v170
	v_cvt_f32_f16_sdwa v170, v177 dst_sel:DWORD dst_unused:UNUSED_PAD src0_sel:WORD_1
	v_max_f32_e32 v32, 0xc1f00000, v32
	v_mul_f32_e32 v32, 0xbfb8aa3b, v32
	v_exp_f32_e32 v32, v32
	v_max_f32_e32 v171, 0xc1f00000, v171
	v_max_f32_e32 v170, 0xc1f00000, v170
	v_mul_f32_e32 v171, 0xbfb8aa3b, v171
	v_mul_f32_e32 v170, 0xbfb8aa3b, v170
	v_add_f32_e32 v35, 1.0, v35
	v_exp_f32_e32 v176, v171
	v_exp_f32_e32 v177, v170
	v_rcp_f32_e32 v170, v35
	v_add_f32_e32 v35, 1.0, v172
	v_rcp_f32_e32 v171, v35
	v_add_f32_e32 v35, 1.0, v173
	v_add_f32_e32 v32, 1.0, v32
	v_rcp_f32_e32 v172, v35
	v_add_f32_e32 v35, 1.0, v174
	v_rcp_f32_e32 v32, v32
	v_rcp_f32_e32 v173, v35
	v_add_f32_e32 v35, 1.0, v175
	v_rcp_f32_e32 v174, v35
	v_add_f32_e32 v35, 1.0, v176
	v_rcp_f32_e32 v175, v35
	v_add_f32_e32 v35, 1.0, v177
	v_mov_b32_e32 v176, v97
	v_mov_b32_e32 v177, v98
	v_pk_mul_f32 v[170:171], v[176:177], v[170:171]
	v_pk_mov_b32 v[176:177], v[98:99], v[92:93] op_sel:[1,0]
	v_fma_mixlo_f16 v32, v96, v32, 0
	v_cvt_pk_f16_f32 v171, v170, v171
	v_pk_mul_f32 v[172:173], v[176:177], v[172:173]
	v_rcp_f32_e32 v35, v35
	v_pack_b32_f16 v170, v32, v171
	v_cvt_pk_f16_f32 v32, v172, v173
	v_mov_b32_e32 v172, v93
	v_mov_b32_e32 v173, v94
	v_pk_mul_f32 v[172:173], v[172:173], v[174:175]
	v_alignbit_b32 v171, v32, v171, 16
	v_cvt_pk_f16_f32 v173, v172, v173
	v_alignbit_b32 v172, v173, v32, 16
	v_lshrrev_b32_e32 v173, 16, v173
	v_fma_mixhi_f16 v173, v95, v35, 0
	v_cvt_f32_f16_e32 v32, v152
	v_cvt_f32_f16_sdwa v35, v152 dst_sel:DWORD dst_unused:UNUSED_PAD src0_sel:WORD_1
	v_cvt_f32_f16_e32 v152, v153
	v_cvt_f32_f16_sdwa v153, v153 dst_sel:DWORD dst_unused:UNUSED_PAD src0_sel:WORD_1
	global_store_dwordx4 v[178:179], v[170:173], off offset:256
	v_max_f32_e32 v35, 0xc1f00000, v35
	v_max_f32_e32 v152, 0xc1f00000, v152
	v_mul_f32_e32 v152, 0xbfb8aa3b, v152
	v_lshlrev_b64 v[170:171], 11, v[160:161]
	v_exp_f32_e32 v161, v152
	v_max_f32_e32 v152, 0xc1f00000, v153
	v_mul_f32_e32 v152, 0xbfb8aa3b, v152
	v_cvt_f32_f16_e32 v153, v154
	v_exp_f32_e32 v172, v152
	v_cvt_f32_f16_sdwa v152, v154 dst_sel:DWORD dst_unused:UNUSED_PAD src0_sel:WORD_1
	v_mul_f32_e32 v35, 0xbfb8aa3b, v35
	v_max_f32_e32 v153, 0xc1f00000, v153
	v_mul_f32_e32 v153, 0xbfb8aa3b, v153
	v_max_f32_e32 v152, 0xc1f00000, v152
	v_mul_f32_e32 v152, 0xbfb8aa3b, v152
	v_exp_f32_e32 v173, v153
	v_cvt_f32_f16_e32 v153, v155
	v_exp_f32_e32 v174, v152
	v_cvt_f32_f16_sdwa v152, v155 dst_sel:DWORD dst_unused:UNUSED_PAD src0_sel:WORD_1
	v_exp_f32_e32 v35, v35
	v_max_f32_e32 v32, 0xc1f00000, v32
	v_mul_f32_e32 v32, 0xbfb8aa3b, v32
	v_exp_f32_e32 v32, v32
	v_max_f32_e32 v153, 0xc1f00000, v153
	v_max_f32_e32 v152, 0xc1f00000, v152
	v_mul_f32_e32 v153, 0xbfb8aa3b, v153
	v_mul_f32_e32 v152, 0xbfb8aa3b, v152
	v_add_f32_e32 v35, 1.0, v35
	v_exp_f32_e32 v175, v153
	v_exp_f32_e32 v176, v152
	v_rcp_f32_e32 v152, v35
	v_add_f32_e32 v35, 1.0, v161
	v_rcp_f32_e32 v153, v35
	v_add_f32_e32 v35, 1.0, v172
	v_add_f32_e32 v32, 1.0, v32
	v_rcp_f32_e32 v154, v35
	v_add_f32_e32 v35, 1.0, v173
	v_rcp_f32_e32 v32, v32
	v_rcp_f32_e32 v155, v35
	v_add_f32_e32 v35, 1.0, v174
	v_rcp_f32_e32 v172, v35
	v_add_f32_e32 v35, 1.0, v175
	v_rcp_f32_e32 v173, v35
	v_mov_b32_e32 v174, v121
	v_mov_b32_e32 v175, v122
	v_pk_mul_f32 v[152:153], v[174:175], v[152:153]
	v_pk_mov_b32 v[174:175], v[122:123], v[116:117] op_sel:[1,0]
	v_add_f32_e32 v35, 1.0, v176
	v_fma_mixlo_f16 v32, v120, v32, 0
	v_cvt_pk_f16_f32 v153, v152, v153
	v_pk_mul_f32 v[154:155], v[174:175], v[154:155]
	v_rcp_f32_e32 v35, v35
	v_pack_b32_f16 v152, v32, v153
	v_cvt_pk_f16_f32 v32, v154, v155
	v_mov_b32_e32 v154, v117
	v_mov_b32_e32 v155, v118
	v_pk_mul_f32 v[154:155], v[154:155], v[172:173]
	v_alignbit_b32 v153, v32, v153, 16
	v_cvt_pk_f16_f32 v155, v154, v155
	v_alignbit_b32 v154, v155, v32, 16
	v_lshrrev_b32_e32 v155, 16, v155
	v_fma_mixhi_f16 v155, v119, v35, 0
	v_cvt_f32_f16_e32 v32, v148
	v_cvt_f32_f16_sdwa v35, v148 dst_sel:DWORD dst_unused:UNUSED_PAD src0_sel:WORD_1
	v_cvt_f32_f16_e32 v148, v149
	v_cvt_f32_f16_sdwa v149, v149 dst_sel:DWORD dst_unused:UNUSED_PAD src0_sel:WORD_1
	v_lshl_add_u64 v[170:171], s[14:15], 0, v[170:171]
	v_lshl_add_u64 v[170:171], v[170:171], 0, v[166:167]
	v_max_f32_e32 v148, 0xc1f00000, v148
	v_mul_f32_e32 v148, 0xbfb8aa3b, v148
	global_store_dwordx4 v[170:171], v[152:155], off
	v_max_f32_e32 v35, 0xc1f00000, v35
	v_mul_f32_e32 v35, 0xbfb8aa3b, v35
	v_exp_f32_e32 v152, v148
	v_max_f32_e32 v148, 0xc1f00000, v149
	v_mul_f32_e32 v148, 0xbfb8aa3b, v148
	v_cvt_f32_f16_e32 v149, v150
	v_exp_f32_e32 v153, v148
	v_cvt_f32_f16_sdwa v148, v150 dst_sel:DWORD dst_unused:UNUSED_PAD src0_sel:WORD_1
	v_exp_f32_e32 v35, v35
	v_max_f32_e32 v149, 0xc1f00000, v149
	v_mul_f32_e32 v149, 0xbfb8aa3b, v149
	v_max_f32_e32 v148, 0xc1f00000, v148
	v_mul_f32_e32 v148, 0xbfb8aa3b, v148
	v_exp_f32_e32 v154, v149
	v_cvt_f32_f16_e32 v149, v151
	v_exp_f32_e32 v155, v148
	v_cvt_f32_f16_sdwa v148, v151 dst_sel:DWORD dst_unused:UNUSED_PAD src0_sel:WORD_1
	v_max_f32_e32 v32, 0xc1f00000, v32
	v_mul_f32_e32 v32, 0xbfb8aa3b, v32
	v_exp_f32_e32 v32, v32
	v_max_f32_e32 v149, 0xc1f00000, v149
	v_max_f32_e32 v148, 0xc1f00000, v148
	v_mul_f32_e32 v149, 0xbfb8aa3b, v149
	v_mul_f32_e32 v148, 0xbfb8aa3b, v148
	v_add_f32_e32 v35, 1.0, v35
	v_exp_f32_e32 v161, v149
	v_exp_f32_e32 v172, v148
	v_rcp_f32_e32 v148, v35
	v_add_f32_e32 v35, 1.0, v152
	v_rcp_f32_e32 v149, v35
	v_add_f32_e32 v35, 1.0, v153
	v_add_f32_e32 v32, 1.0, v32
	v_rcp_f32_e32 v150, v35
	v_add_f32_e32 v35, 1.0, v154
	v_rcp_f32_e32 v32, v32
	v_rcp_f32_e32 v151, v35
	v_add_f32_e32 v35, 1.0, v155
	v_rcp_f32_e32 v152, v35
	v_add_f32_e32 v35, 1.0, v161
	v_rcp_f32_e32 v153, v35
	v_mov_b32_e32 v154, v89
	v_mov_b32_e32 v155, v90
	v_pk_mul_f32 v[148:149], v[154:155], v[148:149]
	v_pk_mov_b32 v[154:155], v[90:91], v[84:85] op_sel:[1,0]
	v_add_f32_e32 v35, 1.0, v172
	v_fma_mixlo_f16 v32, v88, v32, 0
	v_cvt_pk_f16_f32 v149, v148, v149
	v_pk_mul_f32 v[150:151], v[154:155], v[150:151]
	v_rcp_f32_e32 v35, v35
	v_pack_b32_f16 v148, v32, v149
	v_cvt_pk_f16_f32 v32, v150, v151
	v_mov_b32_e32 v150, v85
	v_mov_b32_e32 v151, v86
	v_pk_mul_f32 v[150:151], v[150:151], v[152:153]
	v_alignbit_b32 v149, v32, v149, 16
	v_cvt_pk_f16_f32 v151, v150, v151
	v_alignbit_b32 v150, v151, v32, 16
	v_lshrrev_b32_e32 v151, 16, v151
	v_fma_mixhi_f16 v151, v87, v35, 0
	v_cvt_f32_f16_e32 v32, v144
	v_cvt_f32_f16_sdwa v35, v144 dst_sel:DWORD dst_unused:UNUSED_PAD src0_sel:WORD_1
	v_cvt_f32_f16_e32 v144, v145
	v_cvt_f32_f16_sdwa v145, v145 dst_sel:DWORD dst_unused:UNUSED_PAD src0_sel:WORD_1
	global_store_dwordx4 v[170:171], v[148:151], off offset:256
	v_max_f32_e32 v35, 0xc1f00000, v35
	v_max_f32_e32 v144, 0xc1f00000, v144
	v_mul_f32_e32 v144, 0xbfb8aa3b, v144
	v_exp_f32_e32 v150, v144
	v_max_f32_e32 v144, 0xc1f00000, v145
	v_mul_f32_e32 v144, 0xbfb8aa3b, v144
	v_cvt_f32_f16_e32 v145, v146
	v_exp_f32_e32 v151, v144
	v_cvt_f32_f16_sdwa v144, v146 dst_sel:DWORD dst_unused:UNUSED_PAD src0_sel:WORD_1
	v_mul_f32_e32 v35, 0xbfb8aa3b, v35
	v_max_f32_e32 v145, 0xc1f00000, v145
	v_mul_f32_e32 v145, 0xbfb8aa3b, v145
	v_max_f32_e32 v144, 0xc1f00000, v144
	v_mul_f32_e32 v144, 0xbfb8aa3b, v144
	v_exp_f32_e32 v152, v145
	v_cvt_f32_f16_e32 v145, v147
	v_exp_f32_e32 v153, v144
	v_cvt_f32_f16_sdwa v144, v147 dst_sel:DWORD dst_unused:UNUSED_PAD src0_sel:WORD_1
	v_exp_f32_e32 v35, v35
	v_max_f32_e32 v32, 0xc1f00000, v32
	v_mul_f32_e32 v32, 0xbfb8aa3b, v32
	v_exp_f32_e32 v32, v32
	v_max_f32_e32 v145, 0xc1f00000, v145
	v_max_f32_e32 v144, 0xc1f00000, v144
	v_mul_f32_e32 v145, 0xbfb8aa3b, v145
	v_mul_f32_e32 v144, 0xbfb8aa3b, v144
	v_add_f32_e32 v35, 1.0, v35
	v_exp_f32_e32 v154, v145
	v_exp_f32_e32 v155, v144
	v_rcp_f32_e32 v144, v35
	v_add_f32_e32 v35, 1.0, v150
	v_rcp_f32_e32 v145, v35
	v_add_f32_e32 v35, 1.0, v151
	v_add_f32_e32 v32, 1.0, v32
	v_rcp_f32_e32 v146, v35
	v_add_f32_e32 v35, 1.0, v152
	v_rcp_f32_e32 v32, v32
	v_rcp_f32_e32 v147, v35
	v_add_f32_e32 v35, 1.0, v153
	v_rcp_f32_e32 v150, v35
	v_add_f32_e32 v35, 1.0, v154
	v_rcp_f32_e32 v151, v35
	v_mov_b32_e32 v152, v113
	v_mov_b32_e32 v153, v114
	v_pk_mul_f32 v[144:145], v[152:153], v[144:145]
	v_pk_mov_b32 v[152:153], v[114:115], v[108:109] op_sel:[1,0]
	v_add_f32_e32 v35, 1.0, v155
	v_fma_mixlo_f16 v32, v112, v32, 0
	v_cvt_pk_f16_f32 v145, v144, v145
	v_pk_mul_f32 v[146:147], v[152:153], v[146:147]
	v_rcp_f32_e32 v35, v35
	v_pack_b32_f16 v144, v32, v145
	v_cvt_pk_f16_f32 v32, v146, v147
	v_mov_b32_e32 v146, v109
	v_mov_b32_e32 v147, v110
	v_pk_mul_f32 v[146:147], v[146:147], v[150:151]
	v_alignbit_b32 v145, v32, v145, 16
	v_cvt_pk_f16_f32 v147, v146, v147
	v_alignbit_b32 v146, v147, v32, 16
	v_lshrrev_b32_e32 v147, 16, v147
	v_fma_mixhi_f16 v147, v111, v35, 0
	v_cvt_f32_f16_e32 v32, v140
	v_cvt_f32_f16_sdwa v35, v140 dst_sel:DWORD dst_unused:UNUSED_PAD src0_sel:WORD_1
	v_cvt_f32_f16_e32 v140, v141
	v_cvt_f32_f16_sdwa v141, v141 dst_sel:DWORD dst_unused:UNUSED_PAD src0_sel:WORD_1
	v_lshlrev_b64 v[148:149], 11, v[162:163]
	v_lshl_add_u64 v[148:149], s[14:15], 0, v[148:149]
	v_max_f32_e32 v140, 0xc1f00000, v140
	v_lshl_add_u64 v[148:149], v[148:149], 0, v[166:167]
	v_mul_f32_e32 v140, 0xbfb8aa3b, v140
	global_store_dwordx4 v[148:149], v[144:147], off
	v_max_f32_e32 v35, 0xc1f00000, v35
	v_mul_f32_e32 v35, 0xbfb8aa3b, v35
	v_exp_f32_e32 v144, v140
	v_max_f32_e32 v140, 0xc1f00000, v141
	v_mul_f32_e32 v140, 0xbfb8aa3b, v140
	v_cvt_f32_f16_e32 v141, v142
	v_exp_f32_e32 v145, v140
	v_cvt_f32_f16_sdwa v140, v142 dst_sel:DWORD dst_unused:UNUSED_PAD src0_sel:WORD_1
	v_exp_f32_e32 v35, v35
	v_max_f32_e32 v141, 0xc1f00000, v141
	v_mul_f32_e32 v141, 0xbfb8aa3b, v141
	v_max_f32_e32 v140, 0xc1f00000, v140
	v_mul_f32_e32 v140, 0xbfb8aa3b, v140
	v_exp_f32_e32 v146, v141
	v_cvt_f32_f16_e32 v141, v143
	v_exp_f32_e32 v147, v140
	v_cvt_f32_f16_sdwa v140, v143 dst_sel:DWORD dst_unused:UNUSED_PAD src0_sel:WORD_1
	v_max_f32_e32 v32, 0xc1f00000, v32
	v_mul_f32_e32 v32, 0xbfb8aa3b, v32
	v_exp_f32_e32 v32, v32
	v_max_f32_e32 v141, 0xc1f00000, v141
	v_max_f32_e32 v140, 0xc1f00000, v140
	v_mul_f32_e32 v141, 0xbfb8aa3b, v141
	v_mul_f32_e32 v140, 0xbfb8aa3b, v140
	v_add_f32_e32 v35, 1.0, v35
	v_exp_f32_e32 v150, v141
	v_exp_f32_e32 v151, v140
	v_rcp_f32_e32 v140, v35
	v_add_f32_e32 v35, 1.0, v144
	v_rcp_f32_e32 v141, v35
	v_add_f32_e32 v35, 1.0, v145
	v_add_f32_e32 v32, 1.0, v32
	v_rcp_f32_e32 v142, v35
	v_add_f32_e32 v35, 1.0, v146
	v_rcp_f32_e32 v32, v32
	v_rcp_f32_e32 v143, v35
	v_add_f32_e32 v35, 1.0, v147
	v_rcp_f32_e32 v144, v35
	v_add_f32_e32 v35, 1.0, v150
	v_rcp_f32_e32 v145, v35
	v_mov_b32_e32 v146, v81
	v_mov_b32_e32 v147, v82
	v_pk_mul_f32 v[140:141], v[146:147], v[140:141]
	v_pk_mov_b32 v[146:147], v[82:83], v[76:77] op_sel:[1,0]
	v_add_f32_e32 v35, 1.0, v151
	v_fma_mixlo_f16 v32, v80, v32, 0
	v_cvt_pk_f16_f32 v141, v140, v141
	v_pk_mul_f32 v[142:143], v[146:147], v[142:143]
	v_rcp_f32_e32 v35, v35
	v_pack_b32_f16 v140, v32, v141
	v_cvt_pk_f16_f32 v32, v142, v143
	v_mov_b32_e32 v142, v77
	v_mov_b32_e32 v143, v78
	v_pk_mul_f32 v[142:143], v[142:143], v[144:145]
	v_alignbit_b32 v141, v32, v141, 16
	v_cvt_pk_f16_f32 v143, v142, v143
	v_alignbit_b32 v142, v143, v32, 16
	v_lshrrev_b32_e32 v143, 16, v143
	v_fma_mixhi_f16 v143, v79, v35, 0
	v_cvt_f32_f16_e32 v32, v136
	v_cvt_f32_f16_sdwa v35, v136 dst_sel:DWORD dst_unused:UNUSED_PAD src0_sel:WORD_1
	v_cvt_f32_f16_e32 v136, v137
	v_cvt_f32_f16_sdwa v137, v137 dst_sel:DWORD dst_unused:UNUSED_PAD src0_sel:WORD_1
	global_store_dwordx4 v[148:149], v[140:143], off offset:256
	v_max_f32_e32 v35, 0xc1f00000, v35
	v_max_f32_e32 v136, 0xc1f00000, v136
	v_mul_f32_e32 v136, 0xbfb8aa3b, v136
	v_exp_f32_e32 v142, v136
	v_max_f32_e32 v136, 0xc1f00000, v137
	v_mul_f32_e32 v136, 0xbfb8aa3b, v136
	v_cvt_f32_f16_e32 v137, v138
	v_exp_f32_e32 v143, v136
	v_cvt_f32_f16_sdwa v136, v138 dst_sel:DWORD dst_unused:UNUSED_PAD src0_sel:WORD_1
	v_mul_f32_e32 v35, 0xbfb8aa3b, v35
	v_max_f32_e32 v137, 0xc1f00000, v137
	v_mul_f32_e32 v137, 0xbfb8aa3b, v137
	v_max_f32_e32 v136, 0xc1f00000, v136
	v_mul_f32_e32 v136, 0xbfb8aa3b, v136
	v_exp_f32_e32 v144, v137
	v_cvt_f32_f16_e32 v137, v139
	v_exp_f32_e32 v145, v136
	v_cvt_f32_f16_sdwa v136, v139 dst_sel:DWORD dst_unused:UNUSED_PAD src0_sel:WORD_1
	v_exp_f32_e32 v35, v35
	v_max_f32_e32 v32, 0xc1f00000, v32
	v_mul_f32_e32 v32, 0xbfb8aa3b, v32
	v_exp_f32_e32 v32, v32
	v_max_f32_e32 v137, 0xc1f00000, v137
	v_max_f32_e32 v136, 0xc1f00000, v136
	v_mul_f32_e32 v137, 0xbfb8aa3b, v137
	v_mul_f32_e32 v136, 0xbfb8aa3b, v136
	v_add_f32_e32 v35, 1.0, v35
	v_exp_f32_e32 v146, v137
	v_exp_f32_e32 v147, v136
	v_rcp_f32_e32 v136, v35
	v_add_f32_e32 v35, 1.0, v142
	v_rcp_f32_e32 v137, v35
	v_add_f32_e32 v35, 1.0, v143
	v_add_f32_e32 v32, 1.0, v32
	v_rcp_f32_e32 v138, v35
	v_add_f32_e32 v35, 1.0, v144
	v_rcp_f32_e32 v32, v32
	v_rcp_f32_e32 v139, v35
	v_add_f32_e32 v35, 1.0, v145
	v_rcp_f32_e32 v142, v35
	v_add_f32_e32 v35, 1.0, v146
	v_rcp_f32_e32 v143, v35
	v_mov_b32_e32 v144, v105
	v_mov_b32_e32 v145, v106
	v_pk_mul_f32 v[136:137], v[144:145], v[136:137]
	v_pk_mov_b32 v[144:145], v[106:107], v[100:101] op_sel:[1,0]
	v_add_f32_e32 v35, 1.0, v147
	v_fma_mixlo_f16 v32, v104, v32, 0
	v_cvt_pk_f16_f32 v137, v136, v137
	v_pk_mul_f32 v[138:139], v[144:145], v[138:139]
	v_rcp_f32_e32 v35, v35
	v_pack_b32_f16 v136, v32, v137
	v_cvt_pk_f16_f32 v32, v138, v139
	v_mov_b32_e32 v138, v101
	v_mov_b32_e32 v139, v102
	v_pk_mul_f32 v[138:139], v[138:139], v[142:143]
	v_alignbit_b32 v137, v32, v137, 16
	v_cvt_pk_f16_f32 v139, v138, v139
	v_alignbit_b32 v138, v139, v32, 16
	v_lshrrev_b32_e32 v139, 16, v139
	v_fma_mixhi_f16 v139, v103, v35, 0
	v_cvt_f32_f16_e32 v32, v132
	v_cvt_f32_f16_sdwa v35, v132 dst_sel:DWORD dst_unused:UNUSED_PAD src0_sel:WORD_1
	v_cvt_f32_f16_e32 v132, v133
	v_cvt_f32_f16_sdwa v133, v133 dst_sel:DWORD dst_unused:UNUSED_PAD src0_sel:WORD_1
	v_lshlrev_b64 v[140:141], 11, v[164:165]
	v_lshl_add_u64 v[140:141], s[14:15], 0, v[140:141]
	v_max_f32_e32 v132, 0xc1f00000, v132
	v_lshl_add_u64 v[140:141], v[140:141], 0, v[166:167]
	v_mul_f32_e32 v132, 0xbfb8aa3b, v132
	global_store_dwordx4 v[140:141], v[136:139], off
	v_max_f32_e32 v35, 0xc1f00000, v35
	v_mul_f32_e32 v35, 0xbfb8aa3b, v35
	v_exp_f32_e32 v136, v132
	v_max_f32_e32 v132, 0xc1f00000, v133
	v_mul_f32_e32 v132, 0xbfb8aa3b, v132
	v_cvt_f32_f16_e32 v133, v134
	v_exp_f32_e32 v137, v132
	v_cvt_f32_f16_sdwa v132, v134 dst_sel:DWORD dst_unused:UNUSED_PAD src0_sel:WORD_1
	v_exp_f32_e32 v35, v35
	v_max_f32_e32 v133, 0xc1f00000, v133
	v_mul_f32_e32 v133, 0xbfb8aa3b, v133
	v_max_f32_e32 v132, 0xc1f00000, v132
	v_mul_f32_e32 v132, 0xbfb8aa3b, v132
	v_exp_f32_e32 v138, v133
	v_cvt_f32_f16_e32 v133, v135
	v_exp_f32_e32 v139, v132
	v_cvt_f32_f16_sdwa v132, v135 dst_sel:DWORD dst_unused:UNUSED_PAD src0_sel:WORD_1
	v_max_f32_e32 v32, 0xc1f00000, v32
	v_mul_f32_e32 v32, 0xbfb8aa3b, v32
	v_exp_f32_e32 v32, v32
	v_max_f32_e32 v133, 0xc1f00000, v133
	v_max_f32_e32 v132, 0xc1f00000, v132
	v_mul_f32_e32 v133, 0xbfb8aa3b, v133
	v_mul_f32_e32 v132, 0xbfb8aa3b, v132
	v_add_f32_e32 v35, 1.0, v35
	v_exp_f32_e32 v142, v133
	v_exp_f32_e32 v143, v132
	v_rcp_f32_e32 v132, v35
	v_add_f32_e32 v35, 1.0, v136
	v_rcp_f32_e32 v133, v35
	v_add_f32_e32 v35, 1.0, v137
	v_add_f32_e32 v32, 1.0, v32
	v_rcp_f32_e32 v134, v35
	v_add_f32_e32 v35, 1.0, v138
	v_rcp_f32_e32 v32, v32
	v_rcp_f32_e32 v135, v35
	v_add_f32_e32 v35, 1.0, v139
	v_rcp_f32_e32 v136, v35
	v_add_f32_e32 v35, 1.0, v142
	v_rcp_f32_e32 v137, v35
	v_mov_b32_e32 v138, v73
	v_mov_b32_e32 v139, v74
	v_pk_mul_f32 v[132:133], v[138:139], v[132:133]
	v_pk_mov_b32 v[138:139], v[74:75], v[68:69] op_sel:[1,0]
	v_add_f32_e32 v35, 1.0, v143
	v_fma_mixlo_f16 v32, v72, v32, 0
	v_cvt_pk_f16_f32 v133, v132, v133
	v_pk_mul_f32 v[134:135], v[138:139], v[134:135]
	v_rcp_f32_e32 v35, v35
	v_pack_b32_f16 v132, v32, v133
	v_cvt_pk_f16_f32 v32, v134, v135
	v_mov_b32_e32 v134, v69
	v_mov_b32_e32 v135, v70
	v_pk_mul_f32 v[134:135], v[134:135], v[136:137]
	v_alignbit_b32 v133, v32, v133, 16
	v_cvt_pk_f16_f32 v135, v134, v135
	v_alignbit_b32 v134, v135, v32, 16
	v_lshrrev_b32_e32 v135, 16, v135
	v_fma_mixhi_f16 v135, v71, v35, 0
	global_store_dwordx4 v[140:141], v[132:135], off offset:256
	v_add_u32_e32 v184, 0x80, v34
	s_nop 0
	v_mad_i64_i32 v[132:133], s[12:13], v184, s33, v[168:169]
	v_lshl_add_u64 v[132:133], v[132:133], 0, v[166:167]
	v_add_u32_e32 v174, 0x90, v34
	v_lshl_add_u64 v[134:135], v[132:133], 0, s[16:17]
	v_mad_i64_i32 v[136:137], s[12:13], v174, s33, v[168:169]
	v_add_co_u32_e32 v132, vcc, s1, v132
	v_lshl_add_u64 v[136:137], v[136:137], 0, v[166:167]
	v_add_u32_e32 v172, 0xa0, v34
	v_addc_co_u32_e32 v133, vcc, 0, v133, vcc
	v_lshl_add_u64 v[138:139], v[136:137], 0, s[16:17]
	v_mad_i64_i32 v[140:141], s[12:13], v172, s33, v[168:169]
	v_add_co_u32_e32 v136, vcc, s1, v136
	v_lshl_add_u64 v[140:141], v[140:141], 0, v[166:167]
	v_add_u32_e32 v170, 0xb0, v34
	v_addc_co_u32_e32 v137, vcc, 0, v137, vcc
	v_mad_i64_i32 v[144:145], s[12:13], v170, s33, v[168:169]
	global_load_dwordx4 v[176:179], v[132:133], off offset:2048
	global_load_dwordx4 v[152:155], v[136:137], off offset:2048
	global_load_dwordx4 v[180:183], v[134:135], off offset:256
	global_load_dwordx4 v[148:151], v[138:139], off offset:256
	v_add_co_u32_e32 v132, vcc, s1, v140
	v_lshl_add_u64 v[144:145], v[144:145], 0, v[166:167]
	s_nop 0
	v_addc_co_u32_e32 v133, vcc, 0, v141, vcc
	v_add_co_u32_e32 v134, vcc, s1, v144
	v_lshl_add_u64 v[142:143], v[140:141], 0, s[16:17]
	s_nop 0
	v_addc_co_u32_e32 v135, vcc, 0, v145, vcc
	v_lshl_add_u64 v[168:169], v[144:145], 0, s[16:17]
	global_load_dwordx4 v[144:147], v[132:133], off offset:2048
	global_load_dwordx4 v[136:139], v[134:135], off offset:2048
	s_nop 0
	global_load_dwordx4 v[140:143], v[142:143], off offset:256
	s_nop 0
	global_load_dwordx4 v[132:135], v[168:169], off offset:256
	v_ashrrev_i32_e32 v185, 31, v184
	v_ashrrev_i32_e32 v175, 31, v174
	v_ashrrev_i32_e32 v173, 31, v172
	v_ashrrev_i32_e32 v171, 31, v170
	s_waitcnt vmcnt(0)
	v_cvt_f32_f16_e32 v32, v176
	v_cvt_f32_f16_sdwa v35, v176 dst_sel:DWORD dst_unused:UNUSED_PAD src0_sel:WORD_1
	v_cvt_f32_f16_sdwa v176, v178 dst_sel:DWORD dst_unused:UNUSED_PAD src0_sel:WORD_1
	v_cvt_f32_f16_e32 v161, v177
	v_cvt_f32_f16_sdwa v163, v177 dst_sel:DWORD dst_unused:UNUSED_PAD src0_sel:WORD_1
	v_cvt_f32_f16_e32 v165, v178
	v_max_f32_e32 v176, 0xc1f00000, v176
	v_max_f32_e32 v35, 0xc1f00000, v35
	v_mul_f32_e32 v176, 0xbfb8aa3b, v176
	v_lshlrev_b64 v[168:169], 11, v[184:185]
	v_mul_f32_e32 v35, 0xbfb8aa3b, v35
	v_max_f32_e32 v161, 0xc1f00000, v161
	v_cvt_f32_f16_e32 v177, v179
	v_exp_f32_e32 v184, v176
	v_cvt_f32_f16_sdwa v176, v179 dst_sel:DWORD dst_unused:UNUSED_PAD src0_sel:WORD_1
	v_exp_f32_e32 v35, v35
	v_mul_f32_e32 v161, 0xbfb8aa3b, v161
	v_max_f32_e32 v163, 0xc1f00000, v163
	v_max_f32_e32 v32, 0xc1f00000, v32
	v_exp_f32_e32 v161, v161
	v_mul_f32_e32 v163, 0xbfb8aa3b, v163
	v_max_f32_e32 v165, 0xc1f00000, v165
	v_mul_f32_e32 v32, 0xbfb8aa3b, v32
	v_exp_f32_e32 v163, v163
	v_mul_f32_e32 v165, 0xbfb8aa3b, v165
	v_exp_f32_e32 v32, v32
	v_exp_f32_e32 v165, v165
	v_max_f32_e32 v177, 0xc1f00000, v177
	v_max_f32_e32 v176, 0xc1f00000, v176
	v_mul_f32_e32 v177, 0xbfb8aa3b, v177
	v_mul_f32_e32 v176, 0xbfb8aa3b, v176
	v_add_f32_e32 v35, 1.0, v35
	v_exp_f32_e32 v185, v177
	v_exp_f32_e32 v186, v176
	v_rcp_f32_e32 v176, v35
	v_add_f32_e32 v35, 1.0, v161
	v_rcp_f32_e32 v177, v35
	v_add_f32_e32 v35, 1.0, v163
	v_add_f32_e32 v32, 1.0, v32
	v_rcp_f32_e32 v178, v35
	v_add_f32_e32 v35, 1.0, v165
	v_rcp_f32_e32 v32, v32
	v_rcp_f32_e32 v179, v35
	v_add_f32_e32 v35, 1.0, v184
	v_rcp_f32_e32 v184, v35
	v_add_f32_e32 v35, 1.0, v185
	v_rcp_f32_e32 v185, v35
	v_add_f32_e32 v35, 1.0, v186
	v_mov_b32_e32 v186, v65
	v_mov_b32_e32 v187, v66
	v_pk_mul_f32 v[176:177], v[186:187], v[176:177]
	v_pk_mov_b32 v[186:187], v[66:67], v[60:61] op_sel:[1,0]
	v_fma_mixlo_f16 v32, v64, v32, 0
	v_cvt_pk_f16_f32 v161, v176, v177
	v_pk_mul_f32 v[178:179], v[186:187], v[178:179]
	v_rcp_f32_e32 v35, v35
	v_pack_b32_f16 v176, v32, v161
	v_cvt_pk_f16_f32 v32, v178, v179
	v_mov_b32_e32 v178, v61
	v_mov_b32_e32 v179, v62
	v_pk_mul_f32 v[178:179], v[178:179], v[184:185]
	v_alignbit_b32 v177, v32, v161, 16
	v_cvt_pk_f16_f32 v161, v178, v179
	v_lshrrev_b32_e32 v179, 16, v161
	v_lshl_add_u64 v[168:169], s[14:15], 0, v[168:169]
	v_alignbit_b32 v178, v161, v32, 16
	v_fma_mixhi_f16 v179, v63, v35, 0
	v_lshl_add_u64 v[168:169], v[168:169], 0, v[166:167]
	global_store_dwordx4 v[168:169], v[176:179], off
	v_cvt_f32_f16_sdwa v35, v180 dst_sel:DWORD dst_unused:UNUSED_PAD src0_sel:WORD_1
	v_cvt_f32_f16_e32 v161, v181
	v_cvt_f32_f16_sdwa v176, v182 dst_sel:DWORD dst_unused:UNUSED_PAD src0_sel:WORD_1
	v_cvt_f32_f16_sdwa v163, v181 dst_sel:DWORD dst_unused:UNUSED_PAD src0_sel:WORD_1
	v_cvt_f32_f16_e32 v32, v180
	v_cvt_f32_f16_e32 v165, v182
	v_max_f32_e32 v176, 0xc1f00000, v176
	v_max_f32_e32 v35, 0xc1f00000, v35
	v_mul_f32_e32 v176, 0xbfb8aa3b, v176
	v_mul_f32_e32 v35, 0xbfb8aa3b, v35
	v_max_f32_e32 v161, 0xc1f00000, v161
	v_cvt_f32_f16_e32 v177, v183
	v_exp_f32_e32 v180, v176
	v_cvt_f32_f16_sdwa v176, v183 dst_sel:DWORD dst_unused:UNUSED_PAD src0_sel:WORD_1
	v_exp_f32_e32 v35, v35
	v_mul_f32_e32 v161, 0xbfb8aa3b, v161
	v_max_f32_e32 v163, 0xc1f00000, v163
	v_max_f32_e32 v32, 0xc1f00000, v32
	v_exp_f32_e32 v161, v161
	v_mul_f32_e32 v163, 0xbfb8aa3b, v163
	v_max_f32_e32 v165, 0xc1f00000, v165
	v_mul_f32_e32 v32, 0xbfb8aa3b, v32
	v_exp_f32_e32 v163, v163
	v_mul_f32_e32 v165, 0xbfb8aa3b, v165
	v_exp_f32_e32 v32, v32
	v_exp_f32_e32 v165, v165
	v_max_f32_e32 v177, 0xc1f00000, v177
	v_max_f32_e32 v176, 0xc1f00000, v176
	v_mul_f32_e32 v177, 0xbfb8aa3b, v177
	v_mul_f32_e32 v176, 0xbfb8aa3b, v176
	v_add_f32_e32 v35, 1.0, v35
	v_exp_f32_e32 v181, v177
	v_exp_f32_e32 v182, v176
	v_rcp_f32_e32 v176, v35
	v_add_f32_e32 v35, 1.0, v161
	v_rcp_f32_e32 v177, v35
	v_add_f32_e32 v35, 1.0, v163
	v_add_f32_e32 v32, 1.0, v32
	v_rcp_f32_e32 v178, v35
	v_add_f32_e32 v35, 1.0, v165
	v_rcp_f32_e32 v32, v32
	v_rcp_f32_e32 v179, v35
	v_add_f32_e32 v35, 1.0, v180
	v_rcp_f32_e32 v180, v35
	v_add_f32_e32 v35, 1.0, v181
	v_rcp_f32_e32 v181, v35
	v_add_f32_e32 v35, 1.0, v182
	v_mov_b32_e32 v182, v29
	v_mov_b32_e32 v183, v30
	v_pk_mul_f32 v[176:177], v[182:183], v[176:177]
	v_pk_mov_b32 v[182:183], v[30:31], v[24:25] op_sel:[1,0]
	v_fma_mixlo_f16 v32, v28, v32, 0
	v_cvt_pk_f16_f32 v161, v176, v177
	v_pk_mul_f32 v[178:179], v[182:183], v[178:179]
	v_rcp_f32_e32 v35, v35
	v_pack_b32_f16 v176, v32, v161
	v_cvt_pk_f16_f32 v32, v178, v179
	v_mov_b32_e32 v178, v25
	v_mov_b32_e32 v179, v26
	v_pk_mul_f32 v[178:179], v[178:179], v[180:181]
	v_alignbit_b32 v177, v32, v161, 16
	v_cvt_pk_f16_f32 v161, v178, v179
	v_lshrrev_b32_e32 v179, 16, v161
	v_alignbit_b32 v178, v161, v32, 16
	v_fma_mixhi_f16 v179, v27, v35, 0
	v_cvt_f32_f16_e32 v32, v152
	v_cvt_f32_f16_sdwa v35, v152 dst_sel:DWORD dst_unused:UNUSED_PAD src0_sel:WORD_1
	v_cvt_f32_f16_e32 v152, v153
	v_cvt_f32_f16_sdwa v153, v153 dst_sel:DWORD dst_unused:UNUSED_PAD src0_sel:WORD_1
	global_store_dwordx4 v[168:169], v[176:179], off offset:256
	v_max_f32_e32 v35, 0xc1f00000, v35
	v_max_f32_e32 v152, 0xc1f00000, v152
	v_mul_f32_e32 v152, 0xbfb8aa3b, v152
	v_exp_f32_e32 v161, v152
	v_max_f32_e32 v152, 0xc1f00000, v153
	v_mul_f32_e32 v152, 0xbfb8aa3b, v152
	v_cvt_f32_f16_e32 v153, v154
	v_exp_f32_e32 v163, v152
	v_cvt_f32_f16_sdwa v152, v154 dst_sel:DWORD dst_unused:UNUSED_PAD src0_sel:WORD_1
	v_lshlrev_b64 v[168:169], 11, v[174:175]
	v_max_f32_e32 v153, 0xc1f00000, v153
	v_mul_f32_e32 v153, 0xbfb8aa3b, v153
	v_max_f32_e32 v152, 0xc1f00000, v152
	v_mul_f32_e32 v152, 0xbfb8aa3b, v152
	v_mul_f32_e32 v35, 0xbfb8aa3b, v35
	v_exp_f32_e32 v165, v153
	v_cvt_f32_f16_e32 v153, v155
	v_exp_f32_e32 v174, v152
	v_cvt_f32_f16_sdwa v152, v155 dst_sel:DWORD dst_unused:UNUSED_PAD src0_sel:WORD_1
	v_exp_f32_e32 v35, v35
	v_max_f32_e32 v32, 0xc1f00000, v32
	v_mul_f32_e32 v32, 0xbfb8aa3b, v32
	v_exp_f32_e32 v32, v32
	v_max_f32_e32 v153, 0xc1f00000, v153
	v_max_f32_e32 v152, 0xc1f00000, v152
	v_mul_f32_e32 v153, 0xbfb8aa3b, v153
	v_mul_f32_e32 v152, 0xbfb8aa3b, v152
	v_add_f32_e32 v35, 1.0, v35
	v_exp_f32_e32 v175, v153
	v_exp_f32_e32 v176, v152
	v_rcp_f32_e32 v152, v35
	v_add_f32_e32 v35, 1.0, v161
	v_rcp_f32_e32 v153, v35
	v_add_f32_e32 v35, 1.0, v163
	v_add_f32_e32 v32, 1.0, v32
	v_rcp_f32_e32 v154, v35
	v_add_f32_e32 v35, 1.0, v165
	v_rcp_f32_e32 v32, v32
	v_rcp_f32_e32 v155, v35
	v_add_f32_e32 v35, 1.0, v174
	v_rcp_f32_e32 v174, v35
	v_add_f32_e32 v35, 1.0, v175
	v_rcp_f32_e32 v175, v35
	v_add_f32_e32 v35, 1.0, v176
	v_mov_b32_e32 v176, v57
	v_mov_b32_e32 v177, v58
	v_pk_mul_f32 v[152:153], v[176:177], v[152:153]
	v_pk_mov_b32 v[176:177], v[58:59], v[52:53] op_sel:[1,0]
	v_fma_mixlo_f16 v32, v56, v32, 0
	v_cvt_pk_f16_f32 v153, v152, v153
	v_pk_mul_f32 v[154:155], v[176:177], v[154:155]
	v_rcp_f32_e32 v35, v35
	v_pack_b32_f16 v152, v32, v153
	v_cvt_pk_f16_f32 v32, v154, v155
	v_mov_b32_e32 v154, v53
	v_mov_b32_e32 v155, v54
	v_pk_mul_f32 v[154:155], v[154:155], v[174:175]
	v_alignbit_b32 v153, v32, v153, 16
	v_cvt_pk_f16_f32 v155, v154, v155
	v_alignbit_b32 v154, v155, v32, 16
	v_lshrrev_b32_e32 v155, 16, v155
	v_fma_mixhi_f16 v155, v55, v35, 0
	v_cvt_f32_f16_e32 v32, v148
	v_cvt_f32_f16_sdwa v35, v148 dst_sel:DWORD dst_unused:UNUSED_PAD src0_sel:WORD_1
	v_cvt_f32_f16_e32 v148, v149
	v_cvt_f32_f16_sdwa v149, v149 dst_sel:DWORD dst_unused:UNUSED_PAD src0_sel:WORD_1
	v_lshl_add_u64 v[168:169], s[14:15], 0, v[168:169]
	v_lshl_add_u64 v[168:169], v[168:169], 0, v[166:167]
	v_max_f32_e32 v148, 0xc1f00000, v148
	v_mul_f32_e32 v148, 0xbfb8aa3b, v148
	global_store_dwordx4 v[168:169], v[152:155], off
	v_max_f32_e32 v35, 0xc1f00000, v35
	v_mul_f32_e32 v35, 0xbfb8aa3b, v35
	v_exp_f32_e32 v152, v148
	v_max_f32_e32 v148, 0xc1f00000, v149
	v_mul_f32_e32 v148, 0xbfb8aa3b, v148
	v_cvt_f32_f16_e32 v149, v150
	v_exp_f32_e32 v153, v148
	v_cvt_f32_f16_sdwa v148, v150 dst_sel:DWORD dst_unused:UNUSED_PAD src0_sel:WORD_1
	v_exp_f32_e32 v35, v35
	v_max_f32_e32 v149, 0xc1f00000, v149
	v_mul_f32_e32 v149, 0xbfb8aa3b, v149
	v_max_f32_e32 v148, 0xc1f00000, v148
	v_mul_f32_e32 v148, 0xbfb8aa3b, v148
	v_exp_f32_e32 v154, v149
	v_cvt_f32_f16_e32 v149, v151
	v_exp_f32_e32 v155, v148
	v_cvt_f32_f16_sdwa v148, v151 dst_sel:DWORD dst_unused:UNUSED_PAD src0_sel:WORD_1
	v_max_f32_e32 v32, 0xc1f00000, v32
	v_mul_f32_e32 v32, 0xbfb8aa3b, v32
	v_exp_f32_e32 v32, v32
	v_max_f32_e32 v149, 0xc1f00000, v149
	v_max_f32_e32 v148, 0xc1f00000, v148
	v_mul_f32_e32 v149, 0xbfb8aa3b, v149
	v_mul_f32_e32 v148, 0xbfb8aa3b, v148
	v_add_f32_e32 v35, 1.0, v35
	v_exp_f32_e32 v161, v149
	v_exp_f32_e32 v163, v148
	v_rcp_f32_e32 v148, v35
	v_add_f32_e32 v35, 1.0, v152
	v_rcp_f32_e32 v149, v35
	v_add_f32_e32 v35, 1.0, v153
	v_add_f32_e32 v32, 1.0, v32
	v_rcp_f32_e32 v150, v35
	v_add_f32_e32 v35, 1.0, v154
	v_rcp_f32_e32 v32, v32
	v_rcp_f32_e32 v151, v35
	v_add_f32_e32 v35, 1.0, v155
	v_rcp_f32_e32 v152, v35
	v_add_f32_e32 v35, 1.0, v161
	v_rcp_f32_e32 v153, v35
	v_mov_b32_e32 v154, v21
	v_mov_b32_e32 v155, v22
	v_pk_mul_f32 v[148:149], v[154:155], v[148:149]
	v_pk_mov_b32 v[154:155], v[22:23], v[16:17] op_sel:[1,0]
	v_add_f32_e32 v35, 1.0, v163
	v_fma_mixlo_f16 v32, v20, v32, 0
	v_cvt_pk_f16_f32 v149, v148, v149
	v_pk_mul_f32 v[150:151], v[154:155], v[150:151]
	v_rcp_f32_e32 v35, v35
	v_pack_b32_f16 v148, v32, v149
	v_cvt_pk_f16_f32 v32, v150, v151
	v_mov_b32_e32 v150, v17
	v_mov_b32_e32 v151, v18
	v_pk_mul_f32 v[150:151], v[150:151], v[152:153]
	v_alignbit_b32 v149, v32, v149, 16
	v_cvt_pk_f16_f32 v151, v150, v151
	v_alignbit_b32 v150, v151, v32, 16
	v_lshrrev_b32_e32 v151, 16, v151
	v_fma_mixhi_f16 v151, v19, v35, 0
	v_cvt_f32_f16_e32 v32, v144
	v_cvt_f32_f16_sdwa v35, v144 dst_sel:DWORD dst_unused:UNUSED_PAD src0_sel:WORD_1
	v_cvt_f32_f16_e32 v144, v145
	v_cvt_f32_f16_sdwa v145, v145 dst_sel:DWORD dst_unused:UNUSED_PAD src0_sel:WORD_1
	global_store_dwordx4 v[168:169], v[148:151], off offset:256
	v_max_f32_e32 v35, 0xc1f00000, v35
	v_max_f32_e32 v144, 0xc1f00000, v144
	v_mul_f32_e32 v144, 0xbfb8aa3b, v144
	v_exp_f32_e32 v150, v144
	v_max_f32_e32 v144, 0xc1f00000, v145
	v_mul_f32_e32 v144, 0xbfb8aa3b, v144
	v_cvt_f32_f16_e32 v145, v146
	v_exp_f32_e32 v151, v144
	v_cvt_f32_f16_sdwa v144, v146 dst_sel:DWORD dst_unused:UNUSED_PAD src0_sel:WORD_1
	v_mul_f32_e32 v35, 0xbfb8aa3b, v35
	v_max_f32_e32 v145, 0xc1f00000, v145
	v_mul_f32_e32 v145, 0xbfb8aa3b, v145
	v_max_f32_e32 v144, 0xc1f00000, v144
	v_mul_f32_e32 v144, 0xbfb8aa3b, v144
	v_exp_f32_e32 v152, v145
	v_cvt_f32_f16_e32 v145, v147
	v_exp_f32_e32 v153, v144
	v_cvt_f32_f16_sdwa v144, v147 dst_sel:DWORD dst_unused:UNUSED_PAD src0_sel:WORD_1
	v_exp_f32_e32 v35, v35
	v_max_f32_e32 v32, 0xc1f00000, v32
	v_mul_f32_e32 v32, 0xbfb8aa3b, v32
	v_exp_f32_e32 v32, v32
	v_max_f32_e32 v145, 0xc1f00000, v145
	v_max_f32_e32 v144, 0xc1f00000, v144
	v_mul_f32_e32 v145, 0xbfb8aa3b, v145
	v_mul_f32_e32 v144, 0xbfb8aa3b, v144
	v_add_f32_e32 v35, 1.0, v35
	v_exp_f32_e32 v154, v145
	v_exp_f32_e32 v155, v144
	v_rcp_f32_e32 v144, v35
	v_add_f32_e32 v35, 1.0, v150
	v_rcp_f32_e32 v145, v35
	v_add_f32_e32 v35, 1.0, v151
	v_add_f32_e32 v32, 1.0, v32
	v_rcp_f32_e32 v146, v35
	v_add_f32_e32 v35, 1.0, v152
	v_rcp_f32_e32 v32, v32
	v_rcp_f32_e32 v147, v35
	v_add_f32_e32 v35, 1.0, v153
	v_rcp_f32_e32 v150, v35
	v_add_f32_e32 v35, 1.0, v154
	v_rcp_f32_e32 v151, v35
	v_mov_b32_e32 v152, v49
	v_mov_b32_e32 v153, v50
	v_pk_mul_f32 v[144:145], v[152:153], v[144:145]
	v_pk_mov_b32 v[152:153], v[50:51], v[44:45] op_sel:[1,0]
	v_add_f32_e32 v35, 1.0, v155
	v_fma_mixlo_f16 v32, v48, v32, 0
	v_cvt_pk_f16_f32 v145, v144, v145
	v_pk_mul_f32 v[146:147], v[152:153], v[146:147]
	v_rcp_f32_e32 v35, v35
	v_pack_b32_f16 v144, v32, v145
	v_cvt_pk_f16_f32 v32, v146, v147
	v_mov_b32_e32 v146, v45
	v_mov_b32_e32 v147, v46
	v_pk_mul_f32 v[146:147], v[146:147], v[150:151]
	v_alignbit_b32 v145, v32, v145, 16
	v_cvt_pk_f16_f32 v147, v146, v147
	v_alignbit_b32 v146, v147, v32, 16
	v_lshrrev_b32_e32 v147, 16, v147
	v_fma_mixhi_f16 v147, v47, v35, 0
	v_cvt_f32_f16_e32 v32, v140
	v_cvt_f32_f16_sdwa v35, v140 dst_sel:DWORD dst_unused:UNUSED_PAD src0_sel:WORD_1
	v_cvt_f32_f16_e32 v140, v141
	v_cvt_f32_f16_sdwa v141, v141 dst_sel:DWORD dst_unused:UNUSED_PAD src0_sel:WORD_1
	v_lshlrev_b64 v[148:149], 11, v[172:173]
	v_lshl_add_u64 v[148:149], s[14:15], 0, v[148:149]
	v_max_f32_e32 v140, 0xc1f00000, v140
	v_lshl_add_u64 v[148:149], v[148:149], 0, v[166:167]
	v_mul_f32_e32 v140, 0xbfb8aa3b, v140
	global_store_dwordx4 v[148:149], v[144:147], off
	v_max_f32_e32 v35, 0xc1f00000, v35
	v_mul_f32_e32 v35, 0xbfb8aa3b, v35
	v_exp_f32_e32 v144, v140
	v_max_f32_e32 v140, 0xc1f00000, v141
	v_mul_f32_e32 v140, 0xbfb8aa3b, v140
	v_cvt_f32_f16_e32 v141, v142
	v_exp_f32_e32 v145, v140
	v_cvt_f32_f16_sdwa v140, v142 dst_sel:DWORD dst_unused:UNUSED_PAD src0_sel:WORD_1
	v_exp_f32_e32 v35, v35
	v_max_f32_e32 v141, 0xc1f00000, v141
	v_mul_f32_e32 v141, 0xbfb8aa3b, v141
	v_max_f32_e32 v140, 0xc1f00000, v140
	v_mul_f32_e32 v140, 0xbfb8aa3b, v140
	v_exp_f32_e32 v146, v141
	v_cvt_f32_f16_e32 v141, v143
	v_exp_f32_e32 v147, v140
	v_cvt_f32_f16_sdwa v140, v143 dst_sel:DWORD dst_unused:UNUSED_PAD src0_sel:WORD_1
	v_max_f32_e32 v32, 0xc1f00000, v32
	v_mul_f32_e32 v32, 0xbfb8aa3b, v32
	v_exp_f32_e32 v32, v32
	v_max_f32_e32 v141, 0xc1f00000, v141
	v_max_f32_e32 v140, 0xc1f00000, v140
	v_mul_f32_e32 v141, 0xbfb8aa3b, v141
	v_mul_f32_e32 v140, 0xbfb8aa3b, v140
	v_add_f32_e32 v35, 1.0, v35
	v_exp_f32_e32 v150, v141
	v_exp_f32_e32 v151, v140
	v_rcp_f32_e32 v140, v35
	v_add_f32_e32 v35, 1.0, v144
	v_rcp_f32_e32 v141, v35
	v_add_f32_e32 v35, 1.0, v145
	v_add_f32_e32 v32, 1.0, v32
	v_rcp_f32_e32 v142, v35
	v_add_f32_e32 v35, 1.0, v146
	v_rcp_f32_e32 v32, v32
	v_rcp_f32_e32 v143, v35
	v_add_f32_e32 v35, 1.0, v147
	v_rcp_f32_e32 v144, v35
	v_add_f32_e32 v35, 1.0, v150
	v_rcp_f32_e32 v145, v35
	v_mov_b32_e32 v146, v13
	v_mov_b32_e32 v147, v14
	v_pk_mul_f32 v[140:141], v[146:147], v[140:141]
	v_pk_mov_b32 v[146:147], v[14:15], v[8:9] op_sel:[1,0]
	v_add_f32_e32 v35, 1.0, v151
	v_fma_mixlo_f16 v32, v12, v32, 0
	v_cvt_pk_f16_f32 v141, v140, v141
	v_pk_mul_f32 v[142:143], v[146:147], v[142:143]
	v_rcp_f32_e32 v35, v35
	v_pack_b32_f16 v140, v32, v141
	v_cvt_pk_f16_f32 v32, v142, v143
	v_mov_b32_e32 v142, v9
	v_mov_b32_e32 v143, v10
	v_pk_mul_f32 v[142:143], v[142:143], v[144:145]
	v_alignbit_b32 v141, v32, v141, 16
	v_cvt_pk_f16_f32 v143, v142, v143
	v_alignbit_b32 v142, v143, v32, 16
	v_lshrrev_b32_e32 v143, 16, v143
	v_fma_mixhi_f16 v143, v11, v35, 0
	v_cvt_f32_f16_e32 v32, v136
	v_cvt_f32_f16_sdwa v35, v136 dst_sel:DWORD dst_unused:UNUSED_PAD src0_sel:WORD_1
	v_cvt_f32_f16_e32 v136, v137
	v_cvt_f32_f16_sdwa v137, v137 dst_sel:DWORD dst_unused:UNUSED_PAD src0_sel:WORD_1
	global_store_dwordx4 v[148:149], v[140:143], off offset:256
	v_max_f32_e32 v35, 0xc1f00000, v35
	v_max_f32_e32 v136, 0xc1f00000, v136
	v_mul_f32_e32 v136, 0xbfb8aa3b, v136
	v_exp_f32_e32 v142, v136
	v_max_f32_e32 v136, 0xc1f00000, v137
	v_mul_f32_e32 v136, 0xbfb8aa3b, v136
	v_cvt_f32_f16_e32 v137, v138
	v_exp_f32_e32 v143, v136
	v_cvt_f32_f16_sdwa v136, v138 dst_sel:DWORD dst_unused:UNUSED_PAD src0_sel:WORD_1
	v_mul_f32_e32 v35, 0xbfb8aa3b, v35
	v_max_f32_e32 v137, 0xc1f00000, v137
	v_mul_f32_e32 v137, 0xbfb8aa3b, v137
	v_max_f32_e32 v136, 0xc1f00000, v136
	v_mul_f32_e32 v136, 0xbfb8aa3b, v136
	v_exp_f32_e32 v144, v137
	v_cvt_f32_f16_e32 v137, v139
	v_exp_f32_e32 v145, v136
	v_cvt_f32_f16_sdwa v136, v139 dst_sel:DWORD dst_unused:UNUSED_PAD src0_sel:WORD_1
	v_exp_f32_e32 v35, v35
	v_max_f32_e32 v32, 0xc1f00000, v32
	v_mul_f32_e32 v32, 0xbfb8aa3b, v32
	v_exp_f32_e32 v32, v32
	v_max_f32_e32 v137, 0xc1f00000, v137
	v_max_f32_e32 v136, 0xc1f00000, v136
	v_mul_f32_e32 v137, 0xbfb8aa3b, v137
	v_mul_f32_e32 v136, 0xbfb8aa3b, v136
	v_add_f32_e32 v35, 1.0, v35
	v_exp_f32_e32 v146, v137
	v_exp_f32_e32 v147, v136
	v_rcp_f32_e32 v136, v35
	v_add_f32_e32 v35, 1.0, v142
	v_rcp_f32_e32 v137, v35
	v_add_f32_e32 v35, 1.0, v143
	v_add_f32_e32 v32, 1.0, v32
	v_rcp_f32_e32 v138, v35
	v_add_f32_e32 v35, 1.0, v144
	v_rcp_f32_e32 v32, v32
	v_rcp_f32_e32 v139, v35
	v_add_f32_e32 v35, 1.0, v145
	v_rcp_f32_e32 v142, v35
	v_add_f32_e32 v35, 1.0, v146
	v_rcp_f32_e32 v143, v35
	v_mov_b32_e32 v144, v41
	v_mov_b32_e32 v145, v42
	v_pk_mul_f32 v[136:137], v[144:145], v[136:137]
	v_pk_mov_b32 v[144:145], v[42:43], v[36:37] op_sel:[1,0]
	v_add_f32_e32 v35, 1.0, v147
	v_fma_mixlo_f16 v32, v40, v32, 0
	v_cvt_pk_f16_f32 v137, v136, v137
	v_pk_mul_f32 v[138:139], v[144:145], v[138:139]
	v_rcp_f32_e32 v35, v35
	v_pack_b32_f16 v136, v32, v137
	v_cvt_pk_f16_f32 v32, v138, v139
	v_mov_b32_e32 v138, v37
	v_mov_b32_e32 v139, v38
	v_pk_mul_f32 v[138:139], v[138:139], v[142:143]
	v_alignbit_b32 v137, v32, v137, 16
	v_cvt_pk_f16_f32 v139, v138, v139
	v_alignbit_b32 v138, v139, v32, 16
	v_lshrrev_b32_e32 v139, 16, v139
	v_fma_mixhi_f16 v139, v39, v35, 0
	v_cvt_f32_f16_e32 v32, v132
	v_cvt_f32_f16_sdwa v35, v132 dst_sel:DWORD dst_unused:UNUSED_PAD src0_sel:WORD_1
	v_cvt_f32_f16_e32 v132, v133
	v_cvt_f32_f16_sdwa v133, v133 dst_sel:DWORD dst_unused:UNUSED_PAD src0_sel:WORD_1
	v_lshlrev_b64 v[140:141], 11, v[170:171]
	v_lshl_add_u64 v[140:141], s[14:15], 0, v[140:141]
	v_max_f32_e32 v132, 0xc1f00000, v132
	v_lshl_add_u64 v[140:141], v[140:141], 0, v[166:167]
	v_mul_f32_e32 v132, 0xbfb8aa3b, v132
	global_store_dwordx4 v[140:141], v[136:139], off
	v_max_f32_e32 v35, 0xc1f00000, v35
	v_mul_f32_e32 v35, 0xbfb8aa3b, v35
	v_exp_f32_e32 v136, v132
	v_max_f32_e32 v132, 0xc1f00000, v133
	v_mul_f32_e32 v132, 0xbfb8aa3b, v132
	v_cvt_f32_f16_e32 v133, v134
	v_exp_f32_e32 v137, v132
	v_cvt_f32_f16_sdwa v132, v134 dst_sel:DWORD dst_unused:UNUSED_PAD src0_sel:WORD_1
	v_exp_f32_e32 v35, v35
	v_max_f32_e32 v133, 0xc1f00000, v133
	v_mul_f32_e32 v133, 0xbfb8aa3b, v133
	v_max_f32_e32 v132, 0xc1f00000, v132
	v_mul_f32_e32 v132, 0xbfb8aa3b, v132
	v_exp_f32_e32 v138, v133
	v_cvt_f32_f16_e32 v133, v135
	v_exp_f32_e32 v139, v132
	v_cvt_f32_f16_sdwa v132, v135 dst_sel:DWORD dst_unused:UNUSED_PAD src0_sel:WORD_1
	v_max_f32_e32 v32, 0xc1f00000, v32
	v_mul_f32_e32 v32, 0xbfb8aa3b, v32
	v_exp_f32_e32 v32, v32
	v_max_f32_e32 v133, 0xc1f00000, v133
	v_max_f32_e32 v132, 0xc1f00000, v132
	v_mul_f32_e32 v133, 0xbfb8aa3b, v133
	v_mul_f32_e32 v132, 0xbfb8aa3b, v132
	v_add_f32_e32 v35, 1.0, v35
	v_exp_f32_e32 v142, v133
	v_exp_f32_e32 v143, v132
	v_rcp_f32_e32 v132, v35
	v_add_f32_e32 v35, 1.0, v136
	v_rcp_f32_e32 v133, v35
	v_add_f32_e32 v35, 1.0, v137
	v_add_f32_e32 v32, 1.0, v32
	v_rcp_f32_e32 v134, v35
	v_add_f32_e32 v35, 1.0, v138
	v_rcp_f32_e32 v32, v32
	v_rcp_f32_e32 v135, v35
	v_add_f32_e32 v35, 1.0, v139
	v_rcp_f32_e32 v136, v35
	v_add_f32_e32 v35, 1.0, v142
	v_rcp_f32_e32 v137, v35
	v_mov_b32_e32 v138, v5
	v_mov_b32_e32 v139, v6
	v_pk_mul_f32 v[132:133], v[138:139], v[132:133]
	v_pk_mov_b32 v[138:139], v[6:7], v[0:1] op_sel:[1,0]
	v_add_f32_e32 v35, 1.0, v143
	v_fma_mixlo_f16 v32, v4, v32, 0
	v_cvt_pk_f16_f32 v133, v132, v133
	v_pk_mul_f32 v[134:135], v[138:139], v[134:135]
	v_rcp_f32_e32 v35, v35
	v_pack_b32_f16 v132, v32, v133
	v_cvt_pk_f16_f32 v32, v134, v135
	v_mov_b32_e32 v134, v1
	v_mov_b32_e32 v135, v2
	v_pk_mul_f32 v[134:135], v[134:135], v[136:137]
	v_alignbit_b32 v133, v32, v133, 16
	v_cvt_pk_f16_f32 v135, v134, v135
	v_alignbit_b32 v134, v135, v32, 16
	v_lshrrev_b32_e32 v135, 16, v135
	v_fma_mixhi_f16 v135, v3, v35, 0
	global_store_dwordx4 v[140:141], v[132:135], off offset:256
	s_cbranch_execnz .LBB0_944

.LBB0_958:
	s_add_u32 s12, s10, 0x100
	s_addc_u32 s13, s11, 0
	s_add_i32 s38, 0, 0x10000
	v_add_u32_e32 v142, s38, v196
	ds_read_b128 v[122:125], v142
	ds_read_b128 v[138:141], v142 offset:2048
	ds_read_b128 v[130:133], v142 offset:1024
	ds_read_b128 v[142:145], v142 offset:3072
	s_cmp_eq_u32 s37, 12
	s_cselect_b32 s17, s7, s13
	s_cselect_b32 s16, s6, s12
	s_cselect_b32 s15, s9, s36
	s_cselect_b32 s14, s8, s35
	v_lshl_add_u64 v[230:231], s[10:11], 0, v[188:189]
	s_add_i32 m0, s21, 0xc000
	ds_read_b128 v[146:149], v198
	ds_read_b128 v[192:195], v198 offset:2048
	ds_read_b128 v[204:207], v198 offset:4096
	ds_read_b128 v[212:215], v198 offset:6144
	ds_read_b128 v[150:153], v198 offset:1024
	ds_read_b128 v[200:203], v198 offset:3072
	ds_read_b128 v[208:211], v198 offset:5120
	ds_read_b128 v[216:219], v198 offset:7168
	global_load_lds_dwordx4 v[230:231], off
	v_lshl_add_u64 v[230:231], s[10:11], 0, v[190:191]
	s_add_i32 m0, s21, 0xe000
	s_nop 0
	global_load_lds_dwordx4 v[230:231], off
	s_waitcnt lgkmcnt(8)
	s_barrier
	s_waitcnt lgkmcnt(7)
	s_setprio 1
	v_mfma_f32_16x16x32_f16 v[134:137], v[122:125], v[146:149], v[134:137]
	v_mfma_f32_16x16x32_f16 v[126:129], v[138:141], v[146:149], v[126:129]
	s_waitcnt lgkmcnt(6)
	v_mfma_f32_16x16x32_f16 v[110:113], v[122:125], v[192:195], v[110:113]
	v_mfma_f32_16x16x32_f16 v[106:109], v[138:141], v[192:195], v[106:109]
	s_waitcnt lgkmcnt(5)
	v_mfma_f32_16x16x32_f16 v[94:97], v[122:125], v[204:207], v[94:97]
	v_mfma_f32_16x16x32_f16 v[90:93], v[138:141], v[204:207], v[90:93]
	s_waitcnt lgkmcnt(4)
	v_mfma_f32_16x16x32_f16 v[78:81], v[122:125], v[212:215], v[78:81]
	v_mfma_f32_16x16x32_f16 v[74:77], v[138:141], v[212:215], v[74:77]
	s_waitcnt lgkmcnt(3)
	v_mfma_f32_16x16x32_f16 v[134:137], v[130:133], v[150:153], v[134:137]
	v_mfma_f32_16x16x32_f16 v[126:129], v[142:145], v[150:153], v[126:129]
	s_waitcnt lgkmcnt(2)
	v_mfma_f32_16x16x32_f16 v[110:113], v[130:133], v[200:203], v[110:113]
	v_mfma_f32_16x16x32_f16 v[106:109], v[142:145], v[200:203], v[106:109]
	s_waitcnt lgkmcnt(1)
	v_mfma_f32_16x16x32_f16 v[94:97], v[130:133], v[208:211], v[94:97]
	v_mfma_f32_16x16x32_f16 v[90:93], v[142:145], v[208:211], v[90:93]
	s_waitcnt lgkmcnt(0)
	v_mfma_f32_16x16x32_f16 v[78:81], v[130:133], v[216:219], v[78:81]
	v_mfma_f32_16x16x32_f16 v[74:77], v[142:145], v[216:219], v[74:77]
	s_setprio 0
	s_barrier
	s_add_i32 s39, 0, 0x14000
	s_add_i32 s10, s38, s20
	v_add_u32_e32 v199, s39, v196
	v_lshl_add_u64 v[246:247], s[14:15], 0, v[32:33]
	s_mov_b32 m0, s10
	ds_read_b128 v[230:233], v199
	ds_read_b128 v[238:241], v199 offset:2048
	ds_read_b128 v[234:237], v199 offset:1024
	ds_read_b128 v[242:245], v199 offset:3072
	global_load_lds_dwordx4 v[246:247], off
	v_lshl_add_u64 v[248:249], s[14:15], 0, v[154:155]
	s_add_i32 m0, s10, 0x2000
	s_nop 0
	global_load_lds_dwordx4 v[248:249], off
	s_barrier
	s_waitcnt lgkmcnt(2)
	s_setprio 1
	v_mfma_f32_16x16x32_f16 v[118:121], v[230:233], v[146:149], v[118:121]
	v_mfma_f32_16x16x32_f16 v[114:117], v[238:241], v[146:149], v[114:117]
	v_mfma_f32_16x16x32_f16 v[102:105], v[230:233], v[192:195], v[102:105]
	v_mfma_f32_16x16x32_f16 v[98:101], v[238:241], v[192:195], v[98:101]
	v_mfma_f32_16x16x32_f16 v[86:89], v[230:233], v[204:207], v[86:89]
	v_mfma_f32_16x16x32_f16 v[82:85], v[238:241], v[204:207], v[82:85]
	v_mfma_f32_16x16x32_f16 v[70:73], v[230:233], v[212:215], v[70:73]
	v_mfma_f32_16x16x32_f16 v[66:69], v[238:241], v[212:215], v[66:69]
	s_waitcnt lgkmcnt(0)
	v_mfma_f32_16x16x32_f16 v[118:121], v[234:237], v[150:153], v[118:121]
	v_mfma_f32_16x16x32_f16 v[114:117], v[242:245], v[150:153], v[114:117]
	v_mfma_f32_16x16x32_f16 v[102:105], v[234:237], v[200:203], v[102:105]
	v_mfma_f32_16x16x32_f16 v[98:101], v[242:245], v[200:203], v[98:101]
	v_mfma_f32_16x16x32_f16 v[86:89], v[234:237], v[208:211], v[86:89]
	v_mfma_f32_16x16x32_f16 v[82:85], v[242:245], v[208:211], v[82:85]
	v_mfma_f32_16x16x32_f16 v[70:73], v[234:237], v[216:219], v[70:73]
	v_mfma_f32_16x16x32_f16 v[66:69], v[242:245], v[216:219], v[66:69]
	s_setprio 0
	s_barrier
	s_mov_b32 m0, s21
	v_lshl_add_u64 v[228:229], s[16:17], 0, v[32:33]
	ds_read_b128 v[146:149], v198 offset:16384
	ds_read_b128 v[192:195], v198 offset:18432
	ds_read_b128 v[204:207], v198 offset:20480
	ds_read_b128 v[212:215], v198 offset:22528
	ds_read_b128 v[150:153], v198 offset:17408
	ds_read_b128 v[200:203], v198 offset:19456
	ds_read_b128 v[208:211], v198 offset:21504
	ds_read_b128 v[216:219], v198 offset:23552
	global_load_lds_dwordx4 v[228:229], off
	v_lshl_add_u64 v[222:223], s[16:17], 0, v[154:155]
	s_mov_b32 m0, s22
	s_nop 0
	global_load_lds_dwordx4 v[222:223], off
	s_barrier
	s_waitcnt lgkmcnt(7)
	s_setprio 1
	v_mfma_f32_16x16x32_f16 v[62:65], v[122:125], v[146:149], v[62:65]
	v_mfma_f32_16x16x32_f16 v[58:61], v[138:141], v[146:149], v[58:61]
	s_waitcnt lgkmcnt(6)
	v_mfma_f32_16x16x32_f16 v[46:49], v[122:125], v[192:195], v[46:49]
	v_mfma_f32_16x16x32_f16 v[42:45], v[138:141], v[192:195], v[42:45]
	s_waitcnt lgkmcnt(5)
	v_mfma_f32_16x16x32_f16 v[28:31], v[122:125], v[204:207], v[28:31]
	v_mfma_f32_16x16x32_f16 v[24:27], v[138:141], v[204:207], v[24:27]
	s_waitcnt lgkmcnt(4)
	v_mfma_f32_16x16x32_f16 v[12:15], v[122:125], v[212:215], v[12:15]
	v_mfma_f32_16x16x32_f16 v[8:11], v[138:141], v[212:215], v[8:11]
	s_waitcnt lgkmcnt(3)
	v_mfma_f32_16x16x32_f16 v[62:65], v[130:133], v[150:153], v[62:65]
	v_mfma_f32_16x16x32_f16 v[58:61], v[142:145], v[150:153], v[58:61]
	s_waitcnt lgkmcnt(2)
	v_mfma_f32_16x16x32_f16 v[46:49], v[130:133], v[200:203], v[46:49]
	v_mfma_f32_16x16x32_f16 v[42:45], v[142:145], v[200:203], v[42:45]
	s_waitcnt lgkmcnt(1)
	v_mfma_f32_16x16x32_f16 v[28:31], v[130:133], v[208:211], v[28:31]
	v_mfma_f32_16x16x32_f16 v[24:27], v[142:145], v[208:211], v[24:27]
	s_waitcnt lgkmcnt(0)
	v_mfma_f32_16x16x32_f16 v[12:15], v[130:133], v[216:219], v[12:15]
	v_mfma_f32_16x16x32_f16 v[8:11], v[142:145], v[216:219], v[8:11]
	s_setprio 0
	s_barrier
	s_add_u32 s10, s14, 0x40000
	s_addc_u32 s11, s15, 0
	s_add_i32 s38, s39, s20
	v_lshl_add_u64 v[122:123], s[10:11], 0, v[32:33]
	s_mov_b32 m0, s38
	s_nop 0
	global_load_lds_dwordx4 v[122:123], off
	v_lshl_add_u64 v[122:123], s[10:11], 0, v[154:155]
	s_add_i32 m0, s38, 0x2000
	s_nop 0
	global_load_lds_dwordx4 v[122:123], off
	s_waitcnt vmcnt(6)
	s_barrier
	s_setprio 1
	v_mfma_f32_16x16x32_f16 v[54:57], v[230:233], v[146:149], v[54:57]
	v_mfma_f32_16x16x32_f16 v[50:53], v[238:241], v[146:149], v[50:53]
	v_mfma_f32_16x16x32_f16 v[38:41], v[230:233], v[192:195], v[38:41]
	v_mfma_f32_16x16x32_f16 v[34:37], v[238:241], v[192:195], v[34:37]
	v_mfma_f32_16x16x32_f16 v[20:23], v[230:233], v[204:207], v[20:23]
	v_mfma_f32_16x16x32_f16 v[16:19], v[238:241], v[204:207], v[16:19]
	v_mfma_f32_16x16x32_f16 v[4:7], v[230:233], v[212:215], v[4:7]
	v_mfma_f32_16x16x32_f16 v[0:3], v[238:241], v[212:215], v[0:3]
	v_mfma_f32_16x16x32_f16 v[54:57], v[234:237], v[150:153], v[54:57]
	v_mfma_f32_16x16x32_f16 v[50:53], v[242:245], v[150:153], v[50:53]
	v_mfma_f32_16x16x32_f16 v[38:41], v[234:237], v[200:203], v[38:41]
	v_mfma_f32_16x16x32_f16 v[34:37], v[242:245], v[200:203], v[34:37]
	v_mfma_f32_16x16x32_f16 v[20:23], v[234:237], v[208:211], v[20:23]
	v_mfma_f32_16x16x32_f16 v[16:19], v[242:245], v[208:211], v[16:19]
	v_mfma_f32_16x16x32_f16 v[4:7], v[234:237], v[216:219], v[4:7]
	v_mfma_f32_16x16x32_f16 v[0:3], v[242:245], v[216:219], v[0:3]
	s_setprio 0
	s_barrier
	s_add_i32 s38, 0, 0x18000
	v_add_u32_e32 v142, s38, v196
	ds_read_b128 v[122:125], v142
	ds_read_b128 v[138:141], v142 offset:2048
	ds_read_b128 v[130:133], v142 offset:1024
	ds_read_b128 v[142:145], v142 offset:3072
	s_add_u32 s10, s16, 0x40000
	s_addc_u32 s11, s17, 0
	s_mov_b32 m0, s23
	v_lshl_add_u64 v[230:231], s[10:11], 0, v[32:33]
	ds_read_b128 v[146:149], v198 offset:32768
	ds_read_b128 v[192:195], v198 offset:34816
	ds_read_b128 v[204:207], v198 offset:36864
	ds_read_b128 v[212:215], v198 offset:38912
	ds_read_b128 v[150:153], v198 offset:33792
	ds_read_b128 v[200:203], v198 offset:35840
	ds_read_b128 v[208:211], v198 offset:37888
	ds_read_b128 v[216:219], v198 offset:39936
	global_load_lds_dwordx4 v[230:231], off
	v_lshl_add_u64 v[230:231], s[10:11], 0, v[154:155]
	s_mov_b32 m0, s24
	s_nop 0
	global_load_lds_dwordx4 v[230:231], off
	s_waitcnt lgkmcnt(8)
	s_barrier
	s_waitcnt lgkmcnt(7)
	s_setprio 1
	v_mfma_f32_16x16x32_f16 v[134:137], v[122:125], v[146:149], v[134:137]
	v_mfma_f32_16x16x32_f16 v[126:129], v[138:141], v[146:149], v[126:129]
	s_waitcnt lgkmcnt(6)
	v_mfma_f32_16x16x32_f16 v[110:113], v[122:125], v[192:195], v[110:113]
	v_mfma_f32_16x16x32_f16 v[106:109], v[138:141], v[192:195], v[106:109]
	s_waitcnt lgkmcnt(5)
	v_mfma_f32_16x16x32_f16 v[94:97], v[122:125], v[204:207], v[94:97]
	v_mfma_f32_16x16x32_f16 v[90:93], v[138:141], v[204:207], v[90:93]
	s_waitcnt lgkmcnt(4)
	v_mfma_f32_16x16x32_f16 v[78:81], v[122:125], v[212:215], v[78:81]
	v_mfma_f32_16x16x32_f16 v[74:77], v[138:141], v[212:215], v[74:77]
	s_waitcnt lgkmcnt(3)
	v_mfma_f32_16x16x32_f16 v[134:137], v[130:133], v[150:153], v[134:137]
	v_mfma_f32_16x16x32_f16 v[126:129], v[142:145], v[150:153], v[126:129]
	s_waitcnt lgkmcnt(2)
	v_mfma_f32_16x16x32_f16 v[110:113], v[130:133], v[200:203], v[110:113]
	v_mfma_f32_16x16x32_f16 v[106:109], v[142:145], v[200:203], v[106:109]
	s_waitcnt lgkmcnt(1)
	v_mfma_f32_16x16x32_f16 v[94:97], v[130:133], v[208:211], v[94:97]
	v_mfma_f32_16x16x32_f16 v[90:93], v[142:145], v[208:211], v[90:93]
	s_waitcnt lgkmcnt(0)
	v_mfma_f32_16x16x32_f16 v[78:81], v[130:133], v[216:219], v[78:81]
	v_mfma_f32_16x16x32_f16 v[74:77], v[142:145], v[216:219], v[74:77]
	s_setprio 0
	s_barrier
	s_add_i32 s16, 0, 0x1c000
	s_add_i32 s10, s38, s20
	v_add_u32_e32 v199, s16, v196
	v_lshl_add_u64 v[246:247], v[246:247], 0, s[84:85]
	s_mov_b32 m0, s10
	ds_read_b128 v[230:233], v199
	ds_read_b128 v[238:241], v199 offset:2048
	ds_read_b128 v[234:237], v199 offset:1024
	ds_read_b128 v[242:245], v199 offset:3072
	global_load_lds_dwordx4 v[246:247], off
	v_lshl_add_u64 v[246:247], v[248:249], 0, s[84:85]
	s_add_i32 m0, s10, 0x2000
	s_nop 0
	global_load_lds_dwordx4 v[246:247], off
	s_barrier
	s_waitcnt lgkmcnt(2)
	s_setprio 1
	v_mfma_f32_16x16x32_f16 v[118:121], v[230:233], v[146:149], v[118:121]
	v_mfma_f32_16x16x32_f16 v[114:117], v[238:241], v[146:149], v[114:117]
	v_mfma_f32_16x16x32_f16 v[102:105], v[230:233], v[192:195], v[102:105]
	v_mfma_f32_16x16x32_f16 v[98:101], v[238:241], v[192:195], v[98:101]
	v_mfma_f32_16x16x32_f16 v[86:89], v[230:233], v[204:207], v[86:89]
	v_mfma_f32_16x16x32_f16 v[82:85], v[238:241], v[204:207], v[82:85]
	v_mfma_f32_16x16x32_f16 v[70:73], v[230:233], v[212:215], v[70:73]
	v_mfma_f32_16x16x32_f16 v[66:69], v[238:241], v[212:215], v[66:69]
	s_waitcnt lgkmcnt(0)
	v_mfma_f32_16x16x32_f16 v[118:121], v[234:237], v[150:153], v[118:121]
	v_mfma_f32_16x16x32_f16 v[114:117], v[242:245], v[150:153], v[114:117]
	v_mfma_f32_16x16x32_f16 v[102:105], v[234:237], v[200:203], v[102:105]
	v_mfma_f32_16x16x32_f16 v[98:101], v[242:245], v[200:203], v[98:101]
	v_mfma_f32_16x16x32_f16 v[86:89], v[234:237], v[208:211], v[86:89]
	v_mfma_f32_16x16x32_f16 v[82:85], v[242:245], v[208:211], v[82:85]
	v_mfma_f32_16x16x32_f16 v[70:73], v[234:237], v[216:219], v[70:73]
	v_mfma_f32_16x16x32_f16 v[66:69], v[242:245], v[216:219], v[66:69]
	s_setprio 0
	s_barrier
	s_mov_b32 m0, s25
	v_lshl_add_u64 v[228:229], v[228:229], 0, s[84:85]
	ds_read_b128 v[146:149], v198 offset:49152
	ds_read_b128 v[192:195], v198 offset:51200
	ds_read_b128 v[204:207], v198 offset:53248
	ds_read_b128 v[212:215], v198 offset:55296
	ds_read_b128 v[150:153], v198 offset:50176
	ds_read_b128 v[200:203], v198 offset:52224
	ds_read_b128 v[208:211], v198 offset:54272
	ds_read_b128 v[216:219], v198 offset:56320
	global_load_lds_dwordx4 v[228:229], off
	v_lshl_add_u64 v[222:223], v[222:223], 0, s[84:85]
	s_mov_b32 m0, s27
	s_nop 0
	global_load_lds_dwordx4 v[222:223], off
	s_barrier
	s_waitcnt lgkmcnt(7)
	s_setprio 1
	v_mfma_f32_16x16x32_f16 v[62:65], v[122:125], v[146:149], v[62:65]
	v_mfma_f32_16x16x32_f16 v[58:61], v[138:141], v[146:149], v[58:61]
	s_waitcnt lgkmcnt(6)
	v_mfma_f32_16x16x32_f16 v[46:49], v[122:125], v[192:195], v[46:49]
	v_mfma_f32_16x16x32_f16 v[42:45], v[138:141], v[192:195], v[42:45]
	s_waitcnt lgkmcnt(5)
	v_mfma_f32_16x16x32_f16 v[28:31], v[122:125], v[204:207], v[28:31]
	v_mfma_f32_16x16x32_f16 v[24:27], v[138:141], v[204:207], v[24:27]
	s_waitcnt lgkmcnt(4)
	v_mfma_f32_16x16x32_f16 v[12:15], v[122:125], v[212:215], v[12:15]
	v_mfma_f32_16x16x32_f16 v[8:11], v[138:141], v[212:215], v[8:11]
	s_waitcnt lgkmcnt(3)
	v_mfma_f32_16x16x32_f16 v[62:65], v[130:133], v[150:153], v[62:65]
	v_mfma_f32_16x16x32_f16 v[58:61], v[142:145], v[150:153], v[58:61]
	s_waitcnt lgkmcnt(2)
	v_mfma_f32_16x16x32_f16 v[46:49], v[130:133], v[200:203], v[46:49]
	v_mfma_f32_16x16x32_f16 v[42:45], v[142:145], v[200:203], v[42:45]
	s_waitcnt lgkmcnt(1)
	v_mfma_f32_16x16x32_f16 v[28:31], v[130:133], v[208:211], v[28:31]
	v_mfma_f32_16x16x32_f16 v[24:27], v[142:145], v[208:211], v[24:27]
	s_waitcnt lgkmcnt(0)
	v_mfma_f32_16x16x32_f16 v[12:15], v[130:133], v[216:219], v[12:15]
	v_mfma_f32_16x16x32_f16 v[8:11], v[142:145], v[216:219], v[8:11]
	s_setprio 0
	s_barrier
	s_add_u32 s10, s14, 0x40080
	s_addc_u32 s11, s15, 0
	s_add_i32 s14, s16, s20
	v_lshl_add_u64 v[122:123], s[10:11], 0, v[32:33]
	s_mov_b32 m0, s14
	s_nop 0
	global_load_lds_dwordx4 v[122:123], off
	v_lshl_add_u64 v[122:123], s[10:11], 0, v[154:155]
	s_add_i32 m0, s14, 0x2000
	s_nop 0
	global_load_lds_dwordx4 v[122:123], off
	s_waitcnt vmcnt(6)
	s_barrier
	s_setprio 1
	v_mfma_f32_16x16x32_f16 v[54:57], v[230:233], v[146:149], v[54:57]
	v_mfma_f32_16x16x32_f16 v[50:53], v[238:241], v[146:149], v[50:53]
	v_mfma_f32_16x16x32_f16 v[38:41], v[230:233], v[192:195], v[38:41]
	v_mfma_f32_16x16x32_f16 v[34:37], v[238:241], v[192:195], v[34:37]
	v_mfma_f32_16x16x32_f16 v[20:23], v[230:233], v[204:207], v[20:23]
	v_mfma_f32_16x16x32_f16 v[16:19], v[238:241], v[204:207], v[16:19]
	v_mfma_f32_16x16x32_f16 v[4:7], v[230:233], v[212:215], v[4:7]
	v_mfma_f32_16x16x32_f16 v[0:3], v[238:241], v[212:215], v[0:3]
	v_mfma_f32_16x16x32_f16 v[54:57], v[234:237], v[150:153], v[54:57]
	v_mfma_f32_16x16x32_f16 v[50:53], v[242:245], v[150:153], v[50:53]
	v_mfma_f32_16x16x32_f16 v[38:41], v[234:237], v[200:203], v[38:41]
	v_mfma_f32_16x16x32_f16 v[34:37], v[242:245], v[200:203], v[34:37]
	v_mfma_f32_16x16x32_f16 v[20:23], v[234:237], v[208:211], v[20:23]
	v_mfma_f32_16x16x32_f16 v[16:19], v[242:245], v[208:211], v[16:19]
	v_mfma_f32_16x16x32_f16 v[4:7], v[234:237], v[216:219], v[4:7]
	v_mfma_f32_16x16x32_f16 v[0:3], v[242:245], v[216:219], v[0:3]
	s_setprio 0
	s_barrier
	s_add_i32 s37, s37, 2
	s_add_u32 s35, s35, 0x100
	s_addc_u32 s36, s36, 0
	s_cmp_gt_u32 s37, 13
	s_mov_b64 s[10:11], s[12:13]
	s_cbranch_scc0 .LBB0_958
	s_cmp_eq_u32 s34, 2
	s_movk_i32 s6, 0x2800
	v_lshl_or_b32 v122, s31, 8, v197
	s_cselect_b32 s6, 0x2000, s6
	s_mov_b32 s7, 0x23a3c000
	s_cselect_b32 s8, s7, 0x23abc000
	s_add_u32 s6, s70, s6
	v_ashrrev_i32_e32 v123, 31, v122
	s_addc_u32 s7, s71, 0
	v_lshlrev_b64 v[192:193], 1, v[122:123]
	v_lshl_add_u64 v[194:195], s[6:7], 0, v[192:193]
	v_lshl_add_u64 v[122:123], v[194:195], 0, v[156:157]
	v_lshl_add_u64 v[124:125], v[194:195], 0, v[158:159]
	v_lshl_add_u64 v[130:131], v[194:195], 0, v[160:161]
	v_lshl_add_u64 v[208:209], v[194:195], 0, v[162:163]
	global_load_dwordx4 v[200:203], v[122:123], off
	global_load_dwordx4 v[204:207], v[122:123], off offset:256
	global_load_dwordx4 v[150:153], v[124:125], off
	global_load_dwordx4 v[146:149], v[124:125], off offset:256
	global_load_dwordx4 v[142:145], v[130:131], off
	global_load_dwordx4 v[138:141], v[130:131], off offset:256
	s_nop 0
	global_load_dwordx4 v[130:133], v[208:209], off
	global_load_dwordx4 v[122:125], v[208:209], off offset:256
	v_readlane_b32 s36, v252, 26
	v_readlane_b32 s42, v252, 32
	v_readlane_b32 s43, v252, 33
	s_add_u32 s6, s42, s8
	s_addc_u32 s7, s43, 0
	v_readlane_b32 s37, v252, 27
	v_readlane_b32 s38, v252, 28
	v_readlane_b32 s39, v252, 29
	v_readlane_b32 s40, v252, 30
	v_readlane_b32 s41, v252, 31
	v_lshl_add_u64 v[192:193], s[6:7], 0, v[192:193]
	s_waitcnt vmcnt(0)
	v_cvt_f32_f16_e32 v199, v200
	v_cvt_f32_f16_sdwa v200, v200 dst_sel:DWORD dst_unused:UNUSED_PAD src0_sel:WORD_1
	v_cvt_f32_f16_e32 v210, v201
	v_lshl_add_u64 v[208:209], v[192:193], 0, v[164:165]
	v_max_f32_e32 v199, 0xc1f00000, v199
	v_mul_f32_e32 v199, 0xbfb8aa3b, v199
	v_exp_f32_e32 v199, v199
	v_max_f32_e32 v200, 0xc1f00000, v200
	v_max_f32_e32 v210, 0xc1f00000, v210
	v_mul_f32_e32 v200, 0xbfb8aa3b, v200
	v_add_f32_e32 v199, 1.0, v199
	v_rcp_f32_e32 v199, v199
	v_exp_f32_e32 v200, v200
	v_mul_f32_e32 v210, 0xbfb8aa3b, v210
	v_exp_f32_e32 v211, v210
	v_fma_mixlo_f16 v199, v134, v199, 0
	v_add_f32_e32 v134, 1.0, v200
	v_rcp_f32_e32 v210, v134
	v_add_f32_e32 v134, 1.0, v211
	v_cvt_f32_f16_sdwa v200, v201 dst_sel:DWORD dst_unused:UNUSED_PAD src0_sel:WORD_1
	v_rcp_f32_e32 v211, v134
	v_mov_b32_e32 v134, v135
	v_mov_b32_e32 v135, v136
	v_cvt_f32_f16_e32 v136, v202
	v_max_f32_e32 v200, 0xc1f00000, v200
	v_mul_f32_e32 v200, 0xbfb8aa3b, v200
	v_exp_f32_e32 v200, v200
	v_max_f32_e32 v136, 0xc1f00000, v136
	v_mul_f32_e32 v136, 0xbfb8aa3b, v136
	v_exp_f32_e32 v136, v136
	v_pk_mul_f32 v[134:135], v[134:135], v[210:211]
	s_nop 0
	v_cvt_pk_f16_f32 v135, v134, v135
	v_add_f32_e32 v134, 1.0, v200
	v_rcp_f32_e32 v200, v134
	v_add_f32_e32 v134, 1.0, v136
	v_rcp_f32_e32 v201, v134
	v_pk_mov_b32 v[136:137], v[136:137], v[126:127] op_sel:[1,0]
	v_cvt_f32_f16_sdwa v126, v202 dst_sel:DWORD dst_unused:UNUSED_PAD src0_sel:WORD_1
	v_pack_b32_f16 v134, v199, v135
	v_pk_mul_f32 v[136:137], v[136:137], v[200:201]
	v_cvt_f32_f16_sdwa v200, v203 dst_sel:DWORD dst_unused:UNUSED_PAD src0_sel:WORD_1
	v_cvt_pk_f16_f32 v199, v136, v137
	v_cvt_f32_f16_e32 v136, v203
	v_max_f32_e32 v126, 0xc1f00000, v126
	v_mul_f32_e32 v126, 0xbfb8aa3b, v126
	v_exp_f32_e32 v126, v126
	v_max_f32_e32 v136, 0xc1f00000, v136
	v_mul_f32_e32 v136, 0xbfb8aa3b, v136
	v_exp_f32_e32 v137, v136
	v_add_f32_e32 v126, 1.0, v126
	v_rcp_f32_e32 v136, v126
	v_alignbit_b32 v135, v199, v135, 16
	v_add_f32_e32 v126, 1.0, v137
	v_rcp_f32_e32 v137, v126
	v_mov_b32_e32 v126, v127
	v_mov_b32_e32 v127, v128
	v_cvt_f32_f16_e32 v128, v204
	v_pk_mul_f32 v[126:127], v[126:127], v[136:137]
	s_nop 0
	v_cvt_pk_f16_f32 v126, v126, v127
	v_max_f32_e32 v127, 0xc1f00000, v200
	v_mul_f32_e32 v127, 0xbfb8aa3b, v127
	v_exp_f32_e32 v127, v127
	v_alignbit_b32 v136, v126, v199, 16
	v_lshrrev_b32_e32 v137, 16, v126
	v_add_f32_e32 v126, 1.0, v127
	v_rcp_f32_e32 v126, v126
	v_max_f32_e32 v127, 0xc1f00000, v128
	v_mul_f32_e32 v127, 0xbfb8aa3b, v127
	v_exp_f32_e32 v127, v127
	v_fma_mixhi_f16 v137, v129, v126, 0
	v_cvt_f32_f16_sdwa v126, v204 dst_sel:DWORD dst_unused:UNUSED_PAD src0_sel:WORD_1
	v_cvt_f32_f16_e32 v128, v205
	v_add_f32_e32 v127, 1.0, v127
	v_rcp_f32_e32 v127, v127
	v_max_f32_e32 v126, 0xc1f00000, v126
	v_mul_f32_e32 v126, 0xbfb8aa3b, v126
	v_max_f32_e32 v128, 0xc1f00000, v128
	v_exp_f32_e32 v126, v126
	v_mul_f32_e32 v128, 0xbfb8aa3b, v128
	v_exp_f32_e32 v128, v128
	v_fma_mixlo_f16 v129, v118, v127, 0
	v_add_f32_e32 v118, 1.0, v126
	v_rcp_f32_e32 v126, v118
	v_add_f32_e32 v118, 1.0, v128
	v_rcp_f32_e32 v127, v118
	v_cvt_f32_f16_sdwa v128, v205 dst_sel:DWORD dst_unused:UNUSED_PAD src0_sel:WORD_1
	v_mov_b32_e32 v118, v119
	v_mov_b32_e32 v119, v120
	v_cvt_f32_f16_e32 v120, v206
	v_max_f32_e32 v128, 0xc1f00000, v128
	v_mul_f32_e32 v128, 0xbfb8aa3b, v128
	v_exp_f32_e32 v128, v128
	v_max_f32_e32 v120, 0xc1f00000, v120
	v_mul_f32_e32 v120, 0xbfb8aa3b, v120
	v_exp_f32_e32 v120, v120
	v_pk_mul_f32 v[118:119], v[118:119], v[126:127]
	v_add_f32_e32 v126, 1.0, v128
	v_rcp_f32_e32 v126, v126
	v_add_f32_e32 v120, 1.0, v120
	v_rcp_f32_e32 v127, v120
	v_pk_mov_b32 v[120:121], v[120:121], v[114:115] op_sel:[1,0]
	v_cvt_f32_f16_sdwa v114, v206 dst_sel:DWORD dst_unused:UNUSED_PAD src0_sel:WORD_1
	v_cvt_pk_f16_f32 v119, v118, v119
	v_pk_mul_f32 v[120:121], v[120:121], v[126:127]
	v_cvt_f32_f16_sdwa v127, v207 dst_sel:DWORD dst_unused:UNUSED_PAD src0_sel:WORD_1
	v_cvt_pk_f16_f32 v126, v120, v121
	v_cvt_f32_f16_e32 v120, v207
	v_max_f32_e32 v114, 0xc1f00000, v114
	v_mul_f32_e32 v114, 0xbfb8aa3b, v114
	v_exp_f32_e32 v114, v114
	v_max_f32_e32 v120, 0xc1f00000, v120
	v_mul_f32_e32 v120, 0xbfb8aa3b, v120
	v_exp_f32_e32 v121, v120
	v_add_f32_e32 v114, 1.0, v114
	v_rcp_f32_e32 v120, v114
	v_pack_b32_f16 v118, v129, v119
	v_add_f32_e32 v114, 1.0, v121
	v_rcp_f32_e32 v121, v114
	v_mov_b32_e32 v114, v115
	v_max_f32_e32 v115, 0xc1f00000, v127
	v_mul_f32_e32 v115, 0xbfb8aa3b, v115
	v_exp_f32_e32 v127, v115
	v_mov_b32_e32 v115, v116
	v_pk_mul_f32 v[114:115], v[114:115], v[120:121]
	v_cvt_f32_f16_e32 v116, v150
	v_cvt_pk_f16_f32 v114, v114, v115
	v_add_f32_e32 v115, 1.0, v127
	v_rcp_f32_e32 v115, v115
	v_alignbit_b32 v120, v114, v126, 16
	v_lshrrev_b32_e32 v121, 16, v114
	v_max_f32_e32 v114, 0xc1f00000, v116
	v_alignbit_b32 v119, v126, v119, 16
	v_fma_mixhi_f16 v121, v117, v115, 0
	v_mul_f32_e32 v114, 0xbfb8aa3b, v114
	v_cvt_f32_f16_sdwa v117, v150 dst_sel:DWORD dst_unused:UNUSED_PAD src0_sel:WORD_1
	v_exp_f32_e32 v116, v114
	global_store_dwordx4 v[208:209], v[118:121], off offset:256
	v_lshl_add_u64 v[114:115], v[192:193], 0, v[166:167]
	v_max_f32_e32 v117, 0xc1f00000, v117
	v_cvt_f32_f16_e32 v118, v151
	v_add_f32_e32 v116, 1.0, v116
	v_mul_f32_e32 v117, 0xbfb8aa3b, v117
	v_rcp_f32_e32 v116, v116
	v_max_f32_e32 v118, 0xc1f00000, v118
	v_exp_f32_e32 v117, v117
	v_mul_f32_e32 v118, 0xbfb8aa3b, v118
	v_exp_f32_e32 v118, v118
	v_fma_mixlo_f16 v119, v110, v116, 0
	v_add_f32_e32 v110, 1.0, v117
	v_rcp_f32_e32 v116, v110
	v_add_f32_e32 v110, 1.0, v118
	v_rcp_f32_e32 v117, v110
	v_cvt_f32_f16_sdwa v118, v151 dst_sel:DWORD dst_unused:UNUSED_PAD src0_sel:WORD_1
	v_mov_b32_e32 v110, v111
	v_mov_b32_e32 v111, v112
	v_cvt_f32_f16_e32 v112, v152
	v_pk_mul_f32 v[110:111], v[110:111], v[116:117]
	v_max_f32_e32 v116, 0xc1f00000, v118
	v_mul_f32_e32 v116, 0xbfb8aa3b, v116
	v_max_f32_e32 v112, 0xc1f00000, v112
	v_exp_f32_e32 v116, v116
	v_mul_f32_e32 v112, 0xbfb8aa3b, v112
	v_exp_f32_e32 v112, v112
	v_cvt_pk_f16_f32 v111, v110, v111
	v_add_f32_e32 v110, 1.0, v116
	v_rcp_f32_e32 v116, v110
	v_add_f32_e32 v110, 1.0, v112
	v_rcp_f32_e32 v117, v110
	v_pk_mov_b32 v[112:113], v[112:113], v[106:107] op_sel:[1,0]
	v_cvt_f32_f16_sdwa v106, v152 dst_sel:DWORD dst_unused:UNUSED_PAD src0_sel:WORD_1
	v_pack_b32_f16 v110, v119, v111
	v_pk_mul_f32 v[112:113], v[112:113], v[116:117]
	v_cvt_f32_f16_sdwa v117, v153 dst_sel:DWORD dst_unused:UNUSED_PAD src0_sel:WORD_1
	v_cvt_pk_f16_f32 v116, v112, v113
	v_cvt_f32_f16_e32 v112, v153
	v_max_f32_e32 v106, 0xc1f00000, v106
	v_mul_f32_e32 v106, 0xbfb8aa3b, v106
	v_exp_f32_e32 v106, v106
	v_max_f32_e32 v112, 0xc1f00000, v112
	v_mul_f32_e32 v112, 0xbfb8aa3b, v112
	v_exp_f32_e32 v113, v112
	v_add_f32_e32 v106, 1.0, v106
	v_rcp_f32_e32 v112, v106
	v_alignbit_b32 v111, v116, v111, 16
	v_add_f32_e32 v106, 1.0, v113
	v_rcp_f32_e32 v113, v106
	v_mov_b32_e32 v106, v107
	v_mov_b32_e32 v107, v108
	v_cvt_f32_f16_e32 v108, v146
	v_pk_mul_f32 v[106:107], v[106:107], v[112:113]
	global_store_dwordx4 v[208:209], v[134:137], off
	v_cvt_pk_f16_f32 v106, v106, v107
	v_max_f32_e32 v107, 0xc1f00000, v117
	v_mul_f32_e32 v107, 0xbfb8aa3b, v107
	v_exp_f32_e32 v107, v107
	v_alignbit_b32 v112, v106, v116, 16
	v_lshrrev_b32_e32 v113, 16, v106
	v_add_f32_e32 v106, 1.0, v107
	v_rcp_f32_e32 v106, v106
	v_max_f32_e32 v107, 0xc1f00000, v108
	v_mul_f32_e32 v107, 0xbfb8aa3b, v107
	v_exp_f32_e32 v107, v107
	v_fma_mixhi_f16 v113, v109, v106, 0
	v_cvt_f32_f16_sdwa v106, v146 dst_sel:DWORD dst_unused:UNUSED_PAD src0_sel:WORD_1
	v_cvt_f32_f16_e32 v108, v147
	v_add_f32_e32 v107, 1.0, v107
	v_rcp_f32_e32 v107, v107
	v_max_f32_e32 v106, 0xc1f00000, v106
	v_mul_f32_e32 v106, 0xbfb8aa3b, v106
	v_max_f32_e32 v108, 0xc1f00000, v108
	v_exp_f32_e32 v106, v106
	v_mul_f32_e32 v108, 0xbfb8aa3b, v108
	v_exp_f32_e32 v108, v108
	v_fma_mixlo_f16 v109, v102, v107, 0
	v_add_f32_e32 v102, 1.0, v106
	v_rcp_f32_e32 v106, v102
	v_add_f32_e32 v102, 1.0, v108
	v_rcp_f32_e32 v107, v102
	v_cvt_f32_f16_sdwa v108, v147 dst_sel:DWORD dst_unused:UNUSED_PAD src0_sel:WORD_1
	v_mov_b32_e32 v102, v103
	v_mov_b32_e32 v103, v104
	v_cvt_f32_f16_e32 v104, v148
	v_max_f32_e32 v108, 0xc1f00000, v108
	v_mul_f32_e32 v108, 0xbfb8aa3b, v108
	v_exp_f32_e32 v108, v108
	v_max_f32_e32 v104, 0xc1f00000, v104
	v_mul_f32_e32 v104, 0xbfb8aa3b, v104
	v_exp_f32_e32 v104, v104
	v_pk_mul_f32 v[102:103], v[102:103], v[106:107]
	v_add_f32_e32 v106, 1.0, v108
	v_rcp_f32_e32 v106, v106
	v_add_f32_e32 v104, 1.0, v104
	v_rcp_f32_e32 v107, v104
	v_pk_mov_b32 v[104:105], v[104:105], v[98:99] op_sel:[1,0]
	v_cvt_f32_f16_sdwa v98, v148 dst_sel:DWORD dst_unused:UNUSED_PAD src0_sel:WORD_1
	v_cvt_pk_f16_f32 v103, v102, v103
	v_pk_mul_f32 v[104:105], v[104:105], v[106:107]
	v_cvt_f32_f16_sdwa v107, v149 dst_sel:DWORD dst_unused:UNUSED_PAD src0_sel:WORD_1
	v_cvt_pk_f16_f32 v106, v104, v105
	v_cvt_f32_f16_e32 v104, v149
	v_max_f32_e32 v98, 0xc1f00000, v98
	v_mul_f32_e32 v98, 0xbfb8aa3b, v98
	v_exp_f32_e32 v98, v98
	v_max_f32_e32 v104, 0xc1f00000, v104
	v_mul_f32_e32 v104, 0xbfb8aa3b, v104
	v_exp_f32_e32 v105, v104
	v_add_f32_e32 v98, 1.0, v98
	v_rcp_f32_e32 v104, v98
	v_pack_b32_f16 v102, v109, v103
	v_add_f32_e32 v98, 1.0, v105
	v_rcp_f32_e32 v105, v98
	v_mov_b32_e32 v98, v99
	v_max_f32_e32 v99, 0xc1f00000, v107
	v_mul_f32_e32 v99, 0xbfb8aa3b, v99
	v_exp_f32_e32 v107, v99
	v_mov_b32_e32 v99, v100
	v_pk_mul_f32 v[98:99], v[98:99], v[104:105]
	v_cvt_f32_f16_e32 v100, v142
	v_cvt_pk_f16_f32 v98, v98, v99
	v_add_f32_e32 v99, 1.0, v107
	v_rcp_f32_e32 v99, v99
	v_alignbit_b32 v104, v98, v106, 16
	v_lshrrev_b32_e32 v105, 16, v98
	v_max_f32_e32 v98, 0xc1f00000, v100
	v_alignbit_b32 v103, v106, v103, 16
	v_fma_mixhi_f16 v105, v101, v99, 0
	v_mul_f32_e32 v98, 0xbfb8aa3b, v98
	v_cvt_f32_f16_sdwa v101, v142 dst_sel:DWORD dst_unused:UNUSED_PAD src0_sel:WORD_1
	v_exp_f32_e32 v100, v98
	global_store_dwordx4 v[114:115], v[102:105], off offset:256
	v_lshl_add_u64 v[98:99], v[192:193], 0, v[168:169]
	v_max_f32_e32 v101, 0xc1f00000, v101
	v_cvt_f32_f16_e32 v102, v143
	v_add_f32_e32 v100, 1.0, v100
	v_mul_f32_e32 v101, 0xbfb8aa3b, v101
	v_rcp_f32_e32 v100, v100
	v_max_f32_e32 v102, 0xc1f00000, v102
	v_exp_f32_e32 v101, v101
	v_mul_f32_e32 v102, 0xbfb8aa3b, v102
	v_exp_f32_e32 v102, v102
	v_fma_mixlo_f16 v103, v94, v100, 0
	v_add_f32_e32 v94, 1.0, v101
	v_rcp_f32_e32 v100, v94
	v_add_f32_e32 v94, 1.0, v102
	v_rcp_f32_e32 v101, v94
	v_cvt_f32_f16_sdwa v102, v143 dst_sel:DWORD dst_unused:UNUSED_PAD src0_sel:WORD_1
	v_mov_b32_e32 v94, v95
	v_mov_b32_e32 v95, v96
	v_cvt_f32_f16_e32 v96, v144
	v_pk_mul_f32 v[94:95], v[94:95], v[100:101]
	v_max_f32_e32 v100, 0xc1f00000, v102
	v_mul_f32_e32 v100, 0xbfb8aa3b, v100
	v_max_f32_e32 v96, 0xc1f00000, v96
	v_exp_f32_e32 v100, v100
	v_mul_f32_e32 v96, 0xbfb8aa3b, v96
	v_exp_f32_e32 v96, v96
	v_cvt_pk_f16_f32 v95, v94, v95
	v_add_f32_e32 v94, 1.0, v100
	v_rcp_f32_e32 v100, v94
	v_add_f32_e32 v94, 1.0, v96
	v_rcp_f32_e32 v101, v94
	v_pk_mov_b32 v[96:97], v[96:97], v[90:91] op_sel:[1,0]
	v_cvt_f32_f16_sdwa v90, v144 dst_sel:DWORD dst_unused:UNUSED_PAD src0_sel:WORD_1
	v_pack_b32_f16 v94, v103, v95
	v_pk_mul_f32 v[96:97], v[96:97], v[100:101]
	v_cvt_f32_f16_sdwa v101, v145 dst_sel:DWORD dst_unused:UNUSED_PAD src0_sel:WORD_1
	v_cvt_pk_f16_f32 v100, v96, v97
	v_cvt_f32_f16_e32 v96, v145
	v_max_f32_e32 v90, 0xc1f00000, v90
	v_mul_f32_e32 v90, 0xbfb8aa3b, v90
	v_exp_f32_e32 v90, v90
	v_max_f32_e32 v96, 0xc1f00000, v96
	v_mul_f32_e32 v96, 0xbfb8aa3b, v96
	v_exp_f32_e32 v97, v96
	v_add_f32_e32 v90, 1.0, v90
	v_rcp_f32_e32 v96, v90
	v_alignbit_b32 v95, v100, v95, 16
	v_add_f32_e32 v90, 1.0, v97
	v_rcp_f32_e32 v97, v90
	v_mov_b32_e32 v90, v91
	v_mov_b32_e32 v91, v92
	v_cvt_f32_f16_e32 v92, v138
	v_pk_mul_f32 v[90:91], v[90:91], v[96:97]
	global_store_dwordx4 v[114:115], v[110:113], off
	v_cvt_pk_f16_f32 v90, v90, v91
	v_max_f32_e32 v91, 0xc1f00000, v101
	v_mul_f32_e32 v91, 0xbfb8aa3b, v91
	v_exp_f32_e32 v91, v91
	v_alignbit_b32 v96, v90, v100, 16
	v_lshrrev_b32_e32 v97, 16, v90
	v_add_f32_e32 v90, 1.0, v91
	v_rcp_f32_e32 v90, v90
	v_max_f32_e32 v91, 0xc1f00000, v92
	v_mul_f32_e32 v91, 0xbfb8aa3b, v91
	v_exp_f32_e32 v91, v91
	v_fma_mixhi_f16 v97, v93, v90, 0
	v_cvt_f32_f16_sdwa v90, v138 dst_sel:DWORD dst_unused:UNUSED_PAD src0_sel:WORD_1
	v_cvt_f32_f16_e32 v92, v139
	v_add_f32_e32 v91, 1.0, v91
	v_rcp_f32_e32 v91, v91
	v_max_f32_e32 v90, 0xc1f00000, v90
	v_mul_f32_e32 v90, 0xbfb8aa3b, v90
	v_max_f32_e32 v92, 0xc1f00000, v92
	v_exp_f32_e32 v90, v90
	v_mul_f32_e32 v92, 0xbfb8aa3b, v92
	v_exp_f32_e32 v92, v92
	v_fma_mixlo_f16 v93, v86, v91, 0
	v_add_f32_e32 v86, 1.0, v90
	v_rcp_f32_e32 v90, v86
	v_add_f32_e32 v86, 1.0, v92
	v_rcp_f32_e32 v91, v86
	v_cvt_f32_f16_sdwa v92, v139 dst_sel:DWORD dst_unused:UNUSED_PAD src0_sel:WORD_1
	v_mov_b32_e32 v86, v87
	v_mov_b32_e32 v87, v88
	v_cvt_f32_f16_e32 v88, v140
	v_max_f32_e32 v92, 0xc1f00000, v92
	v_mul_f32_e32 v92, 0xbfb8aa3b, v92
	v_exp_f32_e32 v92, v92
	v_max_f32_e32 v88, 0xc1f00000, v88
	v_mul_f32_e32 v88, 0xbfb8aa3b, v88
	v_exp_f32_e32 v88, v88
	v_pk_mul_f32 v[86:87], v[86:87], v[90:91]
	v_add_f32_e32 v90, 1.0, v92
	v_rcp_f32_e32 v90, v90
	v_add_f32_e32 v88, 1.0, v88
	v_rcp_f32_e32 v91, v88
	v_pk_mov_b32 v[88:89], v[88:89], v[82:83] op_sel:[1,0]
	v_cvt_f32_f16_sdwa v82, v140 dst_sel:DWORD dst_unused:UNUSED_PAD src0_sel:WORD_1
	v_cvt_pk_f16_f32 v87, v86, v87
	v_pk_mul_f32 v[88:89], v[88:89], v[90:91]
	v_cvt_f32_f16_sdwa v91, v141 dst_sel:DWORD dst_unused:UNUSED_PAD src0_sel:WORD_1
	v_cvt_pk_f16_f32 v90, v88, v89
	v_cvt_f32_f16_e32 v88, v141
	v_max_f32_e32 v82, 0xc1f00000, v82
	v_mul_f32_e32 v82, 0xbfb8aa3b, v82
	v_exp_f32_e32 v82, v82
	v_max_f32_e32 v88, 0xc1f00000, v88
	v_mul_f32_e32 v88, 0xbfb8aa3b, v88
	v_exp_f32_e32 v89, v88
	v_add_f32_e32 v82, 1.0, v82
	v_rcp_f32_e32 v88, v82
	v_pack_b32_f16 v86, v93, v87
	v_add_f32_e32 v82, 1.0, v89
	v_rcp_f32_e32 v89, v82
	v_mov_b32_e32 v82, v83
	v_max_f32_e32 v83, 0xc1f00000, v91
	v_mul_f32_e32 v83, 0xbfb8aa3b, v83
	v_exp_f32_e32 v91, v83
	v_mov_b32_e32 v83, v84
	v_pk_mul_f32 v[82:83], v[82:83], v[88:89]
	v_cvt_f32_f16_e32 v84, v130
	v_cvt_pk_f16_f32 v82, v82, v83
	v_add_f32_e32 v83, 1.0, v91
	v_rcp_f32_e32 v83, v83
	v_alignbit_b32 v88, v82, v90, 16
	v_lshrrev_b32_e32 v89, 16, v82
	v_max_f32_e32 v82, 0xc1f00000, v84
	v_alignbit_b32 v87, v90, v87, 16
	v_fma_mixhi_f16 v89, v85, v83, 0
	v_mul_f32_e32 v82, 0xbfb8aa3b, v82
	v_cvt_f32_f16_sdwa v85, v130 dst_sel:DWORD dst_unused:UNUSED_PAD src0_sel:WORD_1
	v_exp_f32_e32 v84, v82
	global_store_dwordx4 v[98:99], v[86:89], off offset:256
	v_lshl_add_u64 v[82:83], v[192:193], 0, v[170:171]
	v_max_f32_e32 v85, 0xc1f00000, v85
	v_cvt_f32_f16_e32 v86, v131
	v_add_f32_e32 v84, 1.0, v84
	v_mul_f32_e32 v85, 0xbfb8aa3b, v85
	v_rcp_f32_e32 v84, v84
	v_max_f32_e32 v86, 0xc1f00000, v86
	v_exp_f32_e32 v85, v85
	v_mul_f32_e32 v86, 0xbfb8aa3b, v86
	v_exp_f32_e32 v86, v86
	v_fma_mixlo_f16 v87, v78, v84, 0
	v_add_f32_e32 v78, 1.0, v85
	v_rcp_f32_e32 v84, v78
	v_add_f32_e32 v78, 1.0, v86
	v_rcp_f32_e32 v85, v78
	v_cvt_f32_f16_sdwa v86, v131 dst_sel:DWORD dst_unused:UNUSED_PAD src0_sel:WORD_1
	v_mov_b32_e32 v78, v79
	v_mov_b32_e32 v79, v80
	v_cvt_f32_f16_e32 v80, v132
	v_pk_mul_f32 v[78:79], v[78:79], v[84:85]
	v_max_f32_e32 v84, 0xc1f00000, v86
	v_mul_f32_e32 v84, 0xbfb8aa3b, v84
	v_max_f32_e32 v80, 0xc1f00000, v80
	v_exp_f32_e32 v84, v84
	v_mul_f32_e32 v80, 0xbfb8aa3b, v80
	v_exp_f32_e32 v80, v80
	v_cvt_pk_f16_f32 v79, v78, v79
	v_add_f32_e32 v78, 1.0, v84
	v_rcp_f32_e32 v84, v78
	v_add_f32_e32 v78, 1.0, v80
	v_rcp_f32_e32 v85, v78
	v_pk_mov_b32 v[80:81], v[80:81], v[74:75] op_sel:[1,0]
	v_cvt_f32_f16_sdwa v74, v132 dst_sel:DWORD dst_unused:UNUSED_PAD src0_sel:WORD_1
	v_pack_b32_f16 v78, v87, v79
	v_pk_mul_f32 v[80:81], v[80:81], v[84:85]
	v_cvt_f32_f16_sdwa v85, v133 dst_sel:DWORD dst_unused:UNUSED_PAD src0_sel:WORD_1
	v_cvt_pk_f16_f32 v84, v80, v81
	v_cvt_f32_f16_e32 v80, v133
	v_max_f32_e32 v74, 0xc1f00000, v74
	v_mul_f32_e32 v74, 0xbfb8aa3b, v74
	v_exp_f32_e32 v74, v74
	v_max_f32_e32 v80, 0xc1f00000, v80
	v_mul_f32_e32 v80, 0xbfb8aa3b, v80
	v_exp_f32_e32 v81, v80
	v_add_f32_e32 v74, 1.0, v74
	v_rcp_f32_e32 v80, v74
	v_alignbit_b32 v79, v84, v79, 16
	v_add_f32_e32 v74, 1.0, v81
	v_rcp_f32_e32 v81, v74
	v_mov_b32_e32 v74, v75
	v_mov_b32_e32 v75, v76
	v_cvt_f32_f16_e32 v76, v122
	v_pk_mul_f32 v[74:75], v[74:75], v[80:81]
	global_store_dwordx4 v[98:99], v[94:97], off
	v_cvt_pk_f16_f32 v74, v74, v75
	v_max_f32_e32 v75, 0xc1f00000, v85
	v_mul_f32_e32 v75, 0xbfb8aa3b, v75
	v_exp_f32_e32 v75, v75
	v_alignbit_b32 v80, v74, v84, 16
	v_lshrrev_b32_e32 v81, 16, v74
	v_add_f32_e32 v74, 1.0, v75
	v_rcp_f32_e32 v74, v74
	v_max_f32_e32 v75, 0xc1f00000, v76
	v_mul_f32_e32 v75, 0xbfb8aa3b, v75
	v_exp_f32_e32 v75, v75
	v_fma_mixhi_f16 v81, v77, v74, 0
	v_cvt_f32_f16_sdwa v74, v122 dst_sel:DWORD dst_unused:UNUSED_PAD src0_sel:WORD_1
	v_cvt_f32_f16_e32 v76, v123
	v_add_f32_e32 v75, 1.0, v75
	v_rcp_f32_e32 v75, v75
	v_max_f32_e32 v74, 0xc1f00000, v74
	v_mul_f32_e32 v74, 0xbfb8aa3b, v74
	v_max_f32_e32 v76, 0xc1f00000, v76
	v_exp_f32_e32 v74, v74
	v_mul_f32_e32 v76, 0xbfb8aa3b, v76
	v_exp_f32_e32 v76, v76
	v_fma_mixlo_f16 v77, v70, v75, 0
	v_add_f32_e32 v70, 1.0, v74
	v_rcp_f32_e32 v74, v70
	v_add_f32_e32 v70, 1.0, v76
	v_rcp_f32_e32 v75, v70
	v_cvt_f32_f16_sdwa v76, v123 dst_sel:DWORD dst_unused:UNUSED_PAD src0_sel:WORD_1
	v_mov_b32_e32 v70, v71
	v_mov_b32_e32 v71, v72
	v_cvt_f32_f16_e32 v72, v124
	v_max_f32_e32 v76, 0xc1f00000, v76
	v_mul_f32_e32 v76, 0xbfb8aa3b, v76
	v_exp_f32_e32 v76, v76
	v_max_f32_e32 v72, 0xc1f00000, v72
	v_mul_f32_e32 v72, 0xbfb8aa3b, v72
	v_exp_f32_e32 v72, v72
	v_pk_mul_f32 v[70:71], v[70:71], v[74:75]
	v_add_f32_e32 v74, 1.0, v76
	v_rcp_f32_e32 v74, v74
	v_add_f32_e32 v72, 1.0, v72
	v_rcp_f32_e32 v75, v72
	v_pk_mov_b32 v[72:73], v[72:73], v[66:67] op_sel:[1,0]
	v_cvt_f32_f16_sdwa v66, v124 dst_sel:DWORD dst_unused:UNUSED_PAD src0_sel:WORD_1
	v_cvt_pk_f16_f32 v71, v70, v71
	v_pk_mul_f32 v[72:73], v[72:73], v[74:75]
	v_cvt_f32_f16_sdwa v75, v125 dst_sel:DWORD dst_unused:UNUSED_PAD src0_sel:WORD_1
	v_cvt_pk_f16_f32 v74, v72, v73
	v_cvt_f32_f16_e32 v72, v125
	v_max_f32_e32 v66, 0xc1f00000, v66
	v_mul_f32_e32 v66, 0xbfb8aa3b, v66
	v_exp_f32_e32 v66, v66
	v_max_f32_e32 v72, 0xc1f00000, v72
	v_mul_f32_e32 v72, 0xbfb8aa3b, v72
	v_exp_f32_e32 v73, v72
	v_add_f32_e32 v66, 1.0, v66
	v_rcp_f32_e32 v72, v66
	v_pack_b32_f16 v70, v77, v71
	v_add_f32_e32 v66, 1.0, v73
	v_rcp_f32_e32 v73, v66
	v_max_f32_e32 v66, 0xc1f00000, v75
	v_mul_f32_e32 v66, 0xbfb8aa3b, v66
	v_exp_f32_e32 v75, v66
	v_mov_b32_e32 v66, v67
	v_mov_b32_e32 v67, v68
	v_pk_mul_f32 v[66:67], v[66:67], v[72:73]
	v_add_f32_e32 v68, 1.0, v75
	v_rcp_f32_e32 v68, v68
	v_cvt_pk_f16_f32 v66, v66, v67
	v_lshrrev_b32_e32 v73, 16, v66
	v_alignbit_b32 v71, v74, v71, 16
	v_alignbit_b32 v72, v66, v74, 16
	v_fma_mixhi_f16 v73, v69, v68, 0
	global_store_dwordx4 v[82:83], v[78:81], off
	global_store_dwordx4 v[82:83], v[70:73], off offset:256
	v_lshl_add_u64 v[66:67], v[194:195], 0, v[172:173]
	v_lshl_add_u64 v[68:69], v[194:195], 0, v[174:175]
	v_lshl_add_u64 v[70:71], v[194:195], 0, v[176:177]
	v_lshl_add_u64 v[98:99], v[194:195], 0, v[178:179]
	global_load_dwordx4 v[90:93], v[66:67], off
	global_load_dwordx4 v[94:97], v[66:67], off offset:256
	global_load_dwordx4 v[86:89], v[68:69], off
	global_load_dwordx4 v[82:85], v[68:69], off offset:256
	global_load_dwordx4 v[78:81], v[70:71], off
	global_load_dwordx4 v[74:77], v[70:71], off offset:256
	s_nop 0
	global_load_dwordx4 v[70:73], v[98:99], off
	global_load_dwordx4 v[66:69], v[98:99], off offset:256
	s_waitcnt vmcnt(0)
	v_cvt_f32_f16_e32 v100, v90
	v_cvt_f32_f16_sdwa v90, v90 dst_sel:DWORD dst_unused:UNUSED_PAD src0_sel:WORD_1
	v_cvt_f32_f16_e32 v101, v91
	v_lshl_add_u64 v[98:99], v[192:193], 0, v[180:181]
	v_max_f32_e32 v100, 0xc1f00000, v100
	v_mul_f32_e32 v100, 0xbfb8aa3b, v100
	v_exp_f32_e32 v100, v100
	v_max_f32_e32 v90, 0xc1f00000, v90
	v_max_f32_e32 v101, 0xc1f00000, v101
	v_mul_f32_e32 v90, 0xbfb8aa3b, v90
	v_add_f32_e32 v100, 1.0, v100
	v_rcp_f32_e32 v100, v100
	v_exp_f32_e32 v90, v90
	v_mul_f32_e32 v101, 0xbfb8aa3b, v101
	v_exp_f32_e32 v101, v101
	v_fma_mixlo_f16 v102, v62, v100, 0
	v_add_f32_e32 v62, 1.0, v90
	v_rcp_f32_e32 v100, v62
	v_add_f32_e32 v62, 1.0, v101
	v_cvt_f32_f16_sdwa v90, v91 dst_sel:DWORD dst_unused:UNUSED_PAD src0_sel:WORD_1
	v_rcp_f32_e32 v101, v62
	v_mov_b32_e32 v62, v63
	v_mov_b32_e32 v63, v64
	v_cvt_f32_f16_e32 v64, v92
	v_max_f32_e32 v90, 0xc1f00000, v90
	v_mul_f32_e32 v90, 0xbfb8aa3b, v90
	v_exp_f32_e32 v90, v90
	v_max_f32_e32 v64, 0xc1f00000, v64
	v_mul_f32_e32 v64, 0xbfb8aa3b, v64
	v_exp_f32_e32 v64, v64
	v_pk_mul_f32 v[62:63], v[62:63], v[100:101]
	s_nop 0
	v_cvt_pk_f16_f32 v63, v62, v63
	v_add_f32_e32 v62, 1.0, v90
	v_rcp_f32_e32 v90, v62
	v_add_f32_e32 v62, 1.0, v64
	v_rcp_f32_e32 v91, v62
	v_pk_mov_b32 v[64:65], v[64:65], v[58:59] op_sel:[1,0]
	v_cvt_f32_f16_sdwa v58, v92 dst_sel:DWORD dst_unused:UNUSED_PAD src0_sel:WORD_1
	v_pack_b32_f16 v62, v102, v63
	v_pk_mul_f32 v[64:65], v[64:65], v[90:91]
	v_cvt_f32_f16_sdwa v91, v93 dst_sel:DWORD dst_unused:UNUSED_PAD src0_sel:WORD_1
	v_cvt_pk_f16_f32 v90, v64, v65
	v_cvt_f32_f16_e32 v64, v93
	v_max_f32_e32 v58, 0xc1f00000, v58
	v_mul_f32_e32 v58, 0xbfb8aa3b, v58
	v_exp_f32_e32 v58, v58
	v_max_f32_e32 v64, 0xc1f00000, v64
	v_mul_f32_e32 v64, 0xbfb8aa3b, v64
	v_exp_f32_e32 v65, v64
	v_add_f32_e32 v58, 1.0, v58
	v_rcp_f32_e32 v64, v58
	v_alignbit_b32 v63, v90, v63, 16
	v_add_f32_e32 v58, 1.0, v65
	v_rcp_f32_e32 v65, v58
	v_mov_b32_e32 v58, v59
	v_mov_b32_e32 v59, v60
	v_cvt_f32_f16_e32 v60, v94
	v_pk_mul_f32 v[58:59], v[58:59], v[64:65]
	s_nop 0
	v_cvt_pk_f16_f32 v58, v58, v59
	v_max_f32_e32 v59, 0xc1f00000, v91
	v_mul_f32_e32 v59, 0xbfb8aa3b, v59
	v_exp_f32_e32 v59, v59
	v_alignbit_b32 v64, v58, v90, 16
	v_lshrrev_b32_e32 v65, 16, v58
	v_add_f32_e32 v58, 1.0, v59
	v_rcp_f32_e32 v58, v58
	v_max_f32_e32 v59, 0xc1f00000, v60
	v_mul_f32_e32 v59, 0xbfb8aa3b, v59
	v_exp_f32_e32 v59, v59
	v_fma_mixhi_f16 v65, v61, v58, 0
	v_cvt_f32_f16_sdwa v58, v94 dst_sel:DWORD dst_unused:UNUSED_PAD src0_sel:WORD_1
	v_cvt_f32_f16_e32 v60, v95
	v_add_f32_e32 v59, 1.0, v59
	v_rcp_f32_e32 v59, v59
	v_max_f32_e32 v58, 0xc1f00000, v58
	v_mul_f32_e32 v58, 0xbfb8aa3b, v58
	v_max_f32_e32 v60, 0xc1f00000, v60
	v_exp_f32_e32 v58, v58
	v_mul_f32_e32 v60, 0xbfb8aa3b, v60
	v_exp_f32_e32 v60, v60
	v_fma_mixlo_f16 v61, v54, v59, 0
	v_add_f32_e32 v54, 1.0, v58
	v_rcp_f32_e32 v58, v54
	v_add_f32_e32 v54, 1.0, v60
	v_rcp_f32_e32 v59, v54
	v_cvt_f32_f16_sdwa v60, v95 dst_sel:DWORD dst_unused:UNUSED_PAD src0_sel:WORD_1
	v_mov_b32_e32 v54, v55
	v_mov_b32_e32 v55, v56
	v_cvt_f32_f16_e32 v56, v96
	v_max_f32_e32 v60, 0xc1f00000, v60
	v_mul_f32_e32 v60, 0xbfb8aa3b, v60
	v_exp_f32_e32 v60, v60
	v_max_f32_e32 v56, 0xc1f00000, v56
	v_mul_f32_e32 v56, 0xbfb8aa3b, v56
	v_exp_f32_e32 v56, v56
	v_pk_mul_f32 v[54:55], v[54:55], v[58:59]
	v_add_f32_e32 v58, 1.0, v60
	v_rcp_f32_e32 v58, v58
	v_add_f32_e32 v56, 1.0, v56
	v_rcp_f32_e32 v59, v56
	v_pk_mov_b32 v[56:57], v[56:57], v[50:51] op_sel:[1,0]
	v_cvt_f32_f16_sdwa v50, v96 dst_sel:DWORD dst_unused:UNUSED_PAD src0_sel:WORD_1
	v_cvt_pk_f16_f32 v55, v54, v55
	v_pk_mul_f32 v[56:57], v[56:57], v[58:59]
	v_cvt_f32_f16_sdwa v59, v97 dst_sel:DWORD dst_unused:UNUSED_PAD src0_sel:WORD_1
	v_cvt_pk_f16_f32 v58, v56, v57
	v_cvt_f32_f16_e32 v56, v97
	v_max_f32_e32 v50, 0xc1f00000, v50
	v_mul_f32_e32 v50, 0xbfb8aa3b, v50
	v_exp_f32_e32 v50, v50
	v_max_f32_e32 v56, 0xc1f00000, v56
	v_mul_f32_e32 v56, 0xbfb8aa3b, v56
	v_exp_f32_e32 v57, v56
	v_add_f32_e32 v50, 1.0, v50
	v_rcp_f32_e32 v56, v50
	v_pack_b32_f16 v54, v61, v55
	v_add_f32_e32 v50, 1.0, v57
	v_rcp_f32_e32 v57, v50
	v_mov_b32_e32 v50, v51
	v_max_f32_e32 v51, 0xc1f00000, v59
	v_mul_f32_e32 v51, 0xbfb8aa3b, v51
	v_exp_f32_e32 v59, v51
	v_mov_b32_e32 v51, v52
	v_pk_mul_f32 v[50:51], v[50:51], v[56:57]
	v_cvt_f32_f16_e32 v52, v86
	v_cvt_pk_f16_f32 v50, v50, v51
	v_add_f32_e32 v51, 1.0, v59
	v_rcp_f32_e32 v51, v51
	v_alignbit_b32 v56, v50, v58, 16
	v_lshrrev_b32_e32 v57, 16, v50
	v_max_f32_e32 v50, 0xc1f00000, v52
	v_alignbit_b32 v55, v58, v55, 16
	v_fma_mixhi_f16 v57, v53, v51, 0
	v_mul_f32_e32 v50, 0xbfb8aa3b, v50
	v_cvt_f32_f16_sdwa v53, v86 dst_sel:DWORD dst_unused:UNUSED_PAD src0_sel:WORD_1
	v_exp_f32_e32 v52, v50
	global_store_dwordx4 v[98:99], v[54:57], off offset:256
	v_lshl_add_u64 v[50:51], v[192:193], 0, v[182:183]
	v_max_f32_e32 v53, 0xc1f00000, v53
	v_cvt_f32_f16_e32 v54, v87
	v_add_f32_e32 v52, 1.0, v52
	v_mul_f32_e32 v53, 0xbfb8aa3b, v53
	v_rcp_f32_e32 v52, v52
	v_max_f32_e32 v54, 0xc1f00000, v54
	v_exp_f32_e32 v53, v53
	v_mul_f32_e32 v54, 0xbfb8aa3b, v54
	v_exp_f32_e32 v54, v54
	v_fma_mixlo_f16 v55, v46, v52, 0
	v_add_f32_e32 v46, 1.0, v53
	v_rcp_f32_e32 v52, v46
	v_add_f32_e32 v46, 1.0, v54
	v_rcp_f32_e32 v53, v46
	v_cvt_f32_f16_sdwa v54, v87 dst_sel:DWORD dst_unused:UNUSED_PAD src0_sel:WORD_1
	v_mov_b32_e32 v46, v47
	v_mov_b32_e32 v47, v48
	v_cvt_f32_f16_e32 v48, v88
	v_pk_mul_f32 v[46:47], v[46:47], v[52:53]
	v_max_f32_e32 v52, 0xc1f00000, v54
	v_mul_f32_e32 v52, 0xbfb8aa3b, v52
	v_max_f32_e32 v48, 0xc1f00000, v48
	v_exp_f32_e32 v52, v52
	v_mul_f32_e32 v48, 0xbfb8aa3b, v48
	v_exp_f32_e32 v48, v48
	v_cvt_pk_f16_f32 v47, v46, v47
	v_add_f32_e32 v46, 1.0, v52
	v_rcp_f32_e32 v52, v46
	v_add_f32_e32 v46, 1.0, v48
	v_rcp_f32_e32 v53, v46
	v_pk_mov_b32 v[48:49], v[48:49], v[42:43] op_sel:[1,0]
	v_cvt_f32_f16_sdwa v42, v88 dst_sel:DWORD dst_unused:UNUSED_PAD src0_sel:WORD_1
	v_pack_b32_f16 v46, v55, v47
	v_pk_mul_f32 v[48:49], v[48:49], v[52:53]
	v_cvt_f32_f16_sdwa v53, v89 dst_sel:DWORD dst_unused:UNUSED_PAD src0_sel:WORD_1
	v_cvt_pk_f16_f32 v52, v48, v49
	v_cvt_f32_f16_e32 v48, v89
	v_max_f32_e32 v42, 0xc1f00000, v42
	v_mul_f32_e32 v42, 0xbfb8aa3b, v42
	v_exp_f32_e32 v42, v42
	v_max_f32_e32 v48, 0xc1f00000, v48
	v_mul_f32_e32 v48, 0xbfb8aa3b, v48
	v_exp_f32_e32 v49, v48
	v_add_f32_e32 v42, 1.0, v42
	v_rcp_f32_e32 v48, v42
	v_alignbit_b32 v47, v52, v47, 16
	v_add_f32_e32 v42, 1.0, v49
	v_rcp_f32_e32 v49, v42
	v_mov_b32_e32 v42, v43
	v_mov_b32_e32 v43, v44
	v_cvt_f32_f16_e32 v44, v82
	v_pk_mul_f32 v[42:43], v[42:43], v[48:49]
	global_store_dwordx4 v[98:99], v[62:65], off
	v_cvt_pk_f16_f32 v42, v42, v43
	v_max_f32_e32 v43, 0xc1f00000, v53
	v_mul_f32_e32 v43, 0xbfb8aa3b, v43
	v_exp_f32_e32 v43, v43
	v_alignbit_b32 v48, v42, v52, 16
	v_lshrrev_b32_e32 v49, 16, v42
	v_add_f32_e32 v42, 1.0, v43
	v_rcp_f32_e32 v42, v42
	v_max_f32_e32 v43, 0xc1f00000, v44
	v_mul_f32_e32 v43, 0xbfb8aa3b, v43
	v_exp_f32_e32 v43, v43
	v_fma_mixhi_f16 v49, v45, v42, 0
	v_cvt_f32_f16_sdwa v42, v82 dst_sel:DWORD dst_unused:UNUSED_PAD src0_sel:WORD_1
	v_cvt_f32_f16_e32 v44, v83
	v_add_f32_e32 v43, 1.0, v43
	v_rcp_f32_e32 v43, v43
	v_max_f32_e32 v42, 0xc1f00000, v42
	v_mul_f32_e32 v42, 0xbfb8aa3b, v42
	v_max_f32_e32 v44, 0xc1f00000, v44
	v_exp_f32_e32 v42, v42
	v_mul_f32_e32 v44, 0xbfb8aa3b, v44
	v_exp_f32_e32 v44, v44
	v_fma_mixlo_f16 v45, v38, v43, 0
	v_add_f32_e32 v38, 1.0, v42
	v_rcp_f32_e32 v42, v38
	v_add_f32_e32 v38, 1.0, v44
	v_rcp_f32_e32 v43, v38
	v_cvt_f32_f16_sdwa v44, v83 dst_sel:DWORD dst_unused:UNUSED_PAD src0_sel:WORD_1
	v_mov_b32_e32 v38, v39
	v_mov_b32_e32 v39, v40
	v_cvt_f32_f16_e32 v40, v84
	v_max_f32_e32 v44, 0xc1f00000, v44
	v_mul_f32_e32 v44, 0xbfb8aa3b, v44
	v_exp_f32_e32 v44, v44
	v_max_f32_e32 v40, 0xc1f00000, v40
	v_mul_f32_e32 v40, 0xbfb8aa3b, v40
	v_exp_f32_e32 v40, v40
	v_pk_mul_f32 v[38:39], v[38:39], v[42:43]
	v_add_f32_e32 v42, 1.0, v44
	v_rcp_f32_e32 v42, v42
	v_add_f32_e32 v40, 1.0, v40
	v_rcp_f32_e32 v43, v40
	v_pk_mov_b32 v[40:41], v[40:41], v[34:35] op_sel:[1,0]
	v_cvt_f32_f16_sdwa v34, v84 dst_sel:DWORD dst_unused:UNUSED_PAD src0_sel:WORD_1
	v_cvt_pk_f16_f32 v39, v38, v39
	v_pk_mul_f32 v[40:41], v[40:41], v[42:43]
	v_cvt_f32_f16_sdwa v43, v85 dst_sel:DWORD dst_unused:UNUSED_PAD src0_sel:WORD_1
	v_cvt_pk_f16_f32 v42, v40, v41
	v_cvt_f32_f16_e32 v40, v85
	v_max_f32_e32 v34, 0xc1f00000, v34
	v_mul_f32_e32 v34, 0xbfb8aa3b, v34
	v_exp_f32_e32 v34, v34
	v_max_f32_e32 v40, 0xc1f00000, v40
	v_mul_f32_e32 v40, 0xbfb8aa3b, v40
	v_exp_f32_e32 v41, v40
	v_add_f32_e32 v34, 1.0, v34
	v_rcp_f32_e32 v40, v34
	v_pack_b32_f16 v38, v45, v39
	v_add_f32_e32 v34, 1.0, v41
	v_rcp_f32_e32 v41, v34
	v_mov_b32_e32 v34, v35
	v_max_f32_e32 v35, 0xc1f00000, v43
	v_mul_f32_e32 v35, 0xbfb8aa3b, v35
	v_exp_f32_e32 v43, v35
	v_mov_b32_e32 v35, v36
	v_pk_mul_f32 v[34:35], v[34:35], v[40:41]
	v_cvt_f32_f16_e32 v36, v78
	v_cvt_pk_f16_f32 v34, v34, v35
	v_add_f32_e32 v35, 1.0, v43
	v_rcp_f32_e32 v35, v35
	v_alignbit_b32 v40, v34, v42, 16
	v_lshrrev_b32_e32 v41, 16, v34
	v_max_f32_e32 v34, 0xc1f00000, v36
	v_alignbit_b32 v39, v42, v39, 16
	v_fma_mixhi_f16 v41, v37, v35, 0
	v_mul_f32_e32 v34, 0xbfb8aa3b, v34
	v_cvt_f32_f16_sdwa v37, v78 dst_sel:DWORD dst_unused:UNUSED_PAD src0_sel:WORD_1
	v_exp_f32_e32 v36, v34
	global_store_dwordx4 v[50:51], v[38:41], off offset:256
	v_lshl_add_u64 v[34:35], v[192:193], 0, v[184:185]
	v_max_f32_e32 v37, 0xc1f00000, v37
	v_cvt_f32_f16_e32 v38, v79
	v_add_f32_e32 v36, 1.0, v36
	v_mul_f32_e32 v37, 0xbfb8aa3b, v37
	v_rcp_f32_e32 v36, v36
	v_max_f32_e32 v38, 0xc1f00000, v38
	v_exp_f32_e32 v37, v37
	v_mul_f32_e32 v38, 0xbfb8aa3b, v38
	v_exp_f32_e32 v38, v38
	v_fma_mixlo_f16 v39, v28, v36, 0
	v_add_f32_e32 v28, 1.0, v37
	v_rcp_f32_e32 v36, v28
	v_add_f32_e32 v28, 1.0, v38
	v_rcp_f32_e32 v37, v28
	v_cvt_f32_f16_sdwa v38, v79 dst_sel:DWORD dst_unused:UNUSED_PAD src0_sel:WORD_1
	v_mov_b32_e32 v28, v29
	v_mov_b32_e32 v29, v30
	v_cvt_f32_f16_e32 v30, v80
	v_pk_mul_f32 v[28:29], v[28:29], v[36:37]
	v_max_f32_e32 v36, 0xc1f00000, v38
	v_mul_f32_e32 v36, 0xbfb8aa3b, v36
	v_max_f32_e32 v30, 0xc1f00000, v30
	v_exp_f32_e32 v36, v36
	v_mul_f32_e32 v30, 0xbfb8aa3b, v30
	v_exp_f32_e32 v30, v30
	v_cvt_pk_f16_f32 v29, v28, v29
	v_add_f32_e32 v28, 1.0, v36
	v_rcp_f32_e32 v36, v28
	v_add_f32_e32 v28, 1.0, v30
	v_rcp_f32_e32 v37, v28
	v_pk_mov_b32 v[30:31], v[30:31], v[24:25] op_sel:[1,0]
	v_cvt_f32_f16_sdwa v24, v80 dst_sel:DWORD dst_unused:UNUSED_PAD src0_sel:WORD_1
	v_pack_b32_f16 v28, v39, v29
	v_pk_mul_f32 v[30:31], v[30:31], v[36:37]
	v_cvt_f32_f16_sdwa v37, v81 dst_sel:DWORD dst_unused:UNUSED_PAD src0_sel:WORD_1
	v_cvt_pk_f16_f32 v36, v30, v31
	v_cvt_f32_f16_e32 v30, v81
	v_max_f32_e32 v24, 0xc1f00000, v24
	v_mul_f32_e32 v24, 0xbfb8aa3b, v24
	v_exp_f32_e32 v24, v24
	v_max_f32_e32 v30, 0xc1f00000, v30
	v_mul_f32_e32 v30, 0xbfb8aa3b, v30
	v_exp_f32_e32 v31, v30
	v_add_f32_e32 v24, 1.0, v24
	v_rcp_f32_e32 v30, v24
	v_alignbit_b32 v29, v36, v29, 16
	v_add_f32_e32 v24, 1.0, v31
	v_rcp_f32_e32 v31, v24
	v_mov_b32_e32 v24, v25
	v_mov_b32_e32 v25, v26
	v_cvt_f32_f16_e32 v26, v74
	v_pk_mul_f32 v[24:25], v[24:25], v[30:31]
	global_store_dwordx4 v[50:51], v[46:49], off
	v_cvt_pk_f16_f32 v24, v24, v25
	v_max_f32_e32 v25, 0xc1f00000, v37
	v_mul_f32_e32 v25, 0xbfb8aa3b, v25
	v_exp_f32_e32 v25, v25
	v_alignbit_b32 v30, v24, v36, 16
	v_lshrrev_b32_e32 v31, 16, v24
	v_add_f32_e32 v24, 1.0, v25
	v_rcp_f32_e32 v24, v24
	v_max_f32_e32 v25, 0xc1f00000, v26
	v_mul_f32_e32 v25, 0xbfb8aa3b, v25
	v_exp_f32_e32 v25, v25
	v_fma_mixhi_f16 v31, v27, v24, 0
	v_cvt_f32_f16_sdwa v24, v74 dst_sel:DWORD dst_unused:UNUSED_PAD src0_sel:WORD_1
	v_cvt_f32_f16_e32 v26, v75
	v_add_f32_e32 v25, 1.0, v25
	v_rcp_f32_e32 v25, v25
	v_max_f32_e32 v24, 0xc1f00000, v24
	v_mul_f32_e32 v24, 0xbfb8aa3b, v24
	v_max_f32_e32 v26, 0xc1f00000, v26
	v_exp_f32_e32 v24, v24
	v_mul_f32_e32 v26, 0xbfb8aa3b, v26
	v_exp_f32_e32 v26, v26
	v_fma_mixlo_f16 v27, v20, v25, 0
	v_add_f32_e32 v20, 1.0, v24
	v_rcp_f32_e32 v24, v20
	v_add_f32_e32 v20, 1.0, v26
	v_rcp_f32_e32 v25, v20
	v_cvt_f32_f16_sdwa v26, v75 dst_sel:DWORD dst_unused:UNUSED_PAD src0_sel:WORD_1
	v_mov_b32_e32 v20, v21
	v_mov_b32_e32 v21, v22
	v_cvt_f32_f16_e32 v22, v76
	v_max_f32_e32 v26, 0xc1f00000, v26
	v_mul_f32_e32 v26, 0xbfb8aa3b, v26
	v_exp_f32_e32 v26, v26
	v_max_f32_e32 v22, 0xc1f00000, v22
	v_mul_f32_e32 v22, 0xbfb8aa3b, v22
	v_exp_f32_e32 v22, v22
	v_pk_mul_f32 v[20:21], v[20:21], v[24:25]
	v_add_f32_e32 v24, 1.0, v26
	v_rcp_f32_e32 v24, v24
	v_add_f32_e32 v22, 1.0, v22
	v_rcp_f32_e32 v25, v22
	v_pk_mov_b32 v[22:23], v[22:23], v[16:17] op_sel:[1,0]
	v_cvt_f32_f16_sdwa v16, v76 dst_sel:DWORD dst_unused:UNUSED_PAD src0_sel:WORD_1
	v_cvt_pk_f16_f32 v21, v20, v21
	v_pk_mul_f32 v[22:23], v[22:23], v[24:25]
	v_cvt_f32_f16_sdwa v25, v77 dst_sel:DWORD dst_unused:UNUSED_PAD src0_sel:WORD_1
	v_cvt_pk_f16_f32 v24, v22, v23
	v_cvt_f32_f16_e32 v22, v77
	v_max_f32_e32 v16, 0xc1f00000, v16
	v_mul_f32_e32 v16, 0xbfb8aa3b, v16
	v_exp_f32_e32 v16, v16
	v_max_f32_e32 v22, 0xc1f00000, v22
	v_mul_f32_e32 v22, 0xbfb8aa3b, v22
	v_exp_f32_e32 v23, v22
	v_add_f32_e32 v16, 1.0, v16
	v_rcp_f32_e32 v22, v16
	v_pack_b32_f16 v20, v27, v21
	v_add_f32_e32 v16, 1.0, v23
	v_rcp_f32_e32 v23, v16
	v_mov_b32_e32 v16, v17
	v_max_f32_e32 v17, 0xc1f00000, v25
	v_mul_f32_e32 v17, 0xbfb8aa3b, v17
	v_exp_f32_e32 v25, v17
	v_mov_b32_e32 v17, v18
	v_pk_mul_f32 v[16:17], v[16:17], v[22:23]
	v_cvt_f32_f16_e32 v18, v70
	v_cvt_pk_f16_f32 v16, v16, v17
	v_add_f32_e32 v17, 1.0, v25
	v_rcp_f32_e32 v17, v17
	v_alignbit_b32 v22, v16, v24, 16
	v_lshrrev_b32_e32 v23, 16, v16
	v_max_f32_e32 v16, 0xc1f00000, v18
	v_alignbit_b32 v21, v24, v21, 16
	v_fma_mixhi_f16 v23, v19, v17, 0
	v_mul_f32_e32 v16, 0xbfb8aa3b, v16
	v_cvt_f32_f16_sdwa v19, v70 dst_sel:DWORD dst_unused:UNUSED_PAD src0_sel:WORD_1
	v_exp_f32_e32 v18, v16
	global_store_dwordx4 v[34:35], v[20:23], off offset:256
	v_lshl_add_u64 v[16:17], v[192:193], 0, v[186:187]
	v_max_f32_e32 v19, 0xc1f00000, v19
	v_cvt_f32_f16_e32 v20, v71
	v_add_f32_e32 v18, 1.0, v18
	v_mul_f32_e32 v19, 0xbfb8aa3b, v19
	v_rcp_f32_e32 v18, v18
	v_max_f32_e32 v20, 0xc1f00000, v20
	v_exp_f32_e32 v19, v19
	v_mul_f32_e32 v20, 0xbfb8aa3b, v20
	v_exp_f32_e32 v20, v20
	v_fma_mixlo_f16 v21, v12, v18, 0
	v_add_f32_e32 v12, 1.0, v19
	v_rcp_f32_e32 v18, v12
	v_add_f32_e32 v12, 1.0, v20
	v_rcp_f32_e32 v19, v12
	v_cvt_f32_f16_sdwa v20, v71 dst_sel:DWORD dst_unused:UNUSED_PAD src0_sel:WORD_1
	v_mov_b32_e32 v12, v13
	v_mov_b32_e32 v13, v14
	v_cvt_f32_f16_e32 v14, v72
	v_pk_mul_f32 v[12:13], v[12:13], v[18:19]
	v_max_f32_e32 v18, 0xc1f00000, v20
	v_mul_f32_e32 v18, 0xbfb8aa3b, v18
	v_max_f32_e32 v14, 0xc1f00000, v14
	v_exp_f32_e32 v18, v18
	v_mul_f32_e32 v14, 0xbfb8aa3b, v14
	v_exp_f32_e32 v14, v14
	v_cvt_pk_f16_f32 v13, v12, v13
	v_add_f32_e32 v12, 1.0, v18
	v_rcp_f32_e32 v18, v12
	v_add_f32_e32 v12, 1.0, v14
	v_rcp_f32_e32 v19, v12
	v_pk_mov_b32 v[14:15], v[14:15], v[8:9] op_sel:[1,0]
	v_cvt_f32_f16_sdwa v8, v72 dst_sel:DWORD dst_unused:UNUSED_PAD src0_sel:WORD_1
	v_pack_b32_f16 v12, v21, v13
	v_pk_mul_f32 v[14:15], v[14:15], v[18:19]
	v_cvt_f32_f16_sdwa v19, v73 dst_sel:DWORD dst_unused:UNUSED_PAD src0_sel:WORD_1
	v_cvt_pk_f16_f32 v18, v14, v15
	v_cvt_f32_f16_e32 v14, v73
	v_max_f32_e32 v8, 0xc1f00000, v8
	v_mul_f32_e32 v8, 0xbfb8aa3b, v8
	v_exp_f32_e32 v8, v8
	v_max_f32_e32 v14, 0xc1f00000, v14
	v_mul_f32_e32 v14, 0xbfb8aa3b, v14
	v_exp_f32_e32 v15, v14
	v_add_f32_e32 v8, 1.0, v8
	v_rcp_f32_e32 v14, v8
	v_alignbit_b32 v13, v18, v13, 16
	v_add_f32_e32 v8, 1.0, v15
	v_rcp_f32_e32 v15, v8
	v_mov_b32_e32 v8, v9
	v_mov_b32_e32 v9, v10
	v_cvt_f32_f16_e32 v10, v66
	v_pk_mul_f32 v[8:9], v[8:9], v[14:15]
	global_store_dwordx4 v[34:35], v[28:31], off
	v_cvt_pk_f16_f32 v8, v8, v9
	v_max_f32_e32 v9, 0xc1f00000, v19
	v_mul_f32_e32 v9, 0xbfb8aa3b, v9
	v_exp_f32_e32 v9, v9
	v_alignbit_b32 v14, v8, v18, 16
	v_lshrrev_b32_e32 v15, 16, v8
	v_add_f32_e32 v8, 1.0, v9
	v_rcp_f32_e32 v8, v8
	v_max_f32_e32 v9, 0xc1f00000, v10
	v_mul_f32_e32 v9, 0xbfb8aa3b, v9
	v_exp_f32_e32 v9, v9
	v_fma_mixhi_f16 v15, v11, v8, 0
	v_cvt_f32_f16_sdwa v8, v66 dst_sel:DWORD dst_unused:UNUSED_PAD src0_sel:WORD_1
	v_cvt_f32_f16_e32 v10, v67
	v_add_f32_e32 v9, 1.0, v9
	v_rcp_f32_e32 v9, v9
	v_max_f32_e32 v8, 0xc1f00000, v8
	v_mul_f32_e32 v8, 0xbfb8aa3b, v8
	v_max_f32_e32 v10, 0xc1f00000, v10
	v_exp_f32_e32 v8, v8
	v_mul_f32_e32 v10, 0xbfb8aa3b, v10
	v_exp_f32_e32 v10, v10
	v_fma_mixlo_f16 v11, v4, v9, 0
	v_add_f32_e32 v4, 1.0, v8
	v_rcp_f32_e32 v8, v4
	v_add_f32_e32 v4, 1.0, v10
	v_rcp_f32_e32 v9, v4
	v_cvt_f32_f16_sdwa v10, v67 dst_sel:DWORD dst_unused:UNUSED_PAD src0_sel:WORD_1
	v_mov_b32_e32 v4, v5
	v_mov_b32_e32 v5, v6
	v_cvt_f32_f16_e32 v6, v68
	v_max_f32_e32 v10, 0xc1f00000, v10
	v_mul_f32_e32 v10, 0xbfb8aa3b, v10
	v_exp_f32_e32 v10, v10
	v_max_f32_e32 v6, 0xc1f00000, v6
	v_mul_f32_e32 v6, 0xbfb8aa3b, v6
	v_exp_f32_e32 v6, v6
	v_pk_mul_f32 v[4:5], v[4:5], v[8:9]
	v_add_f32_e32 v8, 1.0, v10
	v_rcp_f32_e32 v8, v8
	v_add_f32_e32 v6, 1.0, v6
	v_rcp_f32_e32 v9, v6
	v_pk_mov_b32 v[6:7], v[6:7], v[0:1] op_sel:[1,0]
	v_cvt_f32_f16_sdwa v0, v68 dst_sel:DWORD dst_unused:UNUSED_PAD src0_sel:WORD_1
	v_cvt_pk_f16_f32 v5, v4, v5
	v_pk_mul_f32 v[6:7], v[6:7], v[8:9]
	v_cvt_f32_f16_sdwa v9, v69 dst_sel:DWORD dst_unused:UNUSED_PAD src0_sel:WORD_1
	v_cvt_pk_f16_f32 v8, v6, v7
	v_cvt_f32_f16_e32 v6, v69
	v_max_f32_e32 v0, 0xc1f00000, v0
	v_mul_f32_e32 v0, 0xbfb8aa3b, v0
	v_exp_f32_e32 v0, v0
	v_max_f32_e32 v6, 0xc1f00000, v6
	v_mul_f32_e32 v6, 0xbfb8aa3b, v6
	v_exp_f32_e32 v7, v6
	v_add_f32_e32 v0, 1.0, v0
	v_rcp_f32_e32 v6, v0
	v_pack_b32_f16 v4, v11, v5
	v_add_f32_e32 v0, 1.0, v7
	v_rcp_f32_e32 v7, v0
	v_max_f32_e32 v0, 0xc1f00000, v9
	v_mul_f32_e32 v0, 0xbfb8aa3b, v0
	v_exp_f32_e32 v9, v0
	v_mov_b32_e32 v0, v1
	v_mov_b32_e32 v1, v2
	v_pk_mul_f32 v[0:1], v[0:1], v[6:7]
	v_add_f32_e32 v2, 1.0, v9
	v_rcp_f32_e32 v2, v2
	v_cvt_pk_f16_f32 v0, v0, v1
	v_lshrrev_b32_e32 v7, 16, v0
	v_alignbit_b32 v5, v8, v5, 16
	v_alignbit_b32 v6, v0, v8, 16
	v_fma_mixhi_f16 v7, v3, v2, 0
	global_store_dwordx4 v[16:17], v[12:15], off
	global_store_dwordx4 v[16:17], v[4:7], off offset:256
	s_and_b64 vcc, exec, s[4:5]
	s_mov_b32 s31, s30
	s_mov_b32 s34, s29
	s_mov_b64 s[12:13], s[0:1]
	s_mov_b64 s[10:11], s[2:3]
	s_cbranch_vccz .LBB0_955
	s_waitcnt vmcnt(0)
	s_cmpk_gt_u32 s19, 0xff
	s_cbranch_scc1 .LBB0_962
	s_barrier

.LBB0_1117:
	s_add_i32 s41, s22, 2
	s_add_u32 s20, s14, 0x100
	s_addc_u32 s21, s15, 0
	s_add_i32 s42, 0, 0x10000
	s_waitcnt vmcnt(0)
	v_add_u32_e32 v102, s42, v230
	ds_read_b128 v[78:81], v102
	ds_read_b128 v[94:97], v102 offset:2048
	ds_read_b128 v[86:89], v102 offset:1024
	ds_read_b128 v[102:105], v102 offset:3072
	s_cmp_eq_u32 s38, s22
	s_cselect_b32 s22, s18, s39
	s_cselect_b32 s25, s17, s21
	s_cselect_b32 s24, s16, s20
	s_cselect_b32 s23, s19, s40
	v_lshl_add_u64 v[178:179], s[14:15], 0, v[200:201]
	s_add_i32 m0, s28, 0xc000
	ds_read_b128 v[122:125], v232
	ds_read_b128 v[130:133], v232 offset:2048
	ds_read_b128 v[154:157], v232 offset:4096
	ds_read_b128 v[170:173], v232 offset:6144
	ds_read_b128 v[126:129], v232 offset:1024
	ds_read_b128 v[134:137], v232 offset:3072
	ds_read_b128 v[158:161], v232 offset:5120
	ds_read_b128 v[174:177], v232 offset:7168
	global_load_lds_dwordx4 v[178:179], off
	v_lshl_add_u64 v[178:179], s[14:15], 0, v[202:203]
	s_add_i32 m0, s28, 0xe000
	s_nop 0
	global_load_lds_dwordx4 v[178:179], off
	s_waitcnt lgkmcnt(8)
	s_barrier
	s_waitcnt lgkmcnt(7)
	s_setprio 1
	v_mfma_f32_16x16x32_f16 v[166:169], v[78:81], v[122:125], v[166:169]
	v_mfma_f32_16x16x32_f16 v[162:165], v[94:97], v[122:125], v[162:165]
	s_waitcnt lgkmcnt(6)
	v_mfma_f32_16x16x32_f16 v[150:153], v[78:81], v[130:133], v[150:153]
	v_mfma_f32_16x16x32_f16 v[142:145], v[94:97], v[130:133], v[142:145]
	s_waitcnt lgkmcnt(5)
	v_mfma_f32_16x16x32_f16 v[110:113], v[78:81], v[154:157], v[110:113]
	v_mfma_f32_16x16x32_f16 v[106:109], v[94:97], v[154:157], v[106:109]
	s_waitcnt lgkmcnt(4)
	v_mfma_f32_16x16x32_f16 v[82:85], v[78:81], v[170:173], v[82:85]
	v_mfma_f32_16x16x32_f16 v[74:77], v[94:97], v[170:173], v[74:77]
	s_waitcnt lgkmcnt(3)
	v_mfma_f32_16x16x32_f16 v[166:169], v[86:89], v[126:129], v[166:169]
	v_mfma_f32_16x16x32_f16 v[162:165], v[102:105], v[126:129], v[162:165]
	s_waitcnt lgkmcnt(2)
	v_mfma_f32_16x16x32_f16 v[150:153], v[86:89], v[134:137], v[150:153]
	v_mfma_f32_16x16x32_f16 v[142:145], v[102:105], v[134:137], v[142:145]
	s_waitcnt lgkmcnt(1)
	v_mfma_f32_16x16x32_f16 v[110:113], v[86:89], v[158:161], v[110:113]
	v_mfma_f32_16x16x32_f16 v[106:109], v[102:105], v[158:161], v[106:109]
	s_waitcnt lgkmcnt(0)
	v_mfma_f32_16x16x32_f16 v[82:85], v[86:89], v[174:177], v[82:85]
	v_mfma_f32_16x16x32_f16 v[74:77], v[102:105], v[174:177], v[74:77]
	s_setprio 0
	s_barrier
	s_add_i32 s43, 0, 0x14000
	s_add_i32 s14, s42, s13
	v_add_u32_e32 v190, s43, v230
	v_lshl_add_u64 v[204:205], s[22:23], 0, v[32:33]
	s_mov_b32 m0, s14
	ds_read_b128 v[178:181], v190
	ds_read_b128 v[186:189], v190 offset:2048
	ds_read_b128 v[182:185], v190 offset:1024
	ds_read_b128 v[190:193], v190 offset:3072
	global_load_lds_dwordx4 v[204:205], off
	v_lshl_add_u64 v[206:207], s[22:23], 0, v[198:199]
	s_add_i32 m0, s14, 0x2000
	s_nop 0
	global_load_lds_dwordx4 v[206:207], off
	s_barrier
	s_waitcnt lgkmcnt(3)
	s_setprio 1
	v_mfma_f32_16x16x32_f16 v[146:149], v[178:181], v[122:125], v[146:149]
	v_mfma_f32_16x16x32_f16 v[118:121], v[178:181], v[130:133], v[118:121]
	s_waitcnt lgkmcnt(2)
	v_mfma_f32_16x16x32_f16 v[114:117], v[186:189], v[130:133], v[114:117]
	v_mfma_f32_16x16x32_f16 v[98:101], v[178:181], v[154:157], v[98:101]
	v_mfma_f32_16x16x32_f16 v[90:93], v[186:189], v[154:157], v[90:93]
	v_mfma_f32_16x16x32_f16 v[70:73], v[178:181], v[170:173], v[70:73]
	s_waitcnt lgkmcnt(1)
	v_mfma_f32_16x16x32_f16 v[66:69], v[186:189], v[170:173], v[66:69]
	v_mfma_f32_16x16x32_f16 v[146:149], v[182:185], v[126:129], v[146:149]
	v_mfma_f32_16x16x32_f16 v[122:125], v[186:189], v[122:125], v[138:141]
	v_mfma_f32_16x16x32_f16 v[118:121], v[182:185], v[134:137], v[118:121]
	s_waitcnt lgkmcnt(0)
	v_mfma_f32_16x16x32_f16 v[114:117], v[190:193], v[134:137], v[114:117]
	v_mfma_f32_16x16x32_f16 v[98:101], v[182:185], v[158:161], v[98:101]
	v_mfma_f32_16x16x32_f16 v[90:93], v[190:193], v[158:161], v[90:93]
	v_mfma_f32_16x16x32_f16 v[70:73], v[182:185], v[174:177], v[70:73]
	v_mfma_f32_16x16x32_f16 v[66:69], v[190:193], v[174:177], v[66:69]
	v_mfma_f32_16x16x32_f16 v[122:125], v[190:193], v[126:129], v[122:125]
	s_setprio 0
	s_barrier
	s_mov_b32 m0, s28
	v_lshl_add_u64 v[208:209], s[24:25], 0, v[32:33]
	ds_read_b128 v[126:129], v232 offset:16384
	ds_read_b128 v[134:137], v232 offset:18432
	ds_read_b128 v[154:157], v232 offset:20480
	ds_read_b128 v[170:173], v232 offset:22528
	ds_read_b128 v[130:133], v232 offset:17408
	ds_read_b128 v[138:141], v232 offset:19456
	ds_read_b128 v[158:161], v232 offset:21504
	ds_read_b128 v[174:177], v232 offset:23552
	global_load_lds_dwordx4 v[208:209], off
	v_lshl_add_u64 v[210:211], s[24:25], 0, v[198:199]
	s_mov_b32 m0, s29
	s_nop 0
	global_load_lds_dwordx4 v[210:211], off
	s_barrier
	s_waitcnt lgkmcnt(7)
	s_setprio 1
	v_mfma_f32_16x16x32_f16 v[62:65], v[78:81], v[126:129], v[62:65]
	v_mfma_f32_16x16x32_f16 v[58:61], v[94:97], v[126:129], v[58:61]
	s_waitcnt lgkmcnt(6)
	v_mfma_f32_16x16x32_f16 v[46:49], v[78:81], v[134:137], v[46:49]
	v_mfma_f32_16x16x32_f16 v[42:45], v[94:97], v[134:137], v[42:45]
	s_waitcnt lgkmcnt(5)
	v_mfma_f32_16x16x32_f16 v[28:31], v[78:81], v[154:157], v[28:31]
	v_mfma_f32_16x16x32_f16 v[24:27], v[94:97], v[154:157], v[24:27]
	s_waitcnt lgkmcnt(4)
	v_mfma_f32_16x16x32_f16 v[12:15], v[78:81], v[170:173], v[12:15]
	v_mfma_f32_16x16x32_f16 v[8:11], v[94:97], v[170:173], v[8:11]
	s_waitcnt lgkmcnt(3)
	v_mfma_f32_16x16x32_f16 v[62:65], v[86:89], v[130:133], v[62:65]
	v_mfma_f32_16x16x32_f16 v[58:61], v[102:105], v[130:133], v[58:61]
	s_waitcnt lgkmcnt(2)
	v_mfma_f32_16x16x32_f16 v[46:49], v[86:89], v[138:141], v[46:49]
	v_mfma_f32_16x16x32_f16 v[42:45], v[102:105], v[138:141], v[42:45]
	s_waitcnt lgkmcnt(1)
	v_mfma_f32_16x16x32_f16 v[28:31], v[86:89], v[158:161], v[28:31]
	v_mfma_f32_16x16x32_f16 v[24:27], v[102:105], v[158:161], v[24:27]
	s_waitcnt lgkmcnt(0)
	v_mfma_f32_16x16x32_f16 v[12:15], v[86:89], v[174:177], v[12:15]
	v_mfma_f32_16x16x32_f16 v[8:11], v[102:105], v[174:177], v[8:11]
	s_setprio 0
	s_barrier
	s_add_u32 s14, s22, 0x40000
	s_addc_u32 s15, s23, 0
	s_add_i32 s42, s43, s13
	v_lshl_add_u64 v[78:79], s[14:15], 0, v[32:33]
	s_mov_b32 m0, s42
	s_nop 0
	global_load_lds_dwordx4 v[78:79], off
	v_lshl_add_u64 v[78:79], s[14:15], 0, v[198:199]
	s_add_i32 m0, s42, 0x2000
	s_nop 0
	global_load_lds_dwordx4 v[78:79], off
	s_waitcnt vmcnt(6)
	s_barrier
	s_setprio 1
	v_mfma_f32_16x16x32_f16 v[54:57], v[178:181], v[126:129], v[54:57]
	v_mfma_f32_16x16x32_f16 v[50:53], v[186:189], v[126:129], v[50:53]
	v_mfma_f32_16x16x32_f16 v[38:41], v[178:181], v[134:137], v[38:41]
	v_mfma_f32_16x16x32_f16 v[34:37], v[186:189], v[134:137], v[34:37]
	v_mfma_f32_16x16x32_f16 v[20:23], v[178:181], v[154:157], v[20:23]
	v_mfma_f32_16x16x32_f16 v[16:19], v[186:189], v[154:157], v[16:19]
	v_mfma_f32_16x16x32_f16 v[4:7], v[178:181], v[170:173], v[4:7]
	v_mfma_f32_16x16x32_f16 v[0:3], v[186:189], v[170:173], v[0:3]
	v_mfma_f32_16x16x32_f16 v[54:57], v[182:185], v[130:133], v[54:57]
	v_mfma_f32_16x16x32_f16 v[50:53], v[190:193], v[130:133], v[50:53]
	v_mfma_f32_16x16x32_f16 v[38:41], v[182:185], v[138:141], v[38:41]
	v_mfma_f32_16x16x32_f16 v[34:37], v[190:193], v[138:141], v[34:37]
	v_mfma_f32_16x16x32_f16 v[20:23], v[182:185], v[158:161], v[20:23]
	v_mfma_f32_16x16x32_f16 v[16:19], v[190:193], v[158:161], v[16:19]
	v_mfma_f32_16x16x32_f16 v[4:7], v[182:185], v[174:177], v[4:7]
	v_mfma_f32_16x16x32_f16 v[0:3], v[190:193], v[174:177], v[0:3]
	s_setprio 0
	s_barrier
	s_add_i32 s42, 0, 0x18000
	v_add_u32_e32 v102, s42, v230
	ds_read_b128 v[78:81], v102
	ds_read_b128 v[86:89], v102 offset:1024
	ds_read_b128 v[94:97], v102 offset:2048
	ds_read_b128 v[102:105], v102 offset:3072
	s_add_u32 s14, s24, 0x40000
	s_addc_u32 s15, s25, 0
	s_mov_b32 m0, s30
	v_lshl_add_u64 v[138:139], s[14:15], 0, v[32:33]
	ds_read_b128 v[126:129], v232 offset:32768
	ds_read_b128 v[130:133], v232 offset:33792
	ds_read_b128 v[134:137], v232 offset:34816
	ds_read_b128 v[154:157], v232 offset:35840
	ds_read_b128 v[158:161], v232 offset:36864
	ds_read_b128 v[174:177], v232 offset:38912
	ds_read_b128 v[170:173], v232 offset:37888
	ds_read_b128 v[178:181], v232 offset:39936
	global_load_lds_dwordx4 v[138:139], off
	v_lshl_add_u64 v[138:139], s[14:15], 0, v[198:199]
	s_mov_b32 m0, s31
	s_nop 0
	global_load_lds_dwordx4 v[138:139], off
	s_waitcnt lgkmcnt(8)
	s_barrier
	s_waitcnt lgkmcnt(6)
	s_setprio 1
	v_mfma_f32_16x16x32_f16 v[138:141], v[78:81], v[126:129], v[166:169]
	v_mfma_f32_16x16x32_f16 v[166:169], v[86:89], v[130:133], v[138:141]
	v_mfma_f32_16x16x32_f16 v[138:141], v[94:97], v[126:129], v[162:165]
	v_mfma_f32_16x16x32_f16 v[162:165], v[102:105], v[130:133], v[138:141]
	s_waitcnt lgkmcnt(4)
	v_mfma_f32_16x16x32_f16 v[138:141], v[78:81], v[134:137], v[150:153]
	v_mfma_f32_16x16x32_f16 v[150:153], v[86:89], v[154:157], v[138:141]
	s_waitcnt lgkmcnt(3)
	v_mfma_f32_16x16x32_f16 v[138:141], v[94:97], v[134:137], v[142:145]
	v_mfma_f32_16x16x32_f16 v[110:113], v[78:81], v[158:161], v[110:113]
	s_waitcnt lgkmcnt(2)
	v_mfma_f32_16x16x32_f16 v[106:109], v[94:97], v[158:161], v[106:109]
	v_mfma_f32_16x16x32_f16 v[82:85], v[78:81], v[174:177], v[82:85]
	v_mfma_f32_16x16x32_f16 v[74:77], v[94:97], v[174:177], v[74:77]
	v_mfma_f32_16x16x32_f16 v[142:145], v[102:105], v[154:157], v[138:141]
	s_waitcnt lgkmcnt(1)
	v_mfma_f32_16x16x32_f16 v[110:113], v[86:89], v[170:173], v[110:113]
	v_mfma_f32_16x16x32_f16 v[106:109], v[102:105], v[170:173], v[106:109]
	s_waitcnt lgkmcnt(0)
	v_mfma_f32_16x16x32_f16 v[82:85], v[86:89], v[178:181], v[82:85]
	v_mfma_f32_16x16x32_f16 v[74:77], v[102:105], v[178:181], v[74:77]
	s_setprio 0
	s_barrier
	s_add_i32 s24, 0, 0x1c000
	v_add_u32_e32 v138, s24, v230
	s_add_i32 s14, s42, s13
	ds_read_b128 v[182:185], v138
	ds_read_b128 v[190:193], v138 offset:2048
	ds_read_b128 v[186:189], v138 offset:1024
	ds_read_b128 v[194:197], v138 offset:3072
	v_lshl_add_u64 v[138:139], v[204:205], 0, s[84:85]
	s_mov_b32 m0, s14
	s_nop 0
	global_load_lds_dwordx4 v[138:139], off
	v_lshl_add_u64 v[138:139], v[206:207], 0, s[84:85]
	s_add_i32 m0, s14, 0x2000
	s_nop 0
	global_load_lds_dwordx4 v[138:139], off
	s_barrier
	s_waitcnt lgkmcnt(2)
	s_setprio 1
	v_mfma_f32_16x16x32_f16 v[138:141], v[182:185], v[126:129], v[146:149]
	v_mfma_f32_16x16x32_f16 v[122:125], v[190:193], v[126:129], v[122:125]
	v_mfma_f32_16x16x32_f16 v[118:121], v[182:185], v[134:137], v[118:121]
	v_mfma_f32_16x16x32_f16 v[114:117], v[190:193], v[134:137], v[114:117]
	v_mfma_f32_16x16x32_f16 v[98:101], v[182:185], v[158:161], v[98:101]
	v_mfma_f32_16x16x32_f16 v[90:93], v[190:193], v[158:161], v[90:93]
	v_mfma_f32_16x16x32_f16 v[70:73], v[182:185], v[174:177], v[70:73]
	v_mfma_f32_16x16x32_f16 v[66:69], v[190:193], v[174:177], v[66:69]
	s_waitcnt lgkmcnt(0)
	v_mfma_f32_16x16x32_f16 v[146:149], v[186:189], v[130:133], v[138:141]
	v_mfma_f32_16x16x32_f16 v[138:141], v[194:197], v[130:133], v[122:125]
	v_mfma_f32_16x16x32_f16 v[118:121], v[186:189], v[154:157], v[118:121]
	v_mfma_f32_16x16x32_f16 v[114:117], v[194:197], v[154:157], v[114:117]
	v_mfma_f32_16x16x32_f16 v[98:101], v[186:189], v[170:173], v[98:101]
	v_mfma_f32_16x16x32_f16 v[90:93], v[194:197], v[170:173], v[90:93]
	v_mfma_f32_16x16x32_f16 v[70:73], v[186:189], v[178:181], v[70:73]
	v_mfma_f32_16x16x32_f16 v[66:69], v[194:197], v[178:181], v[66:69]
	s_setprio 0
	s_barrier
	s_mov_b32 m0, s34
	v_lshl_add_u64 v[178:179], v[208:209], 0, s[84:85]
	ds_read_b128 v[122:125], v232 offset:49152
	ds_read_b128 v[130:133], v232 offset:51200
	ds_read_b128 v[154:157], v232 offset:53248
	ds_read_b128 v[170:173], v232 offset:55296
	ds_read_b128 v[126:129], v232 offset:50176
	ds_read_b128 v[134:137], v232 offset:52224
	ds_read_b128 v[158:161], v232 offset:54272
	ds_read_b128 v[174:177], v232 offset:56320
	global_load_lds_dwordx4 v[178:179], off
	v_lshl_add_u64 v[178:179], v[210:211], 0, s[84:85]
	s_mov_b32 m0, s35
	s_nop 0
	global_load_lds_dwordx4 v[178:179], off
	s_barrier
	s_waitcnt lgkmcnt(7)
	s_setprio 1
	v_mfma_f32_16x16x32_f16 v[62:65], v[78:81], v[122:125], v[62:65]
	v_mfma_f32_16x16x32_f16 v[58:61], v[94:97], v[122:125], v[58:61]
	s_waitcnt lgkmcnt(6)
	v_mfma_f32_16x16x32_f16 v[46:49], v[78:81], v[130:133], v[46:49]
	v_mfma_f32_16x16x32_f16 v[42:45], v[94:97], v[130:133], v[42:45]
	s_waitcnt lgkmcnt(5)
	v_mfma_f32_16x16x32_f16 v[28:31], v[78:81], v[154:157], v[28:31]
	v_mfma_f32_16x16x32_f16 v[24:27], v[94:97], v[154:157], v[24:27]
	s_waitcnt lgkmcnt(4)
	v_mfma_f32_16x16x32_f16 v[12:15], v[78:81], v[170:173], v[12:15]
	v_mfma_f32_16x16x32_f16 v[8:11], v[94:97], v[170:173], v[8:11]
	s_waitcnt lgkmcnt(3)
	v_mfma_f32_16x16x32_f16 v[62:65], v[86:89], v[126:129], v[62:65]
	v_mfma_f32_16x16x32_f16 v[58:61], v[102:105], v[126:129], v[58:61]
	s_waitcnt lgkmcnt(2)
	v_mfma_f32_16x16x32_f16 v[46:49], v[86:89], v[134:137], v[46:49]
	v_mfma_f32_16x16x32_f16 v[42:45], v[102:105], v[134:137], v[42:45]
	s_waitcnt lgkmcnt(1)
	v_mfma_f32_16x16x32_f16 v[28:31], v[86:89], v[158:161], v[28:31]
	v_mfma_f32_16x16x32_f16 v[24:27], v[102:105], v[158:161], v[24:27]
	s_waitcnt lgkmcnt(0)
	v_mfma_f32_16x16x32_f16 v[12:15], v[86:89], v[174:177], v[12:15]
	v_mfma_f32_16x16x32_f16 v[8:11], v[102:105], v[174:177], v[8:11]
	s_setprio 0
	s_barrier
	s_add_u32 s14, s22, 0x40080
	s_addc_u32 s15, s23, 0
	s_add_i32 s22, s24, s13
	v_lshl_add_u64 v[78:79], s[14:15], 0, v[32:33]
	s_mov_b32 m0, s22
	s_nop 0
	global_load_lds_dwordx4 v[78:79], off
	v_lshl_add_u64 v[78:79], s[14:15], 0, v[198:199]
	s_add_i32 m0, s22, 0x2000
	s_nop 0
	global_load_lds_dwordx4 v[78:79], off
	s_waitcnt vmcnt(6)
	s_barrier
	s_setprio 1
	v_mfma_f32_16x16x32_f16 v[54:57], v[182:185], v[122:125], v[54:57]
	v_mfma_f32_16x16x32_f16 v[50:53], v[190:193], v[122:125], v[50:53]
	v_mfma_f32_16x16x32_f16 v[38:41], v[182:185], v[130:133], v[38:41]
	v_mfma_f32_16x16x32_f16 v[34:37], v[190:193], v[130:133], v[34:37]
	v_mfma_f32_16x16x32_f16 v[20:23], v[182:185], v[154:157], v[20:23]
	v_mfma_f32_16x16x32_f16 v[16:19], v[190:193], v[154:157], v[16:19]
	v_mfma_f32_16x16x32_f16 v[4:7], v[182:185], v[170:173], v[4:7]
	v_mfma_f32_16x16x32_f16 v[0:3], v[190:193], v[170:173], v[0:3]
	v_mfma_f32_16x16x32_f16 v[54:57], v[186:189], v[126:129], v[54:57]
	v_mfma_f32_16x16x32_f16 v[50:53], v[194:197], v[126:129], v[50:53]
	v_mfma_f32_16x16x32_f16 v[38:41], v[186:189], v[134:137], v[38:41]
	v_mfma_f32_16x16x32_f16 v[34:37], v[194:197], v[134:137], v[34:37]
	v_mfma_f32_16x16x32_f16 v[20:23], v[186:189], v[158:161], v[20:23]
	v_mfma_f32_16x16x32_f16 v[16:19], v[194:197], v[158:161], v[16:19]
	v_mfma_f32_16x16x32_f16 v[4:7], v[186:189], v[174:177], v[4:7]
	v_mfma_f32_16x16x32_f16 v[0:3], v[194:197], v[174:177], v[0:3]
	s_setprio 0
	s_barrier
	s_add_u32 s39, s39, 0x100
	s_addc_u32 s40, s40, 0
	s_cmp_ge_u32 s41, s37
	s_mov_b64 s[14:15], s[20:21]
	s_mov_b32 s22, s41
	s_cbranch_scc0 .LBB0_1117
	v_lshl_or_b32 v124, s12, 8, v231
	s_cmp_eq_u32 s10, 0
	s_movk_i32 s12, 0x5000
	s_cselect_b32 s12, 0xe000, s12
	v_readlane_b32 s14, v252, 51
	s_add_u32 s14, s14, s12
	v_readlane_b32 s12, v252, 52
	s_addc_u32 s15, s12, 0
	v_ashrrev_i32_e32 v125, 31, v124
	v_lshl_add_u64 v[86:87], v[124:125], 2, s[14:15]
	global_load_dwordx4 v[94:97], v[86:87], off offset:16
	global_load_dwordx4 v[102:105], v[86:87], off
	global_load_dwordx4 v[78:81], v[86:87], off offset:528
	s_nop 0
	global_load_dwordx4 v[86:89], v[86:87], off offset:512
	v_lshl_add_u32 v130, s10, 8, v229
	v_or_b32_e32 v128, 16, v130
	v_or_b32_e32 v126, 32, v130
	v_or_b32_e32 v122, 48, v130
	s_cmp_eq_u32 s11, 0
	v_ashrrev_i32_e32 v131, 31, v130
	v_ashrrev_i32_e32 v129, 31, v128
	v_ashrrev_i32_e32 v127, 31, v126
	v_ashrrev_i32_e32 v123, 31, v122
	s_cbranch_scc1 .LBB0_1120
	s_add_i32 s96, s11, -1
	s_lshl_b64 s[10:11], s[96:97], 20
	v_readlane_b32 s14, v252, 11
	v_readlane_b32 s15, v252, 12
	s_add_u32 s10, s14, s10
	s_addc_u32 s11, s15, s11
	v_lshlrev_b64 v[132:133], 2, v[124:125]
	v_lshrrev_b32_e32 v134, 5, v220
	v_mul_u32_u24_e32 v134, 48, v134
	s_nop 0
	v_sub_co_u32_e32 v132, vcc, v132, v134
	s_nop 1
	v_subbrev_co_u32_e32 v133, vcc, 0, v133, vcc
	v_lshl_add_u64 v[132:133], s[10:11], 0, v[132:133]
	s_mov_b64 s[10:11], 0x80000
	v_lshlrev_b64 v[204:205], 12, v[130:131]
	v_lshl_add_u64 v[204:205], v[204:205], 0, v[132:133]
	v_lshl_add_u64 v[212:213], v[204:205], 0, s[10:11]
	v_lshlrev_b64 v[206:207], 12, v[128:129]
	v_lshl_add_u64 v[206:207], v[206:207], 0, v[132:133]
	v_lshl_add_u64 v[214:215], v[206:207], 0, s[10:11]
	v_lshlrev_b64 v[208:209], 12, v[126:127]
	v_lshl_add_u64 v[208:209], v[208:209], 0, v[132:133]
	v_lshl_add_u64 v[216:217], v[208:209], 0, s[10:11]
	v_lshlrev_b64 v[210:211], 12, v[122:123]
	v_lshl_add_u64 v[210:211], v[210:211], 0, v[132:133]
	v_lshl_add_u64 v[218:219], v[210:211], 0, s[10:11]
	s_waitcnt vmcnt(0)
	v_pk_mul_f32 v[172:173], v[166:167], v[102:103]
	v_pk_mul_f32 v[174:175], v[168:169], v[104:105]
	v_pk_mul_f32 v[176:177], v[162:163], v[94:95]
	v_pk_mul_f32 v[178:179], v[164:165], v[96:97]
	s_nop 1
	v_permlane32_swap_b32_e32 v172, v176
	v_permlane32_swap_b32_e32 v173, v177
	v_permlane32_swap_b32_e32 v174, v178
	v_permlane32_swap_b32_e32 v175, v179
	s_nop 0
	global_store_dwordx4 v[204:205], v[172:175], off
	global_store_dwordx4 v[204:205], v[176:179], off offset:64
	v_pk_mul_f32 v[180:181], v[146:147], v[86:87]
	v_pk_mul_f32 v[182:183], v[148:149], v[88:89]
	v_pk_mul_f32 v[184:185], v[138:139], v[78:79]
	v_pk_mul_f32 v[186:187], v[140:141], v[80:81]
	s_nop 1
	v_permlane32_swap_b32_e32 v180, v184
	v_permlane32_swap_b32_e32 v181, v185
	v_permlane32_swap_b32_e32 v182, v186
	v_permlane32_swap_b32_e32 v183, v187
	s_nop 0
	global_store_dwordx4 v[204:205], v[180:183], off offset:512
	global_store_dwordx4 v[204:205], v[184:187], off offset:576
	v_pk_mul_f32 v[188:189], v[150:151], v[102:103]
	v_pk_mul_f32 v[190:191], v[152:153], v[104:105]
	v_pk_mul_f32 v[192:193], v[142:143], v[94:95]
	v_pk_mul_f32 v[194:195], v[144:145], v[96:97]
	s_nop 1
	v_permlane32_swap_b32_e32 v188, v192
	v_permlane32_swap_b32_e32 v189, v193
	v_permlane32_swap_b32_e32 v190, v194
	v_permlane32_swap_b32_e32 v191, v195
	s_nop 0
	global_store_dwordx4 v[206:207], v[188:191], off
	global_store_dwordx4 v[206:207], v[192:195], off offset:64
	v_pk_mul_f32 v[154:155], v[118:119], v[86:87]
	v_pk_mul_f32 v[156:157], v[120:121], v[88:89]
	v_pk_mul_f32 v[158:159], v[114:115], v[78:79]
	v_pk_mul_f32 v[160:161], v[116:117], v[80:81]
	s_nop 1
	v_permlane32_swap_b32_e32 v154, v158
	v_permlane32_swap_b32_e32 v155, v159
	v_permlane32_swap_b32_e32 v156, v160
	v_permlane32_swap_b32_e32 v157, v161
	s_nop 0
	global_store_dwordx4 v[206:207], v[154:157], off offset:512
	global_store_dwordx4 v[206:207], v[158:161], off offset:576
	v_pk_mul_f32 v[172:173], v[110:111], v[102:103]
	v_pk_mul_f32 v[174:175], v[112:113], v[104:105]
	v_pk_mul_f32 v[176:177], v[106:107], v[94:95]
	v_pk_mul_f32 v[178:179], v[108:109], v[96:97]
	s_nop 1
	v_permlane32_swap_b32_e32 v172, v176
	v_permlane32_swap_b32_e32 v173, v177
	v_permlane32_swap_b32_e32 v174, v178
	v_permlane32_swap_b32_e32 v175, v179
	s_nop 0
	global_store_dwordx4 v[208:209], v[172:175], off
	global_store_dwordx4 v[208:209], v[176:179], off offset:64
	v_pk_mul_f32 v[180:181], v[98:99], v[86:87]
	v_pk_mul_f32 v[182:183], v[100:101], v[88:89]
	v_pk_mul_f32 v[184:185], v[90:91], v[78:79]
	v_pk_mul_f32 v[186:187], v[92:93], v[80:81]
	s_nop 1
	v_permlane32_swap_b32_e32 v180, v184
	v_permlane32_swap_b32_e32 v181, v185
	v_permlane32_swap_b32_e32 v182, v186
	v_permlane32_swap_b32_e32 v183, v187
	s_nop 0
	global_store_dwordx4 v[208:209], v[180:183], off offset:512
	global_store_dwordx4 v[208:209], v[184:187], off offset:576
	v_pk_mul_f32 v[188:189], v[82:83], v[102:103]
	v_pk_mul_f32 v[190:191], v[84:85], v[104:105]
	v_pk_mul_f32 v[192:193], v[74:75], v[94:95]
	v_pk_mul_f32 v[194:195], v[76:77], v[96:97]
	s_nop 1
	v_permlane32_swap_b32_e32 v188, v192
	v_permlane32_swap_b32_e32 v189, v193
	v_permlane32_swap_b32_e32 v190, v194
	v_permlane32_swap_b32_e32 v191, v195
	s_nop 0
	global_store_dwordx4 v[210:211], v[188:191], off
	global_store_dwordx4 v[210:211], v[192:195], off offset:64
	v_pk_mul_f32 v[154:155], v[70:71], v[86:87]
	v_pk_mul_f32 v[156:157], v[72:73], v[88:89]
	v_pk_mul_f32 v[158:159], v[66:67], v[78:79]
	v_pk_mul_f32 v[160:161], v[68:69], v[80:81]
	s_nop 1
	v_permlane32_swap_b32_e32 v154, v158
	v_permlane32_swap_b32_e32 v155, v159
	v_permlane32_swap_b32_e32 v156, v160
	v_permlane32_swap_b32_e32 v157, v161
	s_nop 0
	global_store_dwordx4 v[210:211], v[154:157], off offset:512
	global_store_dwordx4 v[210:211], v[158:161], off offset:576
	v_pk_mul_f32 v[172:173], v[62:63], v[102:103]
	v_pk_mul_f32 v[174:175], v[64:65], v[104:105]
	v_pk_mul_f32 v[176:177], v[58:59], v[94:95]
	v_pk_mul_f32 v[178:179], v[60:61], v[96:97]
	s_nop 1
	v_permlane32_swap_b32_e32 v172, v176
	v_permlane32_swap_b32_e32 v173, v177
	v_permlane32_swap_b32_e32 v174, v178
	v_permlane32_swap_b32_e32 v175, v179
	s_nop 0
	global_store_dwordx4 v[212:213], v[172:175], off
	global_store_dwordx4 v[212:213], v[176:179], off offset:64
	v_pk_mul_f32 v[180:181], v[54:55], v[86:87]
	v_pk_mul_f32 v[182:183], v[56:57], v[88:89]
	v_pk_mul_f32 v[184:185], v[50:51], v[78:79]
	v_pk_mul_f32 v[186:187], v[52:53], v[80:81]
	s_nop 1
	v_permlane32_swap_b32_e32 v180, v184
	v_permlane32_swap_b32_e32 v181, v185
	v_permlane32_swap_b32_e32 v182, v186
	v_permlane32_swap_b32_e32 v183, v187
	s_nop 0
	global_store_dwordx4 v[212:213], v[180:183], off offset:512
	global_store_dwordx4 v[212:213], v[184:187], off offset:576
	v_pk_mul_f32 v[188:189], v[46:47], v[102:103]
	v_pk_mul_f32 v[190:191], v[48:49], v[104:105]
	v_pk_mul_f32 v[192:193], v[42:43], v[94:95]
	v_pk_mul_f32 v[194:195], v[44:45], v[96:97]
	s_nop 1
	v_permlane32_swap_b32_e32 v188, v192
	v_permlane32_swap_b32_e32 v189, v193
	v_permlane32_swap_b32_e32 v190, v194
	v_permlane32_swap_b32_e32 v191, v195
	s_nop 0
	global_store_dwordx4 v[214:215], v[188:191], off
	global_store_dwordx4 v[214:215], v[192:195], off offset:64
	v_pk_mul_f32 v[154:155], v[38:39], v[86:87]
	v_pk_mul_f32 v[156:157], v[40:41], v[88:89]
	v_pk_mul_f32 v[158:159], v[34:35], v[78:79]
	v_pk_mul_f32 v[160:161], v[36:37], v[80:81]
	s_nop 1
	v_permlane32_swap_b32_e32 v154, v158
	v_permlane32_swap_b32_e32 v155, v159
	v_permlane32_swap_b32_e32 v156, v160
	v_permlane32_swap_b32_e32 v157, v161
	s_nop 0
	global_store_dwordx4 v[214:215], v[154:157], off offset:512
	global_store_dwordx4 v[214:215], v[158:161], off offset:576
	v_pk_mul_f32 v[172:173], v[28:29], v[102:103]
	v_pk_mul_f32 v[174:175], v[30:31], v[104:105]
	v_pk_mul_f32 v[176:177], v[24:25], v[94:95]
	v_pk_mul_f32 v[178:179], v[26:27], v[96:97]
	s_nop 1
	v_permlane32_swap_b32_e32 v172, v176
	v_permlane32_swap_b32_e32 v173, v177
	v_permlane32_swap_b32_e32 v174, v178
	v_permlane32_swap_b32_e32 v175, v179
	s_nop 0
	global_store_dwordx4 v[216:217], v[172:175], off
	global_store_dwordx4 v[216:217], v[176:179], off offset:64
	v_pk_mul_f32 v[180:181], v[20:21], v[86:87]
	v_pk_mul_f32 v[182:183], v[22:23], v[88:89]
	v_pk_mul_f32 v[184:185], v[16:17], v[78:79]
	v_pk_mul_f32 v[186:187], v[18:19], v[80:81]
	s_nop 1
	v_permlane32_swap_b32_e32 v180, v184
	v_permlane32_swap_b32_e32 v181, v185
	v_permlane32_swap_b32_e32 v182, v186
	v_permlane32_swap_b32_e32 v183, v187
	s_nop 0
	global_store_dwordx4 v[216:217], v[180:183], off offset:512
	global_store_dwordx4 v[216:217], v[184:187], off offset:576
	v_pk_mul_f32 v[188:189], v[12:13], v[102:103]
	v_pk_mul_f32 v[190:191], v[14:15], v[104:105]
	v_pk_mul_f32 v[192:193], v[8:9], v[94:95]
	v_pk_mul_f32 v[194:195], v[10:11], v[96:97]
	s_nop 1
	v_permlane32_swap_b32_e32 v188, v192
	v_permlane32_swap_b32_e32 v189, v193
	v_permlane32_swap_b32_e32 v190, v194
	v_permlane32_swap_b32_e32 v191, v195
	s_nop 0
	global_store_dwordx4 v[218:219], v[188:191], off
	global_store_dwordx4 v[218:219], v[192:195], off offset:64
	v_pk_mul_f32 v[154:155], v[4:5], v[86:87]
	v_pk_mul_f32 v[156:157], v[6:7], v[88:89]
	v_pk_mul_f32 v[158:159], v[0:1], v[78:79]
	v_pk_mul_f32 v[160:161], v[2:3], v[80:81]
	s_nop 1
	v_permlane32_swap_b32_e32 v154, v158
	v_permlane32_swap_b32_e32 v155, v159
	v_permlane32_swap_b32_e32 v156, v160
	v_permlane32_swap_b32_e32 v157, v161
	s_nop 0
	global_store_dwordx4 v[218:219], v[154:157], off offset:512
	global_store_dwordx4 v[218:219], v[158:161], off offset:576
	s_cbranch_execnz .LBB0_1104
	s_branch .LBB0_1103

.LBB0_1276:
	s_add_u32 s16, s14, 0x100
	s_addc_u32 s17, s15, 0
	s_add_i32 s39, 0, 0x10000
	v_add_u32_e32 v152, s39, v137
	ds_read_b128 v[140:143], v152
	ds_read_b128 v[148:151], v152 offset:2048
	ds_read_b128 v[144:147], v152 offset:1024
	ds_read_b128 v[152:155], v152 offset:3072
	s_cmp_eq_u32 s38, 12
	s_cselect_b32 s21, s11, s17
	s_cselect_b32 s20, s10, s16
	s_cselect_b32 s19, s13, s37
	s_cselect_b32 s18, s12, s3
	v_lshl_add_u64 v[188:189], s[14:15], 0, v[132:133]
	s_add_i32 m0, s9, 0xc000
	ds_read_b128 v[156:159], v139
	ds_read_b128 v[164:167], v139 offset:2048
	ds_read_b128 v[172:175], v139 offset:4096
	ds_read_b128 v[180:183], v139 offset:6144
	ds_read_b128 v[160:163], v139 offset:1024
	ds_read_b128 v[168:171], v139 offset:3072
	ds_read_b128 v[176:179], v139 offset:5120
	ds_read_b128 v[184:187], v139 offset:7168
	global_load_lds_dwordx4 v[188:189], off
	v_lshl_add_u64 v[188:189], s[14:15], 0, v[134:135]
	s_add_i32 m0, s9, 0xe000
	s_nop 0
	global_load_lds_dwordx4 v[188:189], off
	s_waitcnt lgkmcnt(8)
	s_barrier
	s_waitcnt lgkmcnt(7)
	s_setprio 1
	v_mfma_f32_16x16x32_f16 v[126:129], v[140:143], v[156:159], v[126:129]
	v_mfma_f32_16x16x32_f16 v[122:125], v[148:151], v[156:159], v[122:125]
	s_waitcnt lgkmcnt(6)
	v_mfma_f32_16x16x32_f16 v[110:113], v[140:143], v[164:167], v[110:113]
	v_mfma_f32_16x16x32_f16 v[106:109], v[148:151], v[164:167], v[106:109]
	s_waitcnt lgkmcnt(5)
	v_mfma_f32_16x16x32_f16 v[94:97], v[140:143], v[172:175], v[94:97]
	v_mfma_f32_16x16x32_f16 v[90:93], v[148:151], v[172:175], v[90:93]
	s_waitcnt lgkmcnt(4)
	v_mfma_f32_16x16x32_f16 v[78:81], v[140:143], v[180:183], v[78:81]
	v_mfma_f32_16x16x32_f16 v[74:77], v[148:151], v[180:183], v[74:77]
	s_waitcnt lgkmcnt(3)
	v_mfma_f32_16x16x32_f16 v[126:129], v[144:147], v[160:163], v[126:129]
	v_mfma_f32_16x16x32_f16 v[122:125], v[152:155], v[160:163], v[122:125]
	s_waitcnt lgkmcnt(2)
	v_mfma_f32_16x16x32_f16 v[110:113], v[144:147], v[168:171], v[110:113]
	v_mfma_f32_16x16x32_f16 v[106:109], v[152:155], v[168:171], v[106:109]
	s_waitcnt lgkmcnt(1)
	v_mfma_f32_16x16x32_f16 v[94:97], v[144:147], v[176:179], v[94:97]
	v_mfma_f32_16x16x32_f16 v[90:93], v[152:155], v[176:179], v[90:93]
	s_waitcnt lgkmcnt(0)
	v_mfma_f32_16x16x32_f16 v[78:81], v[144:147], v[184:187], v[78:81]
	v_mfma_f32_16x16x32_f16 v[74:77], v[152:155], v[184:187], v[74:77]
	s_setprio 0
	s_barrier
	s_add_i32 s40, 0, 0x14000
	s_add_i32 s14, s39, s26
	v_add_u32_e32 v200, s40, v137
	v_lshl_add_u64 v[204:205], s[18:19], 0, v[32:33]
	s_mov_b32 m0, s14
	ds_read_b128 v[188:191], v200
	ds_read_b128 v[196:199], v200 offset:2048
	ds_read_b128 v[192:195], v200 offset:1024
	ds_read_b128 v[200:203], v200 offset:3072
	global_load_lds_dwordx4 v[204:205], off
	v_lshl_add_u64 v[206:207], s[18:19], 0, v[130:131]
	s_add_i32 m0, s14, 0x2000
	s_nop 0
	global_load_lds_dwordx4 v[206:207], off
	s_barrier
	s_waitcnt lgkmcnt(2)
	s_setprio 1
	v_mfma_f32_16x16x32_f16 v[118:121], v[188:191], v[156:159], v[118:121]
	v_mfma_f32_16x16x32_f16 v[114:117], v[196:199], v[156:159], v[114:117]
	v_mfma_f32_16x16x32_f16 v[102:105], v[188:191], v[164:167], v[102:105]
	v_mfma_f32_16x16x32_f16 v[98:101], v[196:199], v[164:167], v[98:101]
	v_mfma_f32_16x16x32_f16 v[86:89], v[188:191], v[172:175], v[86:89]
	v_mfma_f32_16x16x32_f16 v[82:85], v[196:199], v[172:175], v[82:85]
	v_mfma_f32_16x16x32_f16 v[70:73], v[188:191], v[180:183], v[70:73]
	v_mfma_f32_16x16x32_f16 v[66:69], v[196:199], v[180:183], v[66:69]
	s_waitcnt lgkmcnt(0)
	v_mfma_f32_16x16x32_f16 v[118:121], v[192:195], v[160:163], v[118:121]
	v_mfma_f32_16x16x32_f16 v[114:117], v[200:203], v[160:163], v[114:117]
	v_mfma_f32_16x16x32_f16 v[102:105], v[192:195], v[168:171], v[102:105]
	v_mfma_f32_16x16x32_f16 v[98:101], v[200:203], v[168:171], v[98:101]
	v_mfma_f32_16x16x32_f16 v[86:89], v[192:195], v[176:179], v[86:89]
	v_mfma_f32_16x16x32_f16 v[82:85], v[200:203], v[176:179], v[82:85]
	v_mfma_f32_16x16x32_f16 v[70:73], v[192:195], v[184:187], v[70:73]
	v_mfma_f32_16x16x32_f16 v[66:69], v[200:203], v[184:187], v[66:69]
	s_setprio 0
	s_barrier
	s_mov_b32 m0, s9
	v_lshl_add_u64 v[208:209], s[20:21], 0, v[32:33]
	ds_read_b128 v[156:159], v139 offset:16384
	ds_read_b128 v[164:167], v139 offset:18432
	ds_read_b128 v[172:175], v139 offset:20480
	ds_read_b128 v[180:183], v139 offset:22528
	ds_read_b128 v[160:163], v139 offset:17408
	ds_read_b128 v[168:171], v139 offset:19456
	ds_read_b128 v[176:179], v139 offset:21504
	ds_read_b128 v[184:187], v139 offset:23552
	global_load_lds_dwordx4 v[208:209], off
	v_lshl_add_u64 v[210:211], s[20:21], 0, v[130:131]
	s_mov_b32 m0, s27
	s_nop 0
	global_load_lds_dwordx4 v[210:211], off
	s_barrier
	s_waitcnt lgkmcnt(7)
	s_setprio 1
	v_mfma_f32_16x16x32_f16 v[62:65], v[140:143], v[156:159], v[62:65]
	v_mfma_f32_16x16x32_f16 v[58:61], v[148:151], v[156:159], v[58:61]
	s_waitcnt lgkmcnt(6)
	v_mfma_f32_16x16x32_f16 v[46:49], v[140:143], v[164:167], v[46:49]
	v_mfma_f32_16x16x32_f16 v[42:45], v[148:151], v[164:167], v[42:45]
	s_waitcnt lgkmcnt(5)
	v_mfma_f32_16x16x32_f16 v[28:31], v[140:143], v[172:175], v[28:31]
	v_mfma_f32_16x16x32_f16 v[24:27], v[148:151], v[172:175], v[24:27]
	s_waitcnt lgkmcnt(4)
	v_mfma_f32_16x16x32_f16 v[12:15], v[140:143], v[180:183], v[12:15]
	v_mfma_f32_16x16x32_f16 v[8:11], v[148:151], v[180:183], v[8:11]
	s_waitcnt lgkmcnt(3)
	v_mfma_f32_16x16x32_f16 v[62:65], v[144:147], v[160:163], v[62:65]
	v_mfma_f32_16x16x32_f16 v[58:61], v[152:155], v[160:163], v[58:61]
	s_waitcnt lgkmcnt(2)
	v_mfma_f32_16x16x32_f16 v[46:49], v[144:147], v[168:171], v[46:49]
	v_mfma_f32_16x16x32_f16 v[42:45], v[152:155], v[168:171], v[42:45]
	s_waitcnt lgkmcnt(1)
	v_mfma_f32_16x16x32_f16 v[28:31], v[144:147], v[176:179], v[28:31]
	v_mfma_f32_16x16x32_f16 v[24:27], v[152:155], v[176:179], v[24:27]
	s_waitcnt lgkmcnt(0)
	v_mfma_f32_16x16x32_f16 v[12:15], v[144:147], v[184:187], v[12:15]
	v_mfma_f32_16x16x32_f16 v[8:11], v[152:155], v[184:187], v[8:11]
	s_setprio 0
	s_barrier
	s_add_u32 s14, s18, 0x40000
	s_addc_u32 s15, s19, 0
	s_add_i32 s39, s40, s26
	v_lshl_add_u64 v[140:141], s[14:15], 0, v[32:33]
	s_mov_b32 m0, s39
	s_nop 0
	global_load_lds_dwordx4 v[140:141], off
	v_lshl_add_u64 v[140:141], s[14:15], 0, v[130:131]
	s_add_i32 m0, s39, 0x2000
	s_nop 0
	global_load_lds_dwordx4 v[140:141], off
	s_waitcnt vmcnt(6)
	s_barrier
	s_setprio 1
	v_mfma_f32_16x16x32_f16 v[54:57], v[188:191], v[156:159], v[54:57]
	v_mfma_f32_16x16x32_f16 v[50:53], v[196:199], v[156:159], v[50:53]
	v_mfma_f32_16x16x32_f16 v[38:41], v[188:191], v[164:167], v[38:41]
	v_mfma_f32_16x16x32_f16 v[34:37], v[196:199], v[164:167], v[34:37]
	v_mfma_f32_16x16x32_f16 v[20:23], v[188:191], v[172:175], v[20:23]
	v_mfma_f32_16x16x32_f16 v[16:19], v[196:199], v[172:175], v[16:19]
	v_mfma_f32_16x16x32_f16 v[4:7], v[188:191], v[180:183], v[4:7]
	v_mfma_f32_16x16x32_f16 v[0:3], v[196:199], v[180:183], v[0:3]
	v_mfma_f32_16x16x32_f16 v[54:57], v[192:195], v[160:163], v[54:57]
	v_mfma_f32_16x16x32_f16 v[50:53], v[200:203], v[160:163], v[50:53]
	v_mfma_f32_16x16x32_f16 v[38:41], v[192:195], v[168:171], v[38:41]
	v_mfma_f32_16x16x32_f16 v[34:37], v[200:203], v[168:171], v[34:37]
	v_mfma_f32_16x16x32_f16 v[20:23], v[192:195], v[176:179], v[20:23]
	v_mfma_f32_16x16x32_f16 v[16:19], v[200:203], v[176:179], v[16:19]
	v_mfma_f32_16x16x32_f16 v[4:7], v[192:195], v[184:187], v[4:7]
	v_mfma_f32_16x16x32_f16 v[0:3], v[200:203], v[184:187], v[0:3]
	s_setprio 0
	s_barrier
	s_add_i32 s39, 0, 0x18000
	v_add_u32_e32 v152, s39, v137
	ds_read_b128 v[140:143], v152
	ds_read_b128 v[148:151], v152 offset:2048
	ds_read_b128 v[144:147], v152 offset:1024
	ds_read_b128 v[152:155], v152 offset:3072
	s_add_u32 s14, s20, 0x40000
	s_addc_u32 s15, s21, 0
	s_mov_b32 m0, s28
	v_lshl_add_u64 v[188:189], s[14:15], 0, v[32:33]
	ds_read_b128 v[156:159], v139 offset:32768
	ds_read_b128 v[164:167], v139 offset:34816
	ds_read_b128 v[172:175], v139 offset:36864
	ds_read_b128 v[180:183], v139 offset:38912
	ds_read_b128 v[160:163], v139 offset:33792
	ds_read_b128 v[168:171], v139 offset:35840
	ds_read_b128 v[176:179], v139 offset:37888
	ds_read_b128 v[184:187], v139 offset:39936
	global_load_lds_dwordx4 v[188:189], off
	v_lshl_add_u64 v[188:189], s[14:15], 0, v[130:131]
	s_mov_b32 m0, s29
	s_nop 0
	global_load_lds_dwordx4 v[188:189], off
	s_waitcnt lgkmcnt(8)
	s_barrier
	s_waitcnt lgkmcnt(7)
	s_setprio 1
	v_mfma_f32_16x16x32_f16 v[126:129], v[140:143], v[156:159], v[126:129]
	v_mfma_f32_16x16x32_f16 v[122:125], v[148:151], v[156:159], v[122:125]
	s_waitcnt lgkmcnt(6)
	v_mfma_f32_16x16x32_f16 v[110:113], v[140:143], v[164:167], v[110:113]
	v_mfma_f32_16x16x32_f16 v[106:109], v[148:151], v[164:167], v[106:109]
	s_waitcnt lgkmcnt(5)
	v_mfma_f32_16x16x32_f16 v[94:97], v[140:143], v[172:175], v[94:97]
	v_mfma_f32_16x16x32_f16 v[90:93], v[148:151], v[172:175], v[90:93]
	s_waitcnt lgkmcnt(4)
	v_mfma_f32_16x16x32_f16 v[78:81], v[140:143], v[180:183], v[78:81]
	v_mfma_f32_16x16x32_f16 v[74:77], v[148:151], v[180:183], v[74:77]
	s_waitcnt lgkmcnt(3)
	v_mfma_f32_16x16x32_f16 v[126:129], v[144:147], v[160:163], v[126:129]
	v_mfma_f32_16x16x32_f16 v[122:125], v[152:155], v[160:163], v[122:125]
	s_waitcnt lgkmcnt(2)
	v_mfma_f32_16x16x32_f16 v[110:113], v[144:147], v[168:171], v[110:113]
	v_mfma_f32_16x16x32_f16 v[106:109], v[152:155], v[168:171], v[106:109]
	s_waitcnt lgkmcnt(1)
	v_mfma_f32_16x16x32_f16 v[94:97], v[144:147], v[176:179], v[94:97]
	v_mfma_f32_16x16x32_f16 v[90:93], v[152:155], v[176:179], v[90:93]
	s_waitcnt lgkmcnt(0)
	v_mfma_f32_16x16x32_f16 v[78:81], v[144:147], v[184:187], v[78:81]
	v_mfma_f32_16x16x32_f16 v[74:77], v[152:155], v[184:187], v[74:77]
	s_setprio 0
	s_barrier
	s_add_i32 s20, 0, 0x1c000
	s_add_i32 s14, s39, s26
	v_add_u32_e32 v200, s20, v137
	v_lshl_add_u64 v[204:205], v[204:205], 0, s[84:85]
	s_mov_b32 m0, s14
	ds_read_b128 v[188:191], v200
	ds_read_b128 v[196:199], v200 offset:2048
	ds_read_b128 v[192:195], v200 offset:1024
	ds_read_b128 v[200:203], v200 offset:3072
	global_load_lds_dwordx4 v[204:205], off
	v_lshl_add_u64 v[204:205], v[206:207], 0, s[84:85]
	s_add_i32 m0, s14, 0x2000
	s_nop 0
	global_load_lds_dwordx4 v[204:205], off
	s_barrier
	s_waitcnt lgkmcnt(2)
	s_setprio 1
	v_mfma_f32_16x16x32_f16 v[118:121], v[188:191], v[156:159], v[118:121]
	v_mfma_f32_16x16x32_f16 v[114:117], v[196:199], v[156:159], v[114:117]
	v_mfma_f32_16x16x32_f16 v[102:105], v[188:191], v[164:167], v[102:105]
	v_mfma_f32_16x16x32_f16 v[98:101], v[196:199], v[164:167], v[98:101]
	v_mfma_f32_16x16x32_f16 v[86:89], v[188:191], v[172:175], v[86:89]
	v_mfma_f32_16x16x32_f16 v[82:85], v[196:199], v[172:175], v[82:85]
	v_mfma_f32_16x16x32_f16 v[70:73], v[188:191], v[180:183], v[70:73]
	v_mfma_f32_16x16x32_f16 v[66:69], v[196:199], v[180:183], v[66:69]
	s_waitcnt lgkmcnt(0)
	v_mfma_f32_16x16x32_f16 v[118:121], v[192:195], v[160:163], v[118:121]
	v_mfma_f32_16x16x32_f16 v[114:117], v[200:203], v[160:163], v[114:117]
	v_mfma_f32_16x16x32_f16 v[102:105], v[192:195], v[168:171], v[102:105]
	v_mfma_f32_16x16x32_f16 v[98:101], v[200:203], v[168:171], v[98:101]
	v_mfma_f32_16x16x32_f16 v[86:89], v[192:195], v[176:179], v[86:89]
	v_mfma_f32_16x16x32_f16 v[82:85], v[200:203], v[176:179], v[82:85]
	v_mfma_f32_16x16x32_f16 v[70:73], v[192:195], v[184:187], v[70:73]
	v_mfma_f32_16x16x32_f16 v[66:69], v[200:203], v[184:187], v[66:69]
	s_setprio 0
	s_barrier
	s_mov_b32 m0, s30
	v_lshl_add_u64 v[204:205], v[208:209], 0, s[84:85]
	ds_read_b128 v[156:159], v139 offset:49152
	ds_read_b128 v[164:167], v139 offset:51200
	ds_read_b128 v[172:175], v139 offset:53248
	ds_read_b128 v[180:183], v139 offset:55296
	ds_read_b128 v[160:163], v139 offset:50176
	ds_read_b128 v[168:171], v139 offset:52224
	ds_read_b128 v[176:179], v139 offset:54272
	ds_read_b128 v[184:187], v139 offset:56320
	global_load_lds_dwordx4 v[204:205], off
	v_lshl_add_u64 v[204:205], v[210:211], 0, s[84:85]
	s_mov_b32 m0, s31
	s_nop 0
	global_load_lds_dwordx4 v[204:205], off
	s_barrier
	s_waitcnt lgkmcnt(7)
	s_setprio 1
	v_mfma_f32_16x16x32_f16 v[62:65], v[140:143], v[156:159], v[62:65]
	v_mfma_f32_16x16x32_f16 v[58:61], v[148:151], v[156:159], v[58:61]
	s_waitcnt lgkmcnt(6)
	v_mfma_f32_16x16x32_f16 v[46:49], v[140:143], v[164:167], v[46:49]
	v_mfma_f32_16x16x32_f16 v[42:45], v[148:151], v[164:167], v[42:45]
	s_waitcnt lgkmcnt(5)
	v_mfma_f32_16x16x32_f16 v[28:31], v[140:143], v[172:175], v[28:31]
	v_mfma_f32_16x16x32_f16 v[24:27], v[148:151], v[172:175], v[24:27]
	s_waitcnt lgkmcnt(4)
	v_mfma_f32_16x16x32_f16 v[12:15], v[140:143], v[180:183], v[12:15]
	v_mfma_f32_16x16x32_f16 v[8:11], v[148:151], v[180:183], v[8:11]
	s_waitcnt lgkmcnt(3)
	v_mfma_f32_16x16x32_f16 v[62:65], v[144:147], v[160:163], v[62:65]
	v_mfma_f32_16x16x32_f16 v[58:61], v[152:155], v[160:163], v[58:61]
	s_waitcnt lgkmcnt(2)
	v_mfma_f32_16x16x32_f16 v[46:49], v[144:147], v[168:171], v[46:49]
	v_mfma_f32_16x16x32_f16 v[42:45], v[152:155], v[168:171], v[42:45]
	s_waitcnt lgkmcnt(1)
	v_mfma_f32_16x16x32_f16 v[28:31], v[144:147], v[176:179], v[28:31]
	v_mfma_f32_16x16x32_f16 v[24:27], v[152:155], v[176:179], v[24:27]
	s_waitcnt lgkmcnt(0)
	v_mfma_f32_16x16x32_f16 v[12:15], v[144:147], v[184:187], v[12:15]
	v_mfma_f32_16x16x32_f16 v[8:11], v[152:155], v[184:187], v[8:11]
	s_setprio 0
	s_barrier
	s_add_u32 s14, s18, 0x40080
	s_addc_u32 s15, s19, 0
	s_add_i32 s18, s20, s26
	v_lshl_add_u64 v[140:141], s[14:15], 0, v[32:33]
	s_mov_b32 m0, s18
	s_nop 0
	global_load_lds_dwordx4 v[140:141], off
	v_lshl_add_u64 v[140:141], s[14:15], 0, v[130:131]
	s_add_i32 m0, s18, 0x2000
	s_nop 0
	global_load_lds_dwordx4 v[140:141], off
	s_waitcnt vmcnt(6)
	s_barrier
	s_setprio 1
	v_mfma_f32_16x16x32_f16 v[54:57], v[188:191], v[156:159], v[54:57]
	v_mfma_f32_16x16x32_f16 v[50:53], v[196:199], v[156:159], v[50:53]
	v_mfma_f32_16x16x32_f16 v[38:41], v[188:191], v[164:167], v[38:41]
	v_mfma_f32_16x16x32_f16 v[34:37], v[196:199], v[164:167], v[34:37]
	v_mfma_f32_16x16x32_f16 v[20:23], v[188:191], v[172:175], v[20:23]
	v_mfma_f32_16x16x32_f16 v[16:19], v[196:199], v[172:175], v[16:19]
	v_mfma_f32_16x16x32_f16 v[4:7], v[188:191], v[180:183], v[4:7]
	v_mfma_f32_16x16x32_f16 v[0:3], v[196:199], v[180:183], v[0:3]
	v_mfma_f32_16x16x32_f16 v[54:57], v[192:195], v[160:163], v[54:57]
	v_mfma_f32_16x16x32_f16 v[50:53], v[200:203], v[160:163], v[50:53]
	v_mfma_f32_16x16x32_f16 v[38:41], v[192:195], v[168:171], v[38:41]
	v_mfma_f32_16x16x32_f16 v[34:37], v[200:203], v[168:171], v[34:37]
	v_mfma_f32_16x16x32_f16 v[20:23], v[192:195], v[176:179], v[20:23]
	v_mfma_f32_16x16x32_f16 v[16:19], v[200:203], v[176:179], v[16:19]
	v_mfma_f32_16x16x32_f16 v[4:7], v[192:195], v[184:187], v[4:7]
	v_mfma_f32_16x16x32_f16 v[0:3], v[200:203], v[184:187], v[0:3]
	s_setprio 0
	s_barrier
	s_add_i32 s38, s38, 2
	s_add_u32 s3, s3, 0x100
	s_addc_u32 s37, s37, 0
	s_cmp_gt_u32 s38, 13
	s_mov_b64 s[14:15], s[16:17]
	s_cbranch_scc0 .LBB0_1276
	v_mul_f32_e32 v144, 0xbfb8aa3b, v127
	v_mul_f32_e32 v141, 0xbfb8aa3b, v126
	v_exp_f32_e32 v145, v144
	v_mul_f32_e32 v144, 0xbfb8aa3b, v128
	v_exp_f32_e32 v141, v141
	v_exp_f32_e32 v146, v144
	v_mul_f32_e32 v144, 0xbfb8aa3b, v129
	v_exp_f32_e32 v147, v144
	v_mul_f32_e32 v144, 0xbfb8aa3b, v122
	v_exp_f32_e32 v148, v144
	v_mul_f32_e32 v144, 0xbfb8aa3b, v123
	v_exp_f32_e32 v149, v144
	v_mul_f32_e32 v144, 0xbfb8aa3b, v124
	v_exp_f32_e32 v150, v144
	v_mul_f32_e32 v144, 0xbfb8aa3b, v125
	v_add_f32_e32 v141, 1.0, v141
	v_exp_f32_e32 v151, v144
	v_rcp_f32_e32 v144, v141
	v_add_f32_e32 v141, 1.0, v145
	v_rcp_f32_e32 v145, v141
	v_add_f32_e32 v141, 1.0, v146
	v_rcp_f32_e32 v146, v141
	v_add_f32_e32 v141, 1.0, v147
	v_rcp_f32_e32 v147, v141
	v_add_f32_e32 v141, 1.0, v148
	v_rcp_f32_e32 v148, v141
	v_add_f32_e32 v141, 1.0, v149
	v_rcp_f32_e32 v149, v141
	v_add_f32_e32 v141, 1.0, v150
	v_rcp_f32_e32 v150, v141
	v_add_f32_e32 v141, 1.0, v151
	v_pk_mul_f32 v[126:127], v[126:127], v[144:145]
	v_rcp_f32_e32 v151, v141
	v_pk_mul_f32 v[118:119], v[126:127], v[118:119]
	v_pk_mul_f32 v[126:127], v[128:129], v[146:147]
	v_cvt_pk_f16_f32 v118, v118, v119
	v_pk_mul_f32 v[120:121], v[126:127], v[120:121]
	v_lshl_or_b32 v142, s36, 7, v138
	v_cvt_pk_f16_f32 v119, v120, v121
	v_pk_mul_f32 v[120:121], v[122:123], v[148:149]
	v_lshl_add_u32 v140, s8, 8, v136
	v_pk_mul_f32 v[114:115], v[120:121], v[114:115]
	v_ashrrev_i32_e32 v143, 31, v142
	v_cvt_pk_f16_f32 v120, v114, v115
	v_pk_mul_f32 v[114:115], v[124:125], v[150:151]
	s_movk_i32 s3, 0x1600
	v_pk_mul_f32 v[114:115], v[114:115], v[116:117]
	v_lshlrev_b64 v[116:117], 1, v[142:143]
	v_cvt_pk_f16_f32 v121, v114, v115
	v_mov_b64_e32 v[114:115], s[92:93]
	v_mad_i64_i32 v[122:123], s[10:11], v140, s3, v[114:115]
	v_lshl_add_u64 v[122:123], v[122:123], 0, v[116:117]
	global_store_dwordx4 v[122:123], v[118:121], off
	v_mul_f32_e32 v122, 0xbfb8aa3b, v106
	v_mul_f32_e32 v123, 0xbfb8aa3b, v107
	v_mul_f32_e32 v118, 0xbfb8aa3b, v110
	v_mul_f32_e32 v119, 0xbfb8aa3b, v111
	v_exp_f32_e32 v118, v118
	v_exp_f32_e32 v119, v119
	v_mul_f32_e32 v120, 0xbfb8aa3b, v112
	v_mul_f32_e32 v121, 0xbfb8aa3b, v113
	v_exp_f32_e32 v120, v120
	v_exp_f32_e32 v121, v121
	v_exp_f32_e32 v122, v122
	v_exp_f32_e32 v123, v123
	v_mul_f32_e32 v124, 0xbfb8aa3b, v108
	v_mul_f32_e32 v125, 0xbfb8aa3b, v109
	v_add_f32_e32 v118, 1.0, v118
	v_add_f32_e32 v119, 1.0, v119
	v_exp_f32_e32 v124, v124
	v_exp_f32_e32 v125, v125
	v_rcp_f32_e32 v118, v118
	v_rcp_f32_e32 v119, v119
	v_add_f32_e32 v120, 1.0, v120
	v_add_f32_e32 v121, 1.0, v121
	v_rcp_f32_e32 v120, v120
	v_rcp_f32_e32 v121, v121
	v_add_f32_e32 v122, 1.0, v122
	v_add_f32_e32 v123, 1.0, v123
	v_rcp_f32_e32 v122, v122
	v_rcp_f32_e32 v123, v123
	v_add_f32_e32 v124, 1.0, v124
	v_add_f32_e32 v125, 1.0, v125
	v_pk_mul_f32 v[110:111], v[110:111], v[118:119]
	v_rcp_f32_e32 v124, v124
	v_rcp_f32_e32 v125, v125
	v_pk_mul_f32 v[102:103], v[110:111], v[102:103]
	v_pk_mul_f32 v[110:111], v[112:113], v[120:121]
	v_cvt_pk_f16_f32 v102, v102, v103
	v_pk_mul_f32 v[104:105], v[110:111], v[104:105]
	s_and_b64 vcc, exec, s[0:1]
	v_cvt_pk_f16_f32 v103, v104, v105
	v_pk_mul_f32 v[104:105], v[106:107], v[122:123]
	s_mov_b32 s36, s35
	v_pk_mul_f32 v[98:99], v[104:105], v[98:99]
	s_mov_b32 s8, s2
	v_cvt_pk_f16_f32 v104, v98, v99
	v_pk_mul_f32 v[98:99], v[108:109], v[124:125]
	s_mov_b64 s[16:17], s[6:7]
	v_pk_mul_f32 v[98:99], v[98:99], v[100:101]
	v_mul_f32_e32 v100, 0xbfb8aa3b, v96
	v_cvt_pk_f16_f32 v105, v98, v99
	v_or_b32_e32 v98, 16, v140
	v_mad_i64_i32 v[98:99], s[10:11], v98, s3, v[114:115]
	v_lshl_add_u64 v[98:99], v[98:99], 0, v[116:117]
	global_store_dwordx4 v[98:99], v[102:105], off
	v_mul_f32_e32 v98, 0xbfb8aa3b, v94
	v_mul_f32_e32 v99, 0xbfb8aa3b, v95
	v_exp_f32_e32 v98, v98
	v_exp_f32_e32 v99, v99
	v_mul_f32_e32 v101, 0xbfb8aa3b, v97
	v_exp_f32_e32 v100, v100
	v_exp_f32_e32 v101, v101
	v_mul_f32_e32 v102, 0xbfb8aa3b, v90
	v_mul_f32_e32 v103, 0xbfb8aa3b, v91
	v_exp_f32_e32 v102, v102
	v_exp_f32_e32 v103, v103
	v_mul_f32_e32 v104, 0xbfb8aa3b, v92
	v_mul_f32_e32 v105, 0xbfb8aa3b, v93
	v_add_f32_e32 v98, 1.0, v98
	v_add_f32_e32 v99, 1.0, v99
	v_exp_f32_e32 v104, v104
	v_exp_f32_e32 v105, v105
	v_rcp_f32_e32 v98, v98
	v_rcp_f32_e32 v99, v99
	v_add_f32_e32 v100, 1.0, v100
	v_add_f32_e32 v101, 1.0, v101
	v_rcp_f32_e32 v100, v100
	v_rcp_f32_e32 v101, v101
	v_add_f32_e32 v102, 1.0, v102
	v_add_f32_e32 v103, 1.0, v103
	v_rcp_f32_e32 v102, v102
	v_rcp_f32_e32 v103, v103
	v_add_f32_e32 v104, 1.0, v104
	v_add_f32_e32 v105, 1.0, v105
	v_pk_mul_f32 v[94:95], v[94:95], v[98:99]
	v_rcp_f32_e32 v104, v104
	v_rcp_f32_e32 v105, v105
	v_pk_mul_f32 v[86:87], v[94:95], v[86:87]
	v_pk_mul_f32 v[94:95], v[96:97], v[100:101]
	v_cvt_pk_f16_f32 v86, v86, v87
	v_pk_mul_f32 v[88:89], v[94:95], v[88:89]
	s_mov_b64 s[14:15], s[4:5]
	v_cvt_pk_f16_f32 v87, v88, v89
	v_pk_mul_f32 v[88:89], v[90:91], v[102:103]
	s_nop 0
	v_pk_mul_f32 v[82:83], v[88:89], v[82:83]
	s_nop 0
	v_cvt_pk_f16_f32 v88, v82, v83
	v_pk_mul_f32 v[82:83], v[92:93], v[104:105]
	s_nop 0
	v_pk_mul_f32 v[82:83], v[82:83], v[84:85]
	v_mul_f32_e32 v84, 0xbfb8aa3b, v80
	v_cvt_pk_f16_f32 v89, v82, v83
	v_or_b32_e32 v82, 32, v140
	v_mad_i64_i32 v[82:83], s[10:11], v82, s3, v[114:115]
	v_lshl_add_u64 v[82:83], v[82:83], 0, v[116:117]
	global_store_dwordx4 v[82:83], v[86:89], off
	v_mul_f32_e32 v82, 0xbfb8aa3b, v78
	v_mul_f32_e32 v83, 0xbfb8aa3b, v79
	v_exp_f32_e32 v82, v82
	v_exp_f32_e32 v83, v83
	v_mul_f32_e32 v85, 0xbfb8aa3b, v81
	v_exp_f32_e32 v84, v84
	v_exp_f32_e32 v85, v85
	v_mul_f32_e32 v86, 0xbfb8aa3b, v74
	v_mul_f32_e32 v87, 0xbfb8aa3b, v75
	v_exp_f32_e32 v86, v86
	v_exp_f32_e32 v87, v87
	v_mul_f32_e32 v88, 0xbfb8aa3b, v76
	v_mul_f32_e32 v89, 0xbfb8aa3b, v77
	v_add_f32_e32 v82, 1.0, v82
	v_add_f32_e32 v83, 1.0, v83
	v_exp_f32_e32 v88, v88
	v_exp_f32_e32 v89, v89
	v_rcp_f32_e32 v82, v82
	v_rcp_f32_e32 v83, v83
	v_add_f32_e32 v84, 1.0, v84
	v_add_f32_e32 v85, 1.0, v85
	v_rcp_f32_e32 v84, v84
	v_rcp_f32_e32 v85, v85
	v_add_f32_e32 v86, 1.0, v86
	v_add_f32_e32 v87, 1.0, v87
	v_rcp_f32_e32 v86, v86
	v_rcp_f32_e32 v87, v87
	v_add_f32_e32 v88, 1.0, v88
	v_add_f32_e32 v89, 1.0, v89
	v_pk_mul_f32 v[78:79], v[78:79], v[82:83]
	v_rcp_f32_e32 v88, v88
	v_rcp_f32_e32 v89, v89
	v_pk_mul_f32 v[70:71], v[78:79], v[70:71]
	v_pk_mul_f32 v[78:79], v[80:81], v[84:85]
	v_cvt_pk_f16_f32 v70, v70, v71
	v_pk_mul_f32 v[72:73], v[78:79], v[72:73]
	s_nop 0
	v_cvt_pk_f16_f32 v71, v72, v73
	v_pk_mul_f32 v[72:73], v[74:75], v[86:87]
	v_add_u32_e32 v74, 0x80, v140
	v_pk_mul_f32 v[66:67], v[72:73], v[66:67]
	s_nop 0
	v_cvt_pk_f16_f32 v72, v66, v67
	v_pk_mul_f32 v[66:67], v[76:77], v[88:89]
	s_nop 0
	v_pk_mul_f32 v[66:67], v[66:67], v[68:69]
	v_mul_f32_e32 v68, 0xbfb8aa3b, v64
	v_cvt_pk_f16_f32 v73, v66, v67
	v_or_b32_e32 v66, 48, v140
	v_mad_i64_i32 v[66:67], s[10:11], v66, s3, v[114:115]
	v_lshl_add_u64 v[66:67], v[66:67], 0, v[116:117]
	global_store_dwordx4 v[66:67], v[70:73], off
	v_mul_f32_e32 v66, 0xbfb8aa3b, v62
	v_mul_f32_e32 v67, 0xbfb8aa3b, v63
	v_exp_f32_e32 v66, v66
	v_exp_f32_e32 v67, v67
	v_mul_f32_e32 v69, 0xbfb8aa3b, v65
	v_exp_f32_e32 v68, v68
	v_exp_f32_e32 v69, v69
	v_mul_f32_e32 v70, 0xbfb8aa3b, v58
	v_mul_f32_e32 v71, 0xbfb8aa3b, v59
	v_exp_f32_e32 v70, v70
	v_exp_f32_e32 v71, v71
	v_mul_f32_e32 v72, 0xbfb8aa3b, v60
	v_mul_f32_e32 v73, 0xbfb8aa3b, v61
	v_add_f32_e32 v66, 1.0, v66
	v_add_f32_e32 v67, 1.0, v67
	v_exp_f32_e32 v72, v72
	v_exp_f32_e32 v73, v73
	v_rcp_f32_e32 v66, v66
	v_rcp_f32_e32 v67, v67
	v_add_f32_e32 v68, 1.0, v68
	v_add_f32_e32 v69, 1.0, v69
	v_rcp_f32_e32 v68, v68
	v_rcp_f32_e32 v69, v69
	v_add_f32_e32 v70, 1.0, v70
	v_add_f32_e32 v71, 1.0, v71
	v_rcp_f32_e32 v70, v70
	v_rcp_f32_e32 v71, v71
	v_add_f32_e32 v72, 1.0, v72
	v_add_f32_e32 v73, 1.0, v73
	v_pk_mul_f32 v[62:63], v[62:63], v[66:67]
	v_rcp_f32_e32 v72, v72
	v_rcp_f32_e32 v73, v73
	v_pk_mul_f32 v[54:55], v[62:63], v[54:55]
	v_pk_mul_f32 v[62:63], v[64:65], v[68:69]
	v_cvt_pk_f16_f32 v54, v54, v55
	v_pk_mul_f32 v[56:57], v[62:63], v[56:57]
	s_nop 0
	v_cvt_pk_f16_f32 v55, v56, v57
	v_pk_mul_f32 v[56:57], v[58:59], v[70:71]
	s_nop 0
	v_pk_mul_f32 v[50:51], v[56:57], v[50:51]
	s_nop 0
	v_cvt_pk_f16_f32 v56, v50, v51
	v_pk_mul_f32 v[50:51], v[60:61], v[72:73]
	s_nop 0
	v_pk_mul_f32 v[50:51], v[50:51], v[52:53]
	v_mul_f32_e32 v52, 0xbfb8aa3b, v48
	v_cvt_pk_f16_f32 v57, v50, v51
	v_mad_i64_i32 v[50:51], s[10:11], v74, s3, v[114:115]
	v_lshl_add_u64 v[50:51], v[50:51], 0, v[116:117]
	global_store_dwordx4 v[50:51], v[54:57], off
	v_mul_f32_e32 v50, 0xbfb8aa3b, v46
	v_mul_f32_e32 v51, 0xbfb8aa3b, v47
	v_exp_f32_e32 v50, v50
	v_exp_f32_e32 v51, v51
	v_mul_f32_e32 v53, 0xbfb8aa3b, v49
	v_exp_f32_e32 v52, v52
	v_exp_f32_e32 v53, v53
	v_mul_f32_e32 v54, 0xbfb8aa3b, v42
	v_mul_f32_e32 v55, 0xbfb8aa3b, v43
	v_exp_f32_e32 v54, v54
	v_exp_f32_e32 v55, v55
	v_mul_f32_e32 v56, 0xbfb8aa3b, v44
	v_mul_f32_e32 v57, 0xbfb8aa3b, v45
	v_add_f32_e32 v50, 1.0, v50
	v_add_f32_e32 v51, 1.0, v51
	v_exp_f32_e32 v56, v56
	v_exp_f32_e32 v57, v57
	v_rcp_f32_e32 v50, v50
	v_rcp_f32_e32 v51, v51
	v_add_f32_e32 v52, 1.0, v52
	v_add_f32_e32 v53, 1.0, v53
	v_rcp_f32_e32 v52, v52
	v_rcp_f32_e32 v53, v53
	v_add_f32_e32 v54, 1.0, v54
	v_add_f32_e32 v55, 1.0, v55
	v_rcp_f32_e32 v54, v54
	v_rcp_f32_e32 v55, v55
	v_add_f32_e32 v56, 1.0, v56
	v_add_f32_e32 v57, 1.0, v57
	v_pk_mul_f32 v[46:47], v[46:47], v[50:51]
	v_rcp_f32_e32 v56, v56
	v_rcp_f32_e32 v57, v57
	v_pk_mul_f32 v[38:39], v[46:47], v[38:39]
	v_pk_mul_f32 v[46:47], v[48:49], v[52:53]
	v_cvt_pk_f16_f32 v38, v38, v39
	v_pk_mul_f32 v[40:41], v[46:47], v[40:41]
	s_nop 0
	v_cvt_pk_f16_f32 v39, v40, v41
	v_pk_mul_f32 v[40:41], v[42:43], v[54:55]
	s_nop 0
	v_pk_mul_f32 v[34:35], v[40:41], v[34:35]
	s_nop 0
	v_cvt_pk_f16_f32 v40, v34, v35
	v_pk_mul_f32 v[34:35], v[44:45], v[56:57]
	s_nop 0
	v_pk_mul_f32 v[34:35], v[34:35], v[36:37]
	v_mul_f32_e32 v36, 0xbfb8aa3b, v30
	v_cvt_pk_f16_f32 v41, v34, v35
	v_add_u32_e32 v34, 0x90, v140
	v_mad_i64_i32 v[34:35], s[10:11], v34, s3, v[114:115]
	v_lshl_add_u64 v[34:35], v[34:35], 0, v[116:117]
	global_store_dwordx4 v[34:35], v[38:41], off
	v_mul_f32_e32 v34, 0xbfb8aa3b, v28
	v_mul_f32_e32 v35, 0xbfb8aa3b, v29
	v_exp_f32_e32 v34, v34
	v_exp_f32_e32 v35, v35
	v_mul_f32_e32 v37, 0xbfb8aa3b, v31
	v_exp_f32_e32 v36, v36
	v_exp_f32_e32 v37, v37
	v_mul_f32_e32 v38, 0xbfb8aa3b, v24
	v_mul_f32_e32 v39, 0xbfb8aa3b, v25
	v_exp_f32_e32 v38, v38
	v_exp_f32_e32 v39, v39
	v_mul_f32_e32 v40, 0xbfb8aa3b, v26
	v_mul_f32_e32 v41, 0xbfb8aa3b, v27
	v_add_f32_e32 v34, 1.0, v34
	v_add_f32_e32 v35, 1.0, v35
	v_exp_f32_e32 v40, v40
	v_exp_f32_e32 v41, v41
	v_rcp_f32_e32 v34, v34
	v_rcp_f32_e32 v35, v35
	v_add_f32_e32 v36, 1.0, v36
	v_add_f32_e32 v37, 1.0, v37
	v_rcp_f32_e32 v36, v36
	v_rcp_f32_e32 v37, v37
	v_add_f32_e32 v38, 1.0, v38
	v_add_f32_e32 v39, 1.0, v39
	v_rcp_f32_e32 v38, v38
	v_rcp_f32_e32 v39, v39
	v_add_f32_e32 v40, 1.0, v40
	v_add_f32_e32 v41, 1.0, v41
	v_pk_mul_f32 v[28:29], v[28:29], v[34:35]
	v_rcp_f32_e32 v40, v40
	v_rcp_f32_e32 v41, v41
	v_pk_mul_f32 v[20:21], v[28:29], v[20:21]
	v_pk_mul_f32 v[28:29], v[30:31], v[36:37]
	v_cvt_pk_f16_f32 v20, v20, v21
	v_pk_mul_f32 v[22:23], v[28:29], v[22:23]
	s_nop 0
	v_cvt_pk_f16_f32 v21, v22, v23
	v_pk_mul_f32 v[22:23], v[24:25], v[38:39]
	s_nop 0
	v_pk_mul_f32 v[16:17], v[22:23], v[16:17]
	s_nop 0
	v_cvt_pk_f16_f32 v22, v16, v17
	v_pk_mul_f32 v[16:17], v[26:27], v[40:41]
	s_nop 0
	v_pk_mul_f32 v[16:17], v[16:17], v[18:19]
	v_mul_f32_e32 v18, 0xbfb8aa3b, v14
	v_cvt_pk_f16_f32 v23, v16, v17
	v_add_u32_e32 v16, 0xa0, v140
	v_mad_i64_i32 v[16:17], s[10:11], v16, s3, v[114:115]
	v_lshl_add_u64 v[16:17], v[16:17], 0, v[116:117]
	global_store_dwordx4 v[16:17], v[20:23], off
	v_mul_f32_e32 v16, 0xbfb8aa3b, v12
	v_mul_f32_e32 v17, 0xbfb8aa3b, v13
	v_exp_f32_e32 v16, v16
	v_exp_f32_e32 v17, v17
	v_mul_f32_e32 v19, 0xbfb8aa3b, v15
	v_exp_f32_e32 v18, v18
	v_exp_f32_e32 v19, v19
	v_mul_f32_e32 v20, 0xbfb8aa3b, v8
	v_mul_f32_e32 v21, 0xbfb8aa3b, v9
	v_exp_f32_e32 v20, v20
	v_exp_f32_e32 v21, v21
	v_mul_f32_e32 v22, 0xbfb8aa3b, v10
	v_mul_f32_e32 v23, 0xbfb8aa3b, v11
	v_add_f32_e32 v16, 1.0, v16
	v_add_f32_e32 v17, 1.0, v17
	v_exp_f32_e32 v22, v22
	v_exp_f32_e32 v23, v23
	v_rcp_f32_e32 v16, v16
	v_rcp_f32_e32 v17, v17
	v_add_f32_e32 v18, 1.0, v18
	v_add_f32_e32 v19, 1.0, v19
	v_rcp_f32_e32 v18, v18
	v_rcp_f32_e32 v19, v19
	v_add_f32_e32 v20, 1.0, v20
	v_add_f32_e32 v21, 1.0, v21
	v_rcp_f32_e32 v20, v20
	v_rcp_f32_e32 v21, v21
	v_add_f32_e32 v22, 1.0, v22
	v_add_f32_e32 v23, 1.0, v23
	v_pk_mul_f32 v[12:13], v[12:13], v[16:17]
	v_rcp_f32_e32 v22, v22
	v_rcp_f32_e32 v23, v23
	v_pk_mul_f32 v[4:5], v[12:13], v[4:5]
	v_pk_mul_f32 v[12:13], v[14:15], v[18:19]
	v_cvt_pk_f16_f32 v4, v4, v5
	v_pk_mul_f32 v[6:7], v[12:13], v[6:7]
	s_nop 0
	v_cvt_pk_f16_f32 v5, v6, v7
	v_pk_mul_f32 v[6:7], v[8:9], v[20:21]
	s_nop 0
	v_pk_mul_f32 v[0:1], v[6:7], v[0:1]
	s_nop 0
	v_cvt_pk_f16_f32 v6, v0, v1
	v_pk_mul_f32 v[0:1], v[10:11], v[22:23]
	s_nop 0
	v_pk_mul_f32 v[0:1], v[0:1], v[2:3]
	s_nop 0
	v_cvt_pk_f16_f32 v7, v0, v1
	v_add_u32_e32 v0, 0xb0, v140
	v_mad_i64_i32 v[0:1], s[10:11], v0, s3, v[114:115]
	v_lshl_add_u64 v[0:1], v[0:1], 0, v[116:117]
	global_store_dwordx4 v[0:1], v[4:7], off
	s_cmp_lg_u32 s34, 1
	s_cbranch_scc1 .Lups_skip
	s_and_b32 s0, s91, 63
	s_cmp_gt_u32 s0, 5
	s_cbranch_scc1 .Lups_skip
	s_cmp_gt_u32 s91, 196
	s_cbranch_scc1 .Lups_skip
	s_waitcnt vmcnt(0)
	s_barrier
	v_readlane_b32 s0, v251, 36
	s_cmp_lg_u32 s0, 0
	s_cbranch_scc1 .Lups_skip
	buffer_wbl2 sc1
	s_waitcnt vmcnt(0)
	v_readlane_b32 s2, v255, 45
	v_readlane_b32 s3, v254, 25
	s_lshl_b32 s2, s2, 1
	s_cmp_eq_u32 s3, 0
	s_cselect_b32 s3, 1, 0
	s_add_i32 s2, s2, s3
	s_lshl_b32 s2, s2, 2
	s_add_i32 s2, s2, 14016
	v_readlane_b32 s0, v251, 32
	v_readlane_b32 s1, v251, 33
	s_add_u32 s0, s0, s2
	s_addc_u32 s1, s1, 0
	s_mov_b64 s[2:3], exec
	s_mov_b64 exec, 1
	global_atomic_add v33, v248, s[0:1]
	s_mov_b64 exec, s[2:3]

.LBB0_1365:
	s_add_i32 s46, s14, 2
	s_add_u32 s12, s10, 0x100
	s_addc_u32 s13, s11, 0
	s_add_i32 s47, 0, 0x10000
	v_add_u32_e32 v134, s47, v230
	ds_read_b128 v[106:109], v134
	ds_read_b128 v[114:117], v134 offset:2048
	ds_read_b128 v[110:113], v134 offset:1024
	ds_read_b128 v[134:137], v134 offset:3072
	s_cmp_eq_u32 s43, s14
	s_cselect_b32 s14, s8, s44
	s_cselect_b32 s17, s7, s13
	s_cselect_b32 s16, s6, s12
	s_cselect_b32 s15, s9, s45
	v_lshl_add_u64 v[178:179], s[10:11], 0, v[184:185]
	s_add_i32 m0, s24, 0xc000
	ds_read_b128 v[138:141], v232
	ds_read_b128 v[154:157], v232 offset:2048
	ds_read_b128 v[162:165], v232 offset:4096
	ds_read_b128 v[170:173], v232 offset:6144
	ds_read_b128 v[150:153], v232 offset:1024
	ds_read_b128 v[158:161], v232 offset:3072
	ds_read_b128 v[166:169], v232 offset:5120
	ds_read_b128 v[174:177], v232 offset:7168
	global_load_lds_dwordx4 v[178:179], off
	v_lshl_add_u64 v[178:179], s[10:11], 0, v[186:187]
	s_add_i32 m0, s24, 0xe000
	s_nop 0
	global_load_lds_dwordx4 v[178:179], off
	s_waitcnt lgkmcnt(8)
	s_barrier
	s_waitcnt lgkmcnt(7)
	s_setprio 1
	v_mfma_f32_16x16x32_f16 v[146:149], v[106:109], v[138:141], v[146:149]
	v_mfma_f32_16x16x32_f16 v[142:145], v[114:117], v[138:141], v[142:145]
	s_waitcnt lgkmcnt(6)
	v_mfma_f32_16x16x32_f16 v[130:133], v[106:109], v[154:157], v[130:133]
	v_mfma_f32_16x16x32_f16 v[122:125], v[114:117], v[154:157], v[122:125]
	s_waitcnt lgkmcnt(5)
	v_mfma_f32_16x16x32_f16 v[94:97], v[106:109], v[162:165], v[94:97]
	v_mfma_f32_16x16x32_f16 v[90:93], v[114:117], v[162:165], v[90:93]
	s_waitcnt lgkmcnt(4)
	v_mfma_f32_16x16x32_f16 v[78:81], v[106:109], v[170:173], v[78:81]
	v_mfma_f32_16x16x32_f16 v[74:77], v[114:117], v[170:173], v[74:77]
	s_waitcnt lgkmcnt(3)
	v_mfma_f32_16x16x32_f16 v[146:149], v[110:113], v[150:153], v[146:149]
	v_mfma_f32_16x16x32_f16 v[142:145], v[134:137], v[150:153], v[142:145]
	s_waitcnt lgkmcnt(2)
	v_mfma_f32_16x16x32_f16 v[130:133], v[110:113], v[158:161], v[130:133]
	v_mfma_f32_16x16x32_f16 v[122:125], v[134:137], v[158:161], v[122:125]
	s_waitcnt lgkmcnt(1)
	v_mfma_f32_16x16x32_f16 v[94:97], v[110:113], v[166:169], v[94:97]
	v_mfma_f32_16x16x32_f16 v[90:93], v[134:137], v[166:169], v[90:93]
	s_waitcnt lgkmcnt(0)
	v_mfma_f32_16x16x32_f16 v[78:81], v[110:113], v[174:177], v[78:81]
	v_mfma_f32_16x16x32_f16 v[74:77], v[134:137], v[174:177], v[74:77]
	s_setprio 0
	s_barrier
	s_add_i32 s48, 0, 0x14000
	s_add_i32 s10, s47, s23
	v_add_u32_e32 v196, s48, v230
	v_lshl_add_u64 v[200:201], s[14:15], 0, v[32:33]
	s_mov_b32 m0, s10
	ds_read_b128 v[178:181], v196
	ds_read_b128 v[192:195], v196 offset:2048
	ds_read_b128 v[188:191], v196 offset:1024
	ds_read_b128 v[196:199], v196 offset:3072
	global_load_lds_dwordx4 v[200:201], off
	v_lshl_add_u64 v[202:203], s[14:15], 0, v[182:183]
	s_add_i32 m0, s10, 0x2000
	s_nop 0
	global_load_lds_dwordx4 v[202:203], off
	s_barrier
	s_waitcnt lgkmcnt(2)
	s_setprio 1
	v_mfma_f32_16x16x32_f16 v[126:129], v[178:181], v[138:141], v[126:129]
	v_mfma_f32_16x16x32_f16 v[118:121], v[192:195], v[138:141], v[118:121]
	v_mfma_f32_16x16x32_f16 v[102:105], v[178:181], v[154:157], v[102:105]
	v_mfma_f32_16x16x32_f16 v[98:101], v[192:195], v[154:157], v[98:101]
	v_mfma_f32_16x16x32_f16 v[86:89], v[178:181], v[162:165], v[86:89]
	v_mfma_f32_16x16x32_f16 v[82:85], v[192:195], v[162:165], v[82:85]
	v_mfma_f32_16x16x32_f16 v[70:73], v[178:181], v[170:173], v[70:73]
	v_mfma_f32_16x16x32_f16 v[66:69], v[192:195], v[170:173], v[66:69]
	s_waitcnt lgkmcnt(0)
	v_mfma_f32_16x16x32_f16 v[126:129], v[188:191], v[150:153], v[126:129]
	v_mfma_f32_16x16x32_f16 v[118:121], v[196:199], v[150:153], v[118:121]
	v_mfma_f32_16x16x32_f16 v[102:105], v[188:191], v[158:161], v[102:105]
	v_mfma_f32_16x16x32_f16 v[98:101], v[196:199], v[158:161], v[98:101]
	v_mfma_f32_16x16x32_f16 v[86:89], v[188:191], v[166:169], v[86:89]
	v_mfma_f32_16x16x32_f16 v[82:85], v[196:199], v[166:169], v[82:85]
	v_mfma_f32_16x16x32_f16 v[70:73], v[188:191], v[174:177], v[70:73]
	v_mfma_f32_16x16x32_f16 v[66:69], v[196:199], v[174:177], v[66:69]
	s_setprio 0
	s_barrier
	s_mov_b32 m0, s24
	v_lshl_add_u64 v[204:205], s[16:17], 0, v[32:33]
	ds_read_b128 v[138:141], v232 offset:16384
	ds_read_b128 v[154:157], v232 offset:18432
	ds_read_b128 v[162:165], v232 offset:20480
	ds_read_b128 v[170:173], v232 offset:22528
	ds_read_b128 v[150:153], v232 offset:17408
	ds_read_b128 v[158:161], v232 offset:19456
	ds_read_b128 v[166:169], v232 offset:21504
	ds_read_b128 v[174:177], v232 offset:23552
	global_load_lds_dwordx4 v[204:205], off
	v_lshl_add_u64 v[206:207], s[16:17], 0, v[182:183]
	s_mov_b32 m0, s25
	s_nop 0
	global_load_lds_dwordx4 v[206:207], off
	s_barrier
	s_waitcnt lgkmcnt(7)
	s_setprio 1
	v_mfma_f32_16x16x32_f16 v[62:65], v[106:109], v[138:141], v[62:65]
	v_mfma_f32_16x16x32_f16 v[58:61], v[114:117], v[138:141], v[58:61]
	s_waitcnt lgkmcnt(6)
	v_mfma_f32_16x16x32_f16 v[46:49], v[106:109], v[154:157], v[46:49]
	v_mfma_f32_16x16x32_f16 v[42:45], v[114:117], v[154:157], v[42:45]
	s_waitcnt lgkmcnt(5)
	v_mfma_f32_16x16x32_f16 v[28:31], v[106:109], v[162:165], v[28:31]
	v_mfma_f32_16x16x32_f16 v[24:27], v[114:117], v[162:165], v[24:27]
	s_waitcnt lgkmcnt(4)
	v_mfma_f32_16x16x32_f16 v[12:15], v[106:109], v[170:173], v[12:15]
	v_mfma_f32_16x16x32_f16 v[8:11], v[114:117], v[170:173], v[8:11]
	s_waitcnt lgkmcnt(3)
	v_mfma_f32_16x16x32_f16 v[62:65], v[110:113], v[150:153], v[62:65]
	v_mfma_f32_16x16x32_f16 v[58:61], v[134:137], v[150:153], v[58:61]
	s_waitcnt lgkmcnt(2)
	v_mfma_f32_16x16x32_f16 v[46:49], v[110:113], v[158:161], v[46:49]
	v_mfma_f32_16x16x32_f16 v[42:45], v[134:137], v[158:161], v[42:45]
	s_waitcnt lgkmcnt(1)
	v_mfma_f32_16x16x32_f16 v[28:31], v[110:113], v[166:169], v[28:31]
	v_mfma_f32_16x16x32_f16 v[24:27], v[134:137], v[166:169], v[24:27]
	s_waitcnt lgkmcnt(0)
	v_mfma_f32_16x16x32_f16 v[12:15], v[110:113], v[174:177], v[12:15]
	v_mfma_f32_16x16x32_f16 v[8:11], v[134:137], v[174:177], v[8:11]
	s_setprio 0
	s_barrier
	s_add_u32 s10, s14, 0xb0000
	s_addc_u32 s11, s15, 0
	s_add_i32 s47, s48, s23
	v_lshl_add_u64 v[106:107], s[10:11], 0, v[32:33]
	s_mov_b32 m0, s47
	s_nop 0
	global_load_lds_dwordx4 v[106:107], off
	v_lshl_add_u64 v[106:107], s[10:11], 0, v[182:183]
	s_add_i32 m0, s47, 0x2000
	s_nop 0
	global_load_lds_dwordx4 v[106:107], off
	s_waitcnt vmcnt(6)
	s_barrier
	s_setprio 1
	v_mfma_f32_16x16x32_f16 v[54:57], v[178:181], v[138:141], v[54:57]
	v_mfma_f32_16x16x32_f16 v[50:53], v[192:195], v[138:141], v[50:53]
	v_mfma_f32_16x16x32_f16 v[38:41], v[178:181], v[154:157], v[38:41]
	v_mfma_f32_16x16x32_f16 v[34:37], v[192:195], v[154:157], v[34:37]
	v_mfma_f32_16x16x32_f16 v[20:23], v[178:181], v[162:165], v[20:23]
	v_mfma_f32_16x16x32_f16 v[16:19], v[192:195], v[162:165], v[16:19]
	v_mfma_f32_16x16x32_f16 v[4:7], v[178:181], v[170:173], v[4:7]
	v_mfma_f32_16x16x32_f16 v[0:3], v[192:195], v[170:173], v[0:3]
	v_mfma_f32_16x16x32_f16 v[54:57], v[188:191], v[150:153], v[54:57]
	v_mfma_f32_16x16x32_f16 v[50:53], v[196:199], v[150:153], v[50:53]
	v_mfma_f32_16x16x32_f16 v[38:41], v[188:191], v[158:161], v[38:41]
	v_mfma_f32_16x16x32_f16 v[34:37], v[196:199], v[158:161], v[34:37]
	v_mfma_f32_16x16x32_f16 v[20:23], v[188:191], v[166:169], v[20:23]
	v_mfma_f32_16x16x32_f16 v[16:19], v[196:199], v[166:169], v[16:19]
	v_mfma_f32_16x16x32_f16 v[4:7], v[188:191], v[174:177], v[4:7]
	v_mfma_f32_16x16x32_f16 v[0:3], v[196:199], v[174:177], v[0:3]
	s_setprio 0
	s_barrier
	s_add_i32 s47, 0, 0x18000
	v_add_u32_e32 v134, s47, v230
	ds_read_b128 v[106:109], v134
	ds_read_b128 v[114:117], v134 offset:2048
	ds_read_b128 v[110:113], v134 offset:1024
	ds_read_b128 v[134:137], v134 offset:3072
	s_add_u32 s10, s16, 0xb0000
	s_addc_u32 s11, s17, 0
	s_mov_b32 m0, s26
	v_lshl_add_u64 v[178:179], s[10:11], 0, v[32:33]
	ds_read_b128 v[138:141], v232 offset:32768
	ds_read_b128 v[154:157], v232 offset:34816
	ds_read_b128 v[162:165], v232 offset:36864
	ds_read_b128 v[170:173], v232 offset:38912
	ds_read_b128 v[150:153], v232 offset:33792
	ds_read_b128 v[158:161], v232 offset:35840
	ds_read_b128 v[166:169], v232 offset:37888
	ds_read_b128 v[174:177], v232 offset:39936
	global_load_lds_dwordx4 v[178:179], off
	v_lshl_add_u64 v[178:179], s[10:11], 0, v[182:183]
	s_mov_b32 m0, s27
	s_nop 0
	global_load_lds_dwordx4 v[178:179], off
	s_waitcnt lgkmcnt(8)
	s_barrier
	s_waitcnt lgkmcnt(7)
	s_setprio 1
	v_mfma_f32_16x16x32_f16 v[146:149], v[106:109], v[138:141], v[146:149]
	v_mfma_f32_16x16x32_f16 v[142:145], v[114:117], v[138:141], v[142:145]
	s_waitcnt lgkmcnt(6)
	v_mfma_f32_16x16x32_f16 v[130:133], v[106:109], v[154:157], v[130:133]
	v_mfma_f32_16x16x32_f16 v[122:125], v[114:117], v[154:157], v[122:125]
	s_waitcnt lgkmcnt(5)
	v_mfma_f32_16x16x32_f16 v[94:97], v[106:109], v[162:165], v[94:97]
	v_mfma_f32_16x16x32_f16 v[90:93], v[114:117], v[162:165], v[90:93]
	s_waitcnt lgkmcnt(4)
	v_mfma_f32_16x16x32_f16 v[78:81], v[106:109], v[170:173], v[78:81]
	v_mfma_f32_16x16x32_f16 v[74:77], v[114:117], v[170:173], v[74:77]
	s_waitcnt lgkmcnt(3)
	v_mfma_f32_16x16x32_f16 v[146:149], v[110:113], v[150:153], v[146:149]
	v_mfma_f32_16x16x32_f16 v[142:145], v[134:137], v[150:153], v[142:145]
	s_waitcnt lgkmcnt(2)
	v_mfma_f32_16x16x32_f16 v[130:133], v[110:113], v[158:161], v[130:133]
	v_mfma_f32_16x16x32_f16 v[122:125], v[134:137], v[158:161], v[122:125]
	s_waitcnt lgkmcnt(1)
	v_mfma_f32_16x16x32_f16 v[94:97], v[110:113], v[166:169], v[94:97]
	v_mfma_f32_16x16x32_f16 v[90:93], v[134:137], v[166:169], v[90:93]
	s_waitcnt lgkmcnt(0)
	v_mfma_f32_16x16x32_f16 v[78:81], v[110:113], v[174:177], v[78:81]
	v_mfma_f32_16x16x32_f16 v[74:77], v[134:137], v[174:177], v[74:77]
	s_setprio 0
	s_barrier
	s_add_i32 s16, 0, 0x1c000
	s_add_i32 s10, s47, s23
	v_add_u32_e32 v196, s16, v230
	v_lshl_add_u64 v[200:201], v[200:201], 0, s[84:85]
	s_mov_b32 m0, s10
	ds_read_b128 v[178:181], v196
	ds_read_b128 v[192:195], v196 offset:2048
	ds_read_b128 v[188:191], v196 offset:1024
	ds_read_b128 v[196:199], v196 offset:3072
	global_load_lds_dwordx4 v[200:201], off
	v_lshl_add_u64 v[200:201], v[202:203], 0, s[84:85]
	s_add_i32 m0, s10, 0x2000
	s_nop 0
	global_load_lds_dwordx4 v[200:201], off
	s_barrier
	s_waitcnt lgkmcnt(2)
	s_setprio 1
	v_mfma_f32_16x16x32_f16 v[126:129], v[178:181], v[138:141], v[126:129]
	v_mfma_f32_16x16x32_f16 v[118:121], v[192:195], v[138:141], v[118:121]
	v_mfma_f32_16x16x32_f16 v[102:105], v[178:181], v[154:157], v[102:105]
	v_mfma_f32_16x16x32_f16 v[98:101], v[192:195], v[154:157], v[98:101]
	v_mfma_f32_16x16x32_f16 v[86:89], v[178:181], v[162:165], v[86:89]
	v_mfma_f32_16x16x32_f16 v[82:85], v[192:195], v[162:165], v[82:85]
	v_mfma_f32_16x16x32_f16 v[70:73], v[178:181], v[170:173], v[70:73]
	v_mfma_f32_16x16x32_f16 v[66:69], v[192:195], v[170:173], v[66:69]
	s_waitcnt lgkmcnt(0)
	v_mfma_f32_16x16x32_f16 v[126:129], v[188:191], v[150:153], v[126:129]
	v_mfma_f32_16x16x32_f16 v[118:121], v[196:199], v[150:153], v[118:121]
	v_mfma_f32_16x16x32_f16 v[102:105], v[188:191], v[158:161], v[102:105]
	v_mfma_f32_16x16x32_f16 v[98:101], v[196:199], v[158:161], v[98:101]
	v_mfma_f32_16x16x32_f16 v[86:89], v[188:191], v[166:169], v[86:89]
	v_mfma_f32_16x16x32_f16 v[82:85], v[196:199], v[166:169], v[82:85]
	v_mfma_f32_16x16x32_f16 v[70:73], v[188:191], v[174:177], v[70:73]
	v_mfma_f32_16x16x32_f16 v[66:69], v[196:199], v[174:177], v[66:69]
	s_setprio 0
	s_barrier
	s_mov_b32 m0, s29
	v_lshl_add_u64 v[200:201], v[204:205], 0, s[84:85]
	ds_read_b128 v[138:141], v232 offset:49152
	ds_read_b128 v[154:157], v232 offset:51200
	ds_read_b128 v[162:165], v232 offset:53248
	ds_read_b128 v[170:173], v232 offset:55296
	ds_read_b128 v[150:153], v232 offset:50176
	ds_read_b128 v[158:161], v232 offset:52224
	ds_read_b128 v[166:169], v232 offset:54272
	ds_read_b128 v[174:177], v232 offset:56320
	global_load_lds_dwordx4 v[200:201], off
	v_lshl_add_u64 v[200:201], v[206:207], 0, s[84:85]
	s_mov_b32 m0, s30
	s_nop 0
	global_load_lds_dwordx4 v[200:201], off
	s_barrier
	s_waitcnt lgkmcnt(7)
	s_setprio 1
	v_mfma_f32_16x16x32_f16 v[62:65], v[106:109], v[138:141], v[62:65]
	v_mfma_f32_16x16x32_f16 v[58:61], v[114:117], v[138:141], v[58:61]
	s_waitcnt lgkmcnt(6)
	v_mfma_f32_16x16x32_f16 v[46:49], v[106:109], v[154:157], v[46:49]
	v_mfma_f32_16x16x32_f16 v[42:45], v[114:117], v[154:157], v[42:45]
	s_waitcnt lgkmcnt(5)
	v_mfma_f32_16x16x32_f16 v[28:31], v[106:109], v[162:165], v[28:31]
	v_mfma_f32_16x16x32_f16 v[24:27], v[114:117], v[162:165], v[24:27]
	s_waitcnt lgkmcnt(4)
	v_mfma_f32_16x16x32_f16 v[12:15], v[106:109], v[170:173], v[12:15]
	v_mfma_f32_16x16x32_f16 v[8:11], v[114:117], v[170:173], v[8:11]
	s_waitcnt lgkmcnt(3)
	v_mfma_f32_16x16x32_f16 v[62:65], v[110:113], v[150:153], v[62:65]
	v_mfma_f32_16x16x32_f16 v[58:61], v[134:137], v[150:153], v[58:61]
	s_waitcnt lgkmcnt(2)
	v_mfma_f32_16x16x32_f16 v[46:49], v[110:113], v[158:161], v[46:49]
	v_mfma_f32_16x16x32_f16 v[42:45], v[134:137], v[158:161], v[42:45]
	s_waitcnt lgkmcnt(1)
	v_mfma_f32_16x16x32_f16 v[28:31], v[110:113], v[166:169], v[28:31]
	v_mfma_f32_16x16x32_f16 v[24:27], v[134:137], v[166:169], v[24:27]
	s_waitcnt lgkmcnt(0)
	v_mfma_f32_16x16x32_f16 v[12:15], v[110:113], v[174:177], v[12:15]
	v_mfma_f32_16x16x32_f16 v[8:11], v[134:137], v[174:177], v[8:11]
	s_setprio 0
	s_barrier
	s_add_u32 s10, s14, 0xb0080
	s_addc_u32 s11, s15, 0
	s_add_i32 s14, s16, s23
	v_lshl_add_u64 v[106:107], s[10:11], 0, v[32:33]
	s_mov_b32 m0, s14
	s_nop 0
	global_load_lds_dwordx4 v[106:107], off
	v_lshl_add_u64 v[106:107], s[10:11], 0, v[182:183]
	s_add_i32 m0, s14, 0x2000
	s_nop 0
	global_load_lds_dwordx4 v[106:107], off
	s_waitcnt vmcnt(6)
	s_barrier
	s_setprio 1
	v_mfma_f32_16x16x32_f16 v[54:57], v[178:181], v[138:141], v[54:57]
	v_mfma_f32_16x16x32_f16 v[50:53], v[192:195], v[138:141], v[50:53]
	v_mfma_f32_16x16x32_f16 v[38:41], v[178:181], v[154:157], v[38:41]
	v_mfma_f32_16x16x32_f16 v[34:37], v[192:195], v[154:157], v[34:37]
	v_mfma_f32_16x16x32_f16 v[20:23], v[178:181], v[162:165], v[20:23]
	v_mfma_f32_16x16x32_f16 v[16:19], v[192:195], v[162:165], v[16:19]
	v_mfma_f32_16x16x32_f16 v[4:7], v[178:181], v[170:173], v[4:7]
	v_mfma_f32_16x16x32_f16 v[0:3], v[192:195], v[170:173], v[0:3]
	v_mfma_f32_16x16x32_f16 v[54:57], v[188:191], v[150:153], v[54:57]
	v_mfma_f32_16x16x32_f16 v[50:53], v[196:199], v[150:153], v[50:53]
	v_mfma_f32_16x16x32_f16 v[38:41], v[188:191], v[158:161], v[38:41]
	v_mfma_f32_16x16x32_f16 v[34:37], v[196:199], v[158:161], v[34:37]
	v_mfma_f32_16x16x32_f16 v[20:23], v[188:191], v[166:169], v[20:23]
	v_mfma_f32_16x16x32_f16 v[16:19], v[196:199], v[166:169], v[16:19]
	v_mfma_f32_16x16x32_f16 v[4:7], v[188:191], v[174:177], v[4:7]
	v_mfma_f32_16x16x32_f16 v[0:3], v[196:199], v[174:177], v[0:3]
	s_setprio 0
	s_barrier
	s_add_u32 s44, s44, 0x100
	s_addc_u32 s45, s45, 0
	s_cmp_ge_u32 s46, s42
	s_mov_b64 s[10:11], s[12:13]
	s_mov_b32 s14, s46
	s_cbranch_scc0 .LBB0_1365
	s_cmp_eq_u32 s40, 0
	s_cselect_b32 s6, 0x9000, 0
	v_lshl_or_b32 v106, s41, 8, v231
	s_add_u32 s6, s31, s6
	s_addc_u32 s7, s34, 0
	v_ashrrev_i32_e32 v107, 31, v106
	v_lshl_add_u64 v[116:117], v[106:107], 2, s[6:7]
	global_load_dwordx4 v[108:111], v[116:117], off offset:16
	global_load_dwordx4 v[112:115], v[116:117], off
	s_cmp_eq_u32 s39, 0
	s_waitcnt vmcnt(0)
	v_pk_mul_f32 v[194:195], v[110:111], 0.5 op_sel_hi:[1,0]
	v_pk_mul_f32 v[198:199], v[114:115], 0.5 op_sel_hi:[1,0]
	v_pk_mul_f32 v[202:203], v[112:113], 0.5 op_sel_hi:[1,0]
	v_pk_mul_f32 v[200:201], v[108:109], 0.5 op_sel_hi:[1,0]
	global_load_dwordx4 v[108:111], v[116:117], off offset:528
	global_load_dwordx4 v[112:115], v[116:117], off offset:512
	s_waitcnt vmcnt(0)
	v_pk_mul_f32 v[188:189], v[110:111], 0.5 op_sel_hi:[1,0]
	v_pk_mul_f32 v[196:197], v[112:113], 0.5 op_sel_hi:[1,0]
	v_lshl_add_u32 v112, s40, 8, v229
	v_pk_mul_f32 v[190:191], v[114:115], 0.5 op_sel_hi:[1,0]
	v_pk_mul_f32 v[192:193], v[108:109], 0.5 op_sel_hi:[1,0]
	v_or_b32_e32 v114, 16, v112
	v_or_b32_e32 v110, 32, v112
	v_or_b32_e32 v108, 48, v112
	v_ashrrev_i32_e32 v113, 31, v112
	v_ashrrev_i32_e32 v115, 31, v114
	v_ashrrev_i32_e32 v111, 31, v110
	v_ashrrev_i32_e32 v109, 31, v108
	s_cbranch_scc1 .LBB0_1368
	s_add_i32 s96, s39, -1
	s_lshl_b64 s[6:7], s[96:97], 20
	v_readlane_b32 s8, v252, 11
	v_readlane_b32 s9, v252, 12
	s_add_u32 s6, s8, s6
	s_addc_u32 s7, s9, s7
	v_lshlrev_b64 v[138:139], 2, v[106:107]
	v_lshrrev_b32_e32 v150, 5, v220
	v_mul_u32_u24_e32 v150, 48, v150
	s_nop 0
	v_sub_co_u32_e32 v138, vcc, v138, v150
	s_nop 1
	v_subbrev_co_u32_e32 v139, vcc, 0, v139, vcc
	v_lshl_add_u64 v[138:139], s[6:7], 0, v[138:139]
	s_mov_b64 s[6:7], 0x80000
	v_lshlrev_b64 v[204:205], 12, v[112:113]
	v_lshl_add_u64 v[204:205], v[204:205], 0, v[138:139]
	v_lshl_add_u64 v[212:213], v[204:205], 0, s[6:7]
	v_lshlrev_b64 v[206:207], 12, v[114:115]
	v_lshl_add_u64 v[206:207], v[206:207], 0, v[138:139]
	v_lshl_add_u64 v[214:215], v[206:207], 0, s[6:7]
	v_lshlrev_b64 v[208:209], 12, v[110:111]
	v_lshl_add_u64 v[208:209], v[208:209], 0, v[138:139]
	v_lshl_add_u64 v[216:217], v[208:209], 0, s[6:7]
	v_lshlrev_b64 v[210:211], 12, v[108:109]
	v_lshl_add_u64 v[210:211], v[210:211], 0, v[138:139]
	v_lshl_add_u64 v[218:219], v[210:211], 0, s[6:7]
	s_waitcnt vmcnt(0)
	v_pk_mul_f32 v[152:153], v[146:147], v[202:203]
	v_pk_mul_f32 v[154:155], v[148:149], v[198:199]
	v_pk_mul_f32 v[156:157], v[142:143], v[200:201]
	v_pk_mul_f32 v[158:159], v[144:145], v[194:195]
	s_nop 1
	v_permlane32_swap_b32_e32 v152, v156
	v_permlane32_swap_b32_e32 v153, v157
	v_permlane32_swap_b32_e32 v154, v158
	v_permlane32_swap_b32_e32 v155, v159
	s_nop 0
	global_store_dwordx4 v[204:205], v[152:155], off
	global_store_dwordx4 v[204:205], v[156:159], off offset:64
	v_pk_mul_f32 v[160:161], v[126:127], v[196:197]
	v_pk_mul_f32 v[162:163], v[128:129], v[190:191]
	v_pk_mul_f32 v[164:165], v[118:119], v[192:193]
	v_pk_mul_f32 v[166:167], v[120:121], v[188:189]
	s_nop 1
	v_permlane32_swap_b32_e32 v160, v164
	v_permlane32_swap_b32_e32 v161, v165
	v_permlane32_swap_b32_e32 v162, v166
	v_permlane32_swap_b32_e32 v163, v167
	s_nop 0
	global_store_dwordx4 v[204:205], v[160:163], off offset:512
	global_store_dwordx4 v[204:205], v[164:167], off offset:576
	v_pk_mul_f32 v[168:169], v[130:131], v[202:203]
	v_pk_mul_f32 v[170:171], v[132:133], v[198:199]
	v_pk_mul_f32 v[172:173], v[122:123], v[200:201]
	v_pk_mul_f32 v[174:175], v[124:125], v[194:195]
	s_nop 1
	v_permlane32_swap_b32_e32 v168, v172
	v_permlane32_swap_b32_e32 v169, v173
	v_permlane32_swap_b32_e32 v170, v174
	v_permlane32_swap_b32_e32 v171, v175
	s_nop 0
	global_store_dwordx4 v[206:207], v[168:171], off
	global_store_dwordx4 v[206:207], v[172:175], off offset:64
	v_pk_mul_f32 v[176:177], v[102:103], v[196:197]
	v_pk_mul_f32 v[178:179], v[104:105], v[190:191]
	v_pk_mul_f32 v[180:181], v[98:99], v[192:193]
	v_pk_mul_f32 v[182:183], v[100:101], v[188:189]
	s_nop 1
	v_permlane32_swap_b32_e32 v176, v180
	v_permlane32_swap_b32_e32 v177, v181
	v_permlane32_swap_b32_e32 v178, v182
	v_permlane32_swap_b32_e32 v179, v183
	s_nop 0
	global_store_dwordx4 v[206:207], v[176:179], off offset:512
	global_store_dwordx4 v[206:207], v[180:183], off offset:576
	v_pk_mul_f32 v[152:153], v[94:95], v[202:203]
	v_pk_mul_f32 v[154:155], v[96:97], v[198:199]
	v_pk_mul_f32 v[156:157], v[90:91], v[200:201]
	v_pk_mul_f32 v[158:159], v[92:93], v[194:195]
	s_nop 1
	v_permlane32_swap_b32_e32 v152, v156
	v_permlane32_swap_b32_e32 v153, v157
	v_permlane32_swap_b32_e32 v154, v158
	v_permlane32_swap_b32_e32 v155, v159
	s_nop 0
	global_store_dwordx4 v[208:209], v[152:155], off
	global_store_dwordx4 v[208:209], v[156:159], off offset:64
	v_pk_mul_f32 v[160:161], v[86:87], v[196:197]
	v_pk_mul_f32 v[162:163], v[88:89], v[190:191]
	v_pk_mul_f32 v[164:165], v[82:83], v[192:193]
	v_pk_mul_f32 v[166:167], v[84:85], v[188:189]
	s_nop 1
	v_permlane32_swap_b32_e32 v160, v164
	v_permlane32_swap_b32_e32 v161, v165
	v_permlane32_swap_b32_e32 v162, v166
	v_permlane32_swap_b32_e32 v163, v167
	s_nop 0
	global_store_dwordx4 v[208:209], v[160:163], off offset:512
	global_store_dwordx4 v[208:209], v[164:167], off offset:576
	v_pk_mul_f32 v[168:169], v[78:79], v[202:203]
	v_pk_mul_f32 v[170:171], v[80:81], v[198:199]
	v_pk_mul_f32 v[172:173], v[74:75], v[200:201]
	v_pk_mul_f32 v[174:175], v[76:77], v[194:195]
	s_nop 1
	v_permlane32_swap_b32_e32 v168, v172
	v_permlane32_swap_b32_e32 v169, v173
	v_permlane32_swap_b32_e32 v170, v174
	v_permlane32_swap_b32_e32 v171, v175
	s_nop 0
	global_store_dwordx4 v[210:211], v[168:171], off
	global_store_dwordx4 v[210:211], v[172:175], off offset:64
	v_pk_mul_f32 v[176:177], v[70:71], v[196:197]
	v_pk_mul_f32 v[178:179], v[72:73], v[190:191]
	v_pk_mul_f32 v[180:181], v[66:67], v[192:193]
	v_pk_mul_f32 v[182:183], v[68:69], v[188:189]
	s_nop 1
	v_permlane32_swap_b32_e32 v176, v180
	v_permlane32_swap_b32_e32 v177, v181
	v_permlane32_swap_b32_e32 v178, v182
	v_permlane32_swap_b32_e32 v179, v183
	s_nop 0
	global_store_dwordx4 v[210:211], v[176:179], off offset:512
	global_store_dwordx4 v[210:211], v[180:183], off offset:576
	v_pk_mul_f32 v[152:153], v[62:63], v[202:203]
	v_pk_mul_f32 v[154:155], v[64:65], v[198:199]
	v_pk_mul_f32 v[156:157], v[58:59], v[200:201]
	v_pk_mul_f32 v[158:159], v[60:61], v[194:195]
	s_nop 1
	v_permlane32_swap_b32_e32 v152, v156
	v_permlane32_swap_b32_e32 v153, v157
	v_permlane32_swap_b32_e32 v154, v158
	v_permlane32_swap_b32_e32 v155, v159
	s_nop 0
	global_store_dwordx4 v[212:213], v[152:155], off
	global_store_dwordx4 v[212:213], v[156:159], off offset:64
	v_pk_mul_f32 v[160:161], v[54:55], v[196:197]
	v_pk_mul_f32 v[162:163], v[56:57], v[190:191]
	v_pk_mul_f32 v[164:165], v[50:51], v[192:193]
	v_pk_mul_f32 v[166:167], v[52:53], v[188:189]
	s_nop 1
	v_permlane32_swap_b32_e32 v160, v164
	v_permlane32_swap_b32_e32 v161, v165
	v_permlane32_swap_b32_e32 v162, v166
	v_permlane32_swap_b32_e32 v163, v167
	s_nop 0
	global_store_dwordx4 v[212:213], v[160:163], off offset:512
	global_store_dwordx4 v[212:213], v[164:167], off offset:576
	v_pk_mul_f32 v[168:169], v[46:47], v[202:203]
	v_pk_mul_f32 v[170:171], v[48:49], v[198:199]
	v_pk_mul_f32 v[172:173], v[42:43], v[200:201]
	v_pk_mul_f32 v[174:175], v[44:45], v[194:195]
	s_nop 1
	v_permlane32_swap_b32_e32 v168, v172
	v_permlane32_swap_b32_e32 v169, v173
	v_permlane32_swap_b32_e32 v170, v174
	v_permlane32_swap_b32_e32 v171, v175
	s_nop 0
	global_store_dwordx4 v[214:215], v[168:171], off
	global_store_dwordx4 v[214:215], v[172:175], off offset:64
	v_pk_mul_f32 v[176:177], v[38:39], v[196:197]
	v_pk_mul_f32 v[178:179], v[40:41], v[190:191]
	v_pk_mul_f32 v[180:181], v[34:35], v[192:193]
	v_pk_mul_f32 v[182:183], v[36:37], v[188:189]
	s_nop 1
	v_permlane32_swap_b32_e32 v176, v180
	v_permlane32_swap_b32_e32 v177, v181
	v_permlane32_swap_b32_e32 v178, v182
	v_permlane32_swap_b32_e32 v179, v183
	s_nop 0
	global_store_dwordx4 v[214:215], v[176:179], off offset:512
	global_store_dwordx4 v[214:215], v[180:183], off offset:576
	v_pk_mul_f32 v[152:153], v[28:29], v[202:203]
	v_pk_mul_f32 v[154:155], v[30:31], v[198:199]
	v_pk_mul_f32 v[156:157], v[24:25], v[200:201]
	v_pk_mul_f32 v[158:159], v[26:27], v[194:195]
	s_nop 1
	v_permlane32_swap_b32_e32 v152, v156
	v_permlane32_swap_b32_e32 v153, v157
	v_permlane32_swap_b32_e32 v154, v158
	v_permlane32_swap_b32_e32 v155, v159
	s_nop 0
	global_store_dwordx4 v[216:217], v[152:155], off
	global_store_dwordx4 v[216:217], v[156:159], off offset:64
	v_pk_mul_f32 v[160:161], v[20:21], v[196:197]
	v_pk_mul_f32 v[162:163], v[22:23], v[190:191]
	v_pk_mul_f32 v[164:165], v[16:17], v[192:193]
	v_pk_mul_f32 v[166:167], v[18:19], v[188:189]
	s_nop 1
	v_permlane32_swap_b32_e32 v160, v164
	v_permlane32_swap_b32_e32 v161, v165
	v_permlane32_swap_b32_e32 v162, v166
	v_permlane32_swap_b32_e32 v163, v167
	s_nop 0
	global_store_dwordx4 v[216:217], v[160:163], off offset:512
	global_store_dwordx4 v[216:217], v[164:167], off offset:576
	v_pk_mul_f32 v[168:169], v[12:13], v[202:203]
	v_pk_mul_f32 v[170:171], v[14:15], v[198:199]
	v_pk_mul_f32 v[172:173], v[8:9], v[200:201]
	v_pk_mul_f32 v[174:175], v[10:11], v[194:195]
	s_nop 1
	v_permlane32_swap_b32_e32 v168, v172
	v_permlane32_swap_b32_e32 v169, v173
	v_permlane32_swap_b32_e32 v170, v174
	v_permlane32_swap_b32_e32 v171, v175
	s_nop 0
	global_store_dwordx4 v[218:219], v[168:171], off
	global_store_dwordx4 v[218:219], v[172:175], off offset:64
	v_pk_mul_f32 v[176:177], v[4:5], v[196:197]
	v_pk_mul_f32 v[178:179], v[6:7], v[190:191]
	v_pk_mul_f32 v[180:181], v[0:1], v[192:193]
	v_pk_mul_f32 v[182:183], v[2:3], v[188:189]
	s_nop 1
	v_permlane32_swap_b32_e32 v176, v180
	v_permlane32_swap_b32_e32 v177, v181
	v_permlane32_swap_b32_e32 v178, v182
	v_permlane32_swap_b32_e32 v179, v183
	s_nop 0
	global_store_dwordx4 v[218:219], v[176:179], off offset:512
	global_store_dwordx4 v[218:219], v[180:183], off offset:576
	s_cbranch_execnz .LBB0_1352
	s_branch .LBB0_1351
